# K-loop load segments re-ordered: LDS-DMA loads issued before the ds_read_b128 burst (long-latency loads first; 25 segments)
# baseline (speedup 1.0000x reference)
; #define PG8_STAGE(bufoff, gbase, voff) do { _Pragma("unroll") for (int _i = 0; _i < 2; ++_i) \
;         __builtin_amdgcn_global_load_lds((const unsigned*)((const char*)(gbase) + (voff)[_i]), (LAS unsigned*)(lds + (bufoff) + ldsw + _i * 8192), 16, 0, 0); } while (0)
; #define PG8_LDA(dst, b, h) do { _Pragma("unroll") for (int m = 0; m < 4; ++m) _Pragma("unroll") for (int k = 0; k < 2; ++k) dst[m][k] = *(const LAS bf16x8*)(lds + PG8_SA(b, h) + aoff + m * 2048 + k * 1024); } while (0)
; #define PG8_LDB(dst, b, h) do { _Pragma("unroll") for (int n = 0; n < 2; ++n) _Pragma("unroll") for (int k = 0; k < 2; ++k) dst[n][k] = *(const LAS bf16x8*)(lds + PG8_SB(b, h) + boff + n * 2048 + k * 1024); } while (0)
; #define PG8_MMA(ai, bj, At, Bt) do { __builtin_amdgcn_s_setprio(1); _Pragma("unroll") for (int m = 0; m < 4; ++m) _Pragma("unroll") for (int n = 0; n < 2; ++n) _Pragma("unroll") for (int k = 0; k < 2; ++k) \
;         acc[ai][bj][m][n] = __builtin_amdgcn_mfma_f32_16x16x32_bf16(Bt[n][k], At[m][k], acc[ai][bj][m][n], 0, 0, 0); __builtin_amdgcn_s_setprio(0); } while (0)
; #define PG8_WAIT_V(n) asm volatile("s_waitcnt vmcnt(" #n ")" ::: "memory")
; #define PG8_WAIT_L(n) asm volatile("s_waitcnt lgkmcnt(" #n ")" ::: "memory")
; #define PG8_BAR __builtin_amdgcn_s_barrier()
; #define PG8_SCHED __builtin_amdgcn_sched_barrier(0)
; template <class Epi, class Sched>
; __device__ __forceinline__ void gemm_phase(LAS unsigned char* lds, const Gemm g, const Sched& S, const Epi& E) {
;     ...
;             PG8_LDB(B0, 0, 0); PG8_LDB(B1, 0, 1); PG8_SCHED; PG8_LDA(At, 0, 0); PG8_STAGE(PG8_SA(1, 1), a1 + hstepA, voffA);
;             PG8_WAIT_V(8); PG8_WAIT_L(0); PG8_BAR; PG8_MMA(0, 0, At, B0); PG8_MMA(0, 1, At, B1); PG8_BAR; PG8_SCHED;
;             PG8_LDA(At, 0, 1); PG8_STAGE(PG8_SB(0, 0), b2, voffB); PG8_STAGE(PG8_SB(0, 1), b2 + hstepB, voffB); PG8_STAGE(PG8_SA(0, 0), a2, voffA);
;             PG8_WAIT_V(8); PG8_WAIT_L(0); PG8_BAR; PG8_MMA(1, 0, At, B0); PG8_MMA(1, 1, At, B1); PG8_BAR; PG8_SCHED;
.LBB0_122:
	s_add_u32 s4, s0, 0xfff80080
	s_addc_u32 s5, s1, -1
	s_cmp_eq_u32 s87, 28
	s_cselect_b32 s7, s8, s5
	s_cselect_b32 s6, s9, s4
	s_cselect_b32 s5, s10, s35
	s_cselect_b32 s4, s11, s34
	v_lshl_add_u64 v[216:217], s[0:1], 0, v[178:179]
	s_add_i32 m0, s15, 0xc000
	s_nop 0
	global_load_lds_dwordx4 v[216:217], off
	v_lshl_add_u64 v[216:217], s[0:1], 0, v[180:181]
	s_add_i32 m0, s15, 0xe000
	s_nop 0
	global_load_lds_dwordx4 v[216:217], off
	ds_read_b128 v[128:131], v209
	ds_read_b128 v[132:135], v209 offset:1024
	ds_read_b128 v[136:139], v209 offset:2048
	ds_read_b128 v[140:143], v209 offset:3072
	ds_read_b128 v[144:147], v210
	ds_read_b128 v[148:151], v210 offset:1024
	ds_read_b128 v[152:155], v210 offset:2048
	ds_read_b128 v[156:159], v210 offset:3072
	ds_read_b128 v[160:163], v211
	ds_read_b128 v[164:167], v211 offset:1024
	ds_read_b128 v[182:185], v211 offset:2048
	ds_read_b128 v[186:189], v211 offset:3072
	ds_read_b128 v[190:193], v211 offset:4096
	ds_read_b128 v[194:197], v211 offset:5120
	ds_read_b128 v[198:201], v211 offset:6144
	ds_read_b128 v[202:205], v211 offset:7168
	s_waitcnt vmcnt(8) lgkmcnt(0)
	s_barrier
	s_setprio 1
	v_mfma_f32_16x16x32_bf16 v[124:127], v[128:131], v[160:163], v[124:127]
	v_mfma_f32_16x16x32_bf16 v[120:123], v[136:139], v[160:163], v[120:123]
	v_mfma_f32_16x16x32_bf16 v[116:119], v[128:131], v[182:185], v[116:119]
	v_mfma_f32_16x16x32_bf16 v[112:115], v[136:139], v[182:185], v[112:115]
	v_mfma_f32_16x16x32_bf16 v[108:111], v[128:131], v[190:193], v[108:111]
	v_mfma_f32_16x16x32_bf16 v[104:107], v[136:139], v[190:193], v[104:107]
	v_mfma_f32_16x16x32_bf16 v[96:99], v[128:131], v[198:201], v[96:99]
	v_mfma_f32_16x16x32_bf16 v[100:103], v[136:139], v[198:201], v[100:103]
	v_mfma_f32_16x16x32_bf16 v[124:127], v[132:135], v[164:167], v[124:127]
	v_mfma_f32_16x16x32_bf16 v[120:123], v[140:143], v[164:167], v[120:123]
	v_mfma_f32_16x16x32_bf16 v[116:119], v[132:135], v[186:189], v[116:119]
	v_mfma_f32_16x16x32_bf16 v[112:115], v[140:143], v[186:189], v[112:115]
	v_mfma_f32_16x16x32_bf16 v[108:111], v[132:135], v[194:197], v[108:111]
	v_mfma_f32_16x16x32_bf16 v[104:107], v[140:143], v[194:197], v[104:107]
	v_mfma_f32_16x16x32_bf16 v[96:99], v[132:135], v[202:205], v[96:99]
	v_mfma_f32_16x16x32_bf16 v[100:103], v[140:143], v[202:205], v[100:103]
	s_setprio 0
	s_setprio 1
	v_mfma_f32_16x16x32_bf16 v[60:63], v[144:147], v[160:163], v[60:63]
	v_mfma_f32_16x16x32_bf16 v[56:59], v[152:155], v[160:163], v[56:59]
	v_mfma_f32_16x16x32_bf16 v[52:55], v[144:147], v[182:185], v[52:55]
	v_mfma_f32_16x16x32_bf16 v[48:51], v[152:155], v[182:185], v[48:51]
	v_mfma_f32_16x16x32_bf16 v[44:47], v[144:147], v[190:193], v[44:47]
	v_mfma_f32_16x16x32_bf16 v[40:43], v[152:155], v[190:193], v[40:43]
	v_mfma_f32_16x16x32_bf16 v[32:35], v[144:147], v[198:201], v[32:35]
	v_mfma_f32_16x16x32_bf16 v[36:39], v[152:155], v[198:201], v[36:39]
	v_mfma_f32_16x16x32_bf16 v[60:63], v[148:151], v[164:167], v[60:63]
	v_mfma_f32_16x16x32_bf16 v[56:59], v[156:159], v[164:167], v[56:59]
	v_mfma_f32_16x16x32_bf16 v[52:55], v[148:151], v[186:189], v[52:55]
	v_mfma_f32_16x16x32_bf16 v[48:51], v[156:159], v[186:189], v[48:51]
	v_mfma_f32_16x16x32_bf16 v[44:47], v[148:151], v[194:197], v[44:47]
	v_mfma_f32_16x16x32_bf16 v[40:43], v[156:159], v[194:197], v[40:43]
	v_mfma_f32_16x16x32_bf16 v[32:35], v[148:151], v[202:205], v[32:35]
	v_mfma_f32_16x16x32_bf16 v[36:39], v[156:159], v[202:205], v[36:39]
	s_setprio 0
	s_barrier
	s_add_i32 s26, s33, s14
	v_lshl_add_u64 v[216:217], s[4:5], 0, v[170:171]
	s_mov_b32 m0, s26
	s_nop 0
	global_load_lds_dwordx4 v[216:217], off
	s_add_i32 m0, s26, 0x2000
	s_add_u32 s96, s4, 0x80000
	v_lshl_add_u64 v[218:219], s[4:5], 0, v[174:175]
	s_addc_u32 s97, s5, 0
	s_add_i32 s26, s36, s14
	global_load_lds_dwordx4 v[218:219], off
	v_lshl_add_u64 v[220:221], s[96:97], 0, v[170:171]
	s_mov_b32 m0, s26
	v_lshl_add_u64 v[222:223], s[6:7], 0, v[172:173]
	global_load_lds_dwordx4 v[220:221], off
	v_lshl_add_u64 v[220:221], s[96:97], 0, v[174:175]
	s_add_i32 m0, s26, 0x2000
	s_nop 0
	global_load_lds_dwordx4 v[220:221], off
	v_lshl_add_u64 v[220:221], s[6:7], 0, v[168:169]
	s_mov_b32 m0, s15
	s_nop 0
	global_load_lds_dwordx4 v[220:221], off
	s_mov_b32 m0, s28
	s_nop 0
	global_load_lds_dwordx4 v[222:223], off
	ds_read_b128 v[160:163], v211 offset:16384
	ds_read_b128 v[164:167], v211 offset:17408
	ds_read_b128 v[182:185], v211 offset:18432
	ds_read_b128 v[186:189], v211 offset:19456
	ds_read_b128 v[190:193], v211 offset:20480
	ds_read_b128 v[194:197], v211 offset:21504
	ds_read_b128 v[198:201], v211 offset:22528
	ds_read_b128 v[202:205], v211 offset:23552
	s_waitcnt vmcnt(8) lgkmcnt(0)
	s_barrier
; #define PG8_STAGE(bufoff, gbase, voff) do { _Pragma("unroll") for (int _i = 0; _i < 2; ++_i) \
;         __builtin_amdgcn_global_load_lds((const unsigned*)((const char*)(gbase) + (voff)[_i]), (LAS unsigned*)(lds + (bufoff) + ldsw + _i * 8192), 16, 0, 0); } while (0)
; #define PG8_LDA(dst, b, h) do { _Pragma("unroll") for (int m = 0; m < 4; ++m) _Pragma("unroll") for (int k = 0; k < 2; ++k) dst[m][k] = *(const LAS bf16x8*)(lds + PG8_SA(b, h) + aoff + m * 2048 + k * 1024); } while (0)
; #define PG8_LDB(dst, b, h) do { _Pragma("unroll") for (int n = 0; n < 2; ++n) _Pragma("unroll") for (int k = 0; k < 2; ++k) dst[n][k] = *(const LAS bf16x8*)(lds + PG8_SB(b, h) + boff + n * 2048 + k * 1024); } while (0)
; #define PG8_MMA(ai, bj, At, Bt) do { __builtin_amdgcn_s_setprio(1); _Pragma("unroll") for (int m = 0; m < 4; ++m) _Pragma("unroll") for (int n = 0; n < 2; ++n) _Pragma("unroll") for (int k = 0; k < 2; ++k) \
;         acc[ai][bj][m][n] = __builtin_amdgcn_mfma_f32_16x16x32_bf16(Bt[n][k], At[m][k], acc[ai][bj][m][n], 0, 0, 0); __builtin_amdgcn_s_setprio(0); } while (0)
; #define PG8_WAIT_V(n) asm volatile("s_waitcnt vmcnt(" #n ")" ::: "memory")
; #define PG8_WAIT_L(n) asm volatile("s_waitcnt lgkmcnt(" #n ")" ::: "memory")
; #define PG8_BAR __builtin_amdgcn_s_barrier()
; #define PG8_SCHED __builtin_amdgcn_sched_barrier(0)
; template <class Epi, class Sched>
; __device__ __forceinline__ void gemm_phase(LAS unsigned char* lds, const Gemm g, const Sched& S, const Epi& E) {
;     ...
;             PG8_WAIT_V(8); PG8_WAIT_L(0); PG8_BAR; PG8_MMA(1, 0, At, B0); PG8_MMA(1, 1, At, B1); PG8_BAR; PG8_SCHED;
;             PG8_LDB(B0, 1, 0); PG8_LDB(B1, 1, 1); PG8_SCHED; PG8_LDA(At, 1, 0); PG8_STAGE(PG8_SA(0, 1), a2 + hstepA, voffA);
;             PG8_WAIT_V(8); PG8_WAIT_L(0); PG8_BAR; PG8_MMA(0, 0, At, B0); PG8_MMA(0, 1, At, B1); PG8_BAR; PG8_SCHED;
	s_setprio 1
	v_mfma_f32_16x16x32_bf16 v[92:95], v[128:131], v[160:163], v[92:95]
	v_mfma_f32_16x16x32_bf16 v[88:91], v[136:139], v[160:163], v[88:91]
	v_mfma_f32_16x16x32_bf16 v[84:87], v[128:131], v[182:185], v[84:87]
	v_mfma_f32_16x16x32_bf16 v[80:83], v[136:139], v[182:185], v[80:83]
	v_mfma_f32_16x16x32_bf16 v[76:79], v[128:131], v[190:193], v[76:79]
	v_mfma_f32_16x16x32_bf16 v[72:75], v[136:139], v[190:193], v[72:75]
	v_mfma_f32_16x16x32_bf16 v[64:67], v[128:131], v[198:201], v[64:67]
	v_mfma_f32_16x16x32_bf16 v[68:71], v[136:139], v[198:201], v[68:71]
	v_mfma_f32_16x16x32_bf16 v[92:95], v[132:135], v[164:167], v[92:95]
	v_mfma_f32_16x16x32_bf16 v[88:91], v[140:143], v[164:167], v[88:91]
	v_mfma_f32_16x16x32_bf16 v[84:87], v[132:135], v[186:189], v[84:87]
	v_mfma_f32_16x16x32_bf16 v[80:83], v[140:143], v[186:189], v[80:83]
	v_mfma_f32_16x16x32_bf16 v[76:79], v[132:135], v[194:197], v[76:79]
	v_mfma_f32_16x16x32_bf16 v[72:75], v[140:143], v[194:197], v[72:75]
	v_mfma_f32_16x16x32_bf16 v[64:67], v[132:135], v[202:205], v[64:67]
	v_mfma_f32_16x16x32_bf16 v[68:71], v[140:143], v[202:205], v[68:71]
	s_setprio 0
	s_setprio 1
	v_mfma_f32_16x16x32_bf16 v[28:31], v[144:147], v[160:163], v[28:31]
	v_mfma_f32_16x16x32_bf16 v[24:27], v[152:155], v[160:163], v[24:27]
	v_mfma_f32_16x16x32_bf16 v[20:23], v[144:147], v[182:185], v[20:23]
	v_mfma_f32_16x16x32_bf16 v[16:19], v[152:155], v[182:185], v[16:19]
	v_mfma_f32_16x16x32_bf16 v[12:15], v[144:147], v[190:193], v[12:15]
	v_mfma_f32_16x16x32_bf16 v[8:11], v[152:155], v[190:193], v[8:11]
	v_mfma_f32_16x16x32_bf16 v[0:3], v[144:147], v[198:201], v[0:3]
	v_mfma_f32_16x16x32_bf16 v[4:7], v[152:155], v[198:201], v[4:7]
	v_mfma_f32_16x16x32_bf16 v[28:31], v[148:151], v[164:167], v[28:31]
	v_mfma_f32_16x16x32_bf16 v[24:27], v[156:159], v[164:167], v[24:27]
	v_mfma_f32_16x16x32_bf16 v[20:23], v[148:151], v[186:189], v[20:23]
	v_mfma_f32_16x16x32_bf16 v[16:19], v[156:159], v[186:189], v[16:19]
	v_mfma_f32_16x16x32_bf16 v[12:15], v[148:151], v[194:197], v[12:15]
	v_mfma_f32_16x16x32_bf16 v[8:11], v[156:159], v[194:197], v[8:11]
	v_mfma_f32_16x16x32_bf16 v[0:3], v[148:151], v[202:205], v[0:3]
	v_mfma_f32_16x16x32_bf16 v[4:7], v[156:159], v[202:205], v[4:7]
	s_setprio 0
	s_barrier
	s_add_i32 s37, 0, 0x18000
	s_add_i32 s26, 0, 0x1c000
	v_add_u32_e32 v140, s37, v208
	v_add_u32_e32 v156, s26, v208
	s_add_u32 s6, s6, 0x80000
	s_addc_u32 s7, s7, 0
	s_mov_b32 m0, s29
	v_lshl_add_u64 v[224:225], s[6:7], 0, v[168:169]
	global_load_lds_dwordx4 v[224:225], off
	v_lshl_add_u64 v[224:225], s[6:7], 0, v[172:173]
	s_mov_b32 m0, s30
	s_nop 0
	global_load_lds_dwordx4 v[224:225], off
	ds_read_b128 v[128:131], v140
	ds_read_b128 v[132:135], v140 offset:1024
	ds_read_b128 v[136:139], v140 offset:2048
	ds_read_b128 v[140:143], v140 offset:3072
	ds_read_b128 v[144:147], v156
	ds_read_b128 v[148:151], v156 offset:1024
	ds_read_b128 v[152:155], v156 offset:2048
	ds_read_b128 v[156:159], v156 offset:3072
	ds_read_b128 v[160:163], v211 offset:32768
	ds_read_b128 v[164:167], v211 offset:33792
	ds_read_b128 v[182:185], v211 offset:34816
	ds_read_b128 v[186:189], v211 offset:35840
	ds_read_b128 v[190:193], v211 offset:36864
	ds_read_b128 v[194:197], v211 offset:37888
	ds_read_b128 v[198:201], v211 offset:38912
	ds_read_b128 v[202:205], v211 offset:39936
	s_waitcnt vmcnt(8) lgkmcnt(0)
	s_barrier
	s_setprio 1
	v_mfma_f32_16x16x32_bf16 v[124:127], v[128:131], v[160:163], v[124:127]
	v_mfma_f32_16x16x32_bf16 v[120:123], v[136:139], v[160:163], v[120:123]
	v_mfma_f32_16x16x32_bf16 v[116:119], v[128:131], v[182:185], v[116:119]
	v_mfma_f32_16x16x32_bf16 v[112:115], v[136:139], v[182:185], v[112:115]
	v_mfma_f32_16x16x32_bf16 v[108:111], v[128:131], v[190:193], v[108:111]
	v_mfma_f32_16x16x32_bf16 v[104:107], v[136:139], v[190:193], v[104:107]
	v_mfma_f32_16x16x32_bf16 v[96:99], v[128:131], v[198:201], v[96:99]
	v_mfma_f32_16x16x32_bf16 v[100:103], v[136:139], v[198:201], v[100:103]
	v_mfma_f32_16x16x32_bf16 v[124:127], v[132:135], v[164:167], v[124:127]
	v_mfma_f32_16x16x32_bf16 v[120:123], v[140:143], v[164:167], v[120:123]
	v_mfma_f32_16x16x32_bf16 v[116:119], v[132:135], v[186:189], v[116:119]
	v_mfma_f32_16x16x32_bf16 v[112:115], v[140:143], v[186:189], v[112:115]
	v_mfma_f32_16x16x32_bf16 v[108:111], v[132:135], v[194:197], v[108:111]
	v_mfma_f32_16x16x32_bf16 v[104:107], v[140:143], v[194:197], v[104:107]
	v_mfma_f32_16x16x32_bf16 v[96:99], v[132:135], v[202:205], v[96:99]
	v_mfma_f32_16x16x32_bf16 v[100:103], v[140:143], v[202:205], v[100:103]
	s_setprio 0
	s_setprio 1
	v_mfma_f32_16x16x32_bf16 v[60:63], v[144:147], v[160:163], v[60:63]
	v_mfma_f32_16x16x32_bf16 v[56:59], v[152:155], v[160:163], v[56:59]
	v_mfma_f32_16x16x32_bf16 v[52:55], v[144:147], v[182:185], v[52:55]
	v_mfma_f32_16x16x32_bf16 v[48:51], v[152:155], v[182:185], v[48:51]
	v_mfma_f32_16x16x32_bf16 v[44:47], v[144:147], v[190:193], v[44:47]
	v_mfma_f32_16x16x32_bf16 v[40:43], v[152:155], v[190:193], v[40:43]
	v_mfma_f32_16x16x32_bf16 v[32:35], v[144:147], v[198:201], v[32:35]
	v_mfma_f32_16x16x32_bf16 v[36:39], v[152:155], v[198:201], v[36:39]
	v_mfma_f32_16x16x32_bf16 v[60:63], v[148:151], v[164:167], v[60:63]
	v_mfma_f32_16x16x32_bf16 v[56:59], v[156:159], v[164:167], v[56:59]
	v_mfma_f32_16x16x32_bf16 v[52:55], v[148:151], v[186:189], v[52:55]
	v_mfma_f32_16x16x32_bf16 v[48:51], v[156:159], v[186:189], v[48:51]
	v_mfma_f32_16x16x32_bf16 v[44:47], v[148:151], v[194:197], v[44:47]
	v_mfma_f32_16x16x32_bf16 v[40:43], v[156:159], v[194:197], v[40:43]
	v_mfma_f32_16x16x32_bf16 v[32:35], v[148:151], v[202:205], v[32:35]
	v_mfma_f32_16x16x32_bf16 v[36:39], v[156:159], v[202:205], v[36:39]
	s_setprio 0
	s_barrier
; #define PG8_STAGE(bufoff, gbase, voff) do { _Pragma("unroll") for (int _i = 0; _i < 2; ++_i) \
;         __builtin_amdgcn_global_load_lds((const unsigned*)((const char*)(gbase) + (voff)[_i]), (LAS unsigned*)(lds + (bufoff) + ldsw + _i * 8192), 16, 0, 0); } while (0)
; #define PG8_LDA(dst, b, h) do { _Pragma("unroll") for (int m = 0; m < 4; ++m) _Pragma("unroll") for (int k = 0; k < 2; ++k) dst[m][k] = *(const LAS bf16x8*)(lds + PG8_SA(b, h) + aoff + m * 2048 + k * 1024); } while (0)
; #define PG8_MMA(ai, bj, At, Bt) do { __builtin_amdgcn_s_setprio(1); _Pragma("unroll") for (int m = 0; m < 4; ++m) _Pragma("unroll") for (int n = 0; n < 2; ++n) _Pragma("unroll") for (int k = 0; k < 2; ++k) \
;         acc[ai][bj][m][n] = __builtin_amdgcn_mfma_f32_16x16x32_bf16(Bt[n][k], At[m][k], acc[ai][bj][m][n], 0, 0, 0); __builtin_amdgcn_s_setprio(0); } while (0)
; #define PG8_WAIT_V(n) asm volatile("s_waitcnt vmcnt(" #n ")" ::: "memory")
; #define PG8_WAIT_L(n) asm volatile("s_waitcnt lgkmcnt(" #n ")" ::: "memory")
; #define PG8_BAR __builtin_amdgcn_s_barrier()
; #define PG8_SCHED __builtin_amdgcn_sched_barrier(0)
; template <class Epi, class Sched>
; __device__ __forceinline__ void gemm_phase(LAS unsigned char* lds, const Gemm g, const Sched& S, const Epi& E) {
;     ...
;             PG8_WAIT_V(8); PG8_WAIT_L(0); PG8_BAR; PG8_MMA(0, 0, At, B0); PG8_MMA(0, 1, At, B1); PG8_BAR; PG8_SCHED;
;             PG8_LDA(At, 1, 1); PG8_STAGE(PG8_SB(1, 0), b3, voffB); PG8_STAGE(PG8_SB(1, 1), b3 + hstepB, voffB); PG8_STAGE(PG8_SA(1, 0), a3, voffA);
;             PG8_WAIT_V(8); PG8_WAIT_L(0); PG8_BAR; PG8_MMA(1, 0, At, B0); PG8_MMA(1, 1, At, B1); PG8_BAR; PG8_SCHED;
;         }
;         if (wr == 0) PG8_BAR;
	s_add_i32 s6, s37, s14
	v_lshl_add_u64 v[216:217], v[216:217], 0, s[80:81]
	s_mov_b32 m0, s6
	s_nop 0
	global_load_lds_dwordx4 v[216:217], off
	s_add_i32 m0, s6, 0x2000
	s_add_u32 s4, s4, 0x80080
	v_lshl_add_u64 v[216:217], v[218:219], 0, s[80:81]
	s_addc_u32 s5, s5, 0
	s_add_i32 s6, s26, s14
	global_load_lds_dwordx4 v[216:217], off
	v_lshl_add_u64 v[216:217], s[4:5], 0, v[170:171]
	s_mov_b32 m0, s6
	s_nop 0
	global_load_lds_dwordx4 v[216:217], off
	v_lshl_add_u64 v[216:217], s[4:5], 0, v[174:175]
	s_add_i32 m0, s6, 0x2000
	s_nop 0
	global_load_lds_dwordx4 v[216:217], off
	v_lshl_add_u64 v[216:217], v[220:221], 0, s[80:81]
	s_mov_b32 m0, s21
	s_nop 0
	global_load_lds_dwordx4 v[216:217], off
	v_lshl_add_u64 v[216:217], v[222:223], 0, s[80:81]
	s_mov_b32 m0, s18
	s_nop 0
	global_load_lds_dwordx4 v[216:217], off
	ds_read_b128 v[160:163], v211 offset:49152
	ds_read_b128 v[164:167], v211 offset:50176
	ds_read_b128 v[182:185], v211 offset:51200
	ds_read_b128 v[186:189], v211 offset:52224
	ds_read_b128 v[190:193], v211 offset:53248
	ds_read_b128 v[194:197], v211 offset:54272
	ds_read_b128 v[198:201], v211 offset:55296
	ds_read_b128 v[202:205], v211 offset:56320
	s_waitcnt vmcnt(8) lgkmcnt(0)
	s_barrier
	s_setprio 1
	v_mfma_f32_16x16x32_bf16 v[92:95], v[128:131], v[160:163], v[92:95]
	v_mfma_f32_16x16x32_bf16 v[88:91], v[136:139], v[160:163], v[88:91]
	v_mfma_f32_16x16x32_bf16 v[84:87], v[128:131], v[182:185], v[84:87]
	v_mfma_f32_16x16x32_bf16 v[80:83], v[136:139], v[182:185], v[80:83]
	v_mfma_f32_16x16x32_bf16 v[76:79], v[128:131], v[190:193], v[76:79]
	v_mfma_f32_16x16x32_bf16 v[72:75], v[136:139], v[190:193], v[72:75]
	v_mfma_f32_16x16x32_bf16 v[64:67], v[128:131], v[198:201], v[64:67]
	v_mfma_f32_16x16x32_bf16 v[68:71], v[136:139], v[198:201], v[68:71]
	v_mfma_f32_16x16x32_bf16 v[92:95], v[132:135], v[164:167], v[92:95]
	v_mfma_f32_16x16x32_bf16 v[88:91], v[140:143], v[164:167], v[88:91]
	v_mfma_f32_16x16x32_bf16 v[84:87], v[132:135], v[186:189], v[84:87]
	v_mfma_f32_16x16x32_bf16 v[80:83], v[140:143], v[186:189], v[80:83]
	v_mfma_f32_16x16x32_bf16 v[76:79], v[132:135], v[194:197], v[76:79]
	v_mfma_f32_16x16x32_bf16 v[72:75], v[140:143], v[194:197], v[72:75]
	v_mfma_f32_16x16x32_bf16 v[64:67], v[132:135], v[202:205], v[64:67]
	v_mfma_f32_16x16x32_bf16 v[68:71], v[140:143], v[202:205], v[68:71]
	s_setprio 0
	s_setprio 1
	v_mfma_f32_16x16x32_bf16 v[28:31], v[144:147], v[160:163], v[28:31]
	v_mfma_f32_16x16x32_bf16 v[24:27], v[152:155], v[160:163], v[24:27]
	v_mfma_f32_16x16x32_bf16 v[20:23], v[144:147], v[182:185], v[20:23]
	v_mfma_f32_16x16x32_bf16 v[16:19], v[152:155], v[182:185], v[16:19]
	v_mfma_f32_16x16x32_bf16 v[12:15], v[144:147], v[190:193], v[12:15]
	v_mfma_f32_16x16x32_bf16 v[8:11], v[152:155], v[190:193], v[8:11]
	v_mfma_f32_16x16x32_bf16 v[0:3], v[144:147], v[198:201], v[0:3]
	v_mfma_f32_16x16x32_bf16 v[4:7], v[152:155], v[198:201], v[4:7]
	v_mfma_f32_16x16x32_bf16 v[28:31], v[148:151], v[164:167], v[28:31]
	v_mfma_f32_16x16x32_bf16 v[24:27], v[156:159], v[164:167], v[24:27]
	v_mfma_f32_16x16x32_bf16 v[20:23], v[148:151], v[186:189], v[20:23]
	v_mfma_f32_16x16x32_bf16 v[16:19], v[156:159], v[186:189], v[16:19]
	v_mfma_f32_16x16x32_bf16 v[12:15], v[148:151], v[194:197], v[12:15]
	v_mfma_f32_16x16x32_bf16 v[8:11], v[156:159], v[194:197], v[8:11]
	v_mfma_f32_16x16x32_bf16 v[0:3], v[148:151], v[202:205], v[0:3]
	v_mfma_f32_16x16x32_bf16 v[4:7], v[156:159], v[202:205], v[4:7]
	s_setprio 0
	s_barrier
	s_add_i32 s87, s87, 2
	s_add_u32 s0, s0, 0x100
	s_addc_u32 s1, s1, 0
	s_add_u32 s34, s34, 0x100
	s_addc_u32 s35, s35, 0
	s_cmp_gt_u32 s87, 29
	s_cbranch_scc0 .LBB0_122
	s_and_b64 vcc, exec, s[82:83]
	s_cbranch_vccz .LBB0_125
	s_barrier

; #define PG8_STAGE(bufoff, gbase, voff) do { _Pragma("unroll") for (int _i = 0; _i < 2; ++_i) \
;         __builtin_amdgcn_global_load_lds((const unsigned*)((const char*)(gbase) + (voff)[_i]), (LAS unsigned*)(lds + (bufoff) + ldsw + _i * 8192), 16, 0, 0); } while (0)
; #define PG8_LDA(dst, b, h) do { _Pragma("unroll") for (int m = 0; m < 4; ++m) _Pragma("unroll") for (int k = 0; k < 2; ++k) dst[m][k] = *(const LAS bf16x8*)(lds + PG8_SA(b, h) + aoff + m * 2048 + k * 1024); } while (0)
; #define PG8_LDB(dst, b, h) do { _Pragma("unroll") for (int n = 0; n < 2; ++n) _Pragma("unroll") for (int k = 0; k < 2; ++k) dst[n][k] = *(const LAS bf16x8*)(lds + PG8_SB(b, h) + boff + n * 2048 + k * 1024); } while (0)
; #define PG8_MMA(ai, bj, At, Bt) do { __builtin_amdgcn_s_setprio(1); _Pragma("unroll") for (int m = 0; m < 4; ++m) _Pragma("unroll") for (int n = 0; n < 2; ++n) _Pragma("unroll") for (int k = 0; k < 2; ++k) \
;         acc[ai][bj][m][n] = __builtin_amdgcn_mfma_f32_16x16x32_bf16(Bt[n][k], At[m][k], acc[ai][bj][m][n], 0, 0, 0); __builtin_amdgcn_s_setprio(0); } while (0)
; #define PG8_WAIT_V(n) asm volatile("s_waitcnt vmcnt(" #n ")" ::: "memory")
; #define PG8_WAIT_L(n) asm volatile("s_waitcnt lgkmcnt(" #n ")" ::: "memory")
; #define PG8_BAR __builtin_amdgcn_s_barrier()
; #define PG8_SCHED __builtin_amdgcn_sched_barrier(0)
; template <class Epi, class Sched>
; __device__ __forceinline__ void gemm_phase(LAS unsigned char* lds, const Gemm g, const Sched& S, const Epi& E) {
;     ...
;             const bool last = (t == nt - 2);
;             const char* a1 = cA + (size_t)(t + 1) * kstep;
;             const char* a2 = last ? nA : cA + (size_t)(t + 2) * kstep; const char* b2 = last ? nB : cB + (size_t)(t + 2) * kstep;
;             const char* a3 = a2 + kstep; const char* b3 = b2 + kstep;
;             PG8_LDB(B0, 0, 0); PG8_LDB(B1, 0, 1); PG8_SCHED; PG8_LDA(At, 0, 0); PG8_STAGE(PG8_SA(1, 1), a1 + hstepA, voffA);
;             PG8_WAIT_V(8); PG8_WAIT_L(0); PG8_BAR; PG8_MMA(0, 0, At, B0); PG8_MMA(0, 1, At, B1); PG8_BAR; PG8_SCHED;
;             PG8_LDA(At, 0, 1); PG8_STAGE(PG8_SB(0, 0), b2, voffB); PG8_STAGE(PG8_SB(0, 1), b2 + hstepB, voffB); PG8_STAGE(PG8_SA(0, 0), a2, voffA);
;             PG8_WAIT_V(8); PG8_WAIT_L(0); PG8_BAR; PG8_MMA(1, 0, At, B0); PG8_MMA(1, 1, At, B1); PG8_BAR; PG8_SCHED;
.LBB0_531:
	s_add_u32 s61, s76, s82
	s_addc_u32 s73, s77, s83
	s_add_u32 s86, s61, 0x100
	s_addc_u32 s87, s73, 0
	s_and_b64 s[84:85], s[80:81], exec
	s_cselect_b32 s85, s12, s87
	s_cselect_b32 s84, s13, s86
	s_add_u32 s82, s74, s82
	s_addc_u32 s83, s75, s83
	s_add_u32 s82, s82, 0x100
	s_addc_u32 s83, s83, 0
	s_and_b64 s[80:81], s[80:81], exec
	s_cselect_b32 s87, s49, s83
	s_cselect_b32 s86, s59, s82
	s_add_u32 s90, s61, 0x40080
	s_addc_u32 s91, s73, 0
	s_add_i32 s97, s33, s14
	s_add_i32 m0, s15, 0xc000
	s_add_i32 vcc_lo, s15, 0xe000
	s_add_i32 s94, s97, 0x2000
	s_add_u32 s88, s86, 0x10000
	s_addc_u32 s89, s87, 0
	s_add_i32 s96, s36, s14
	s_add_i32 s95, s96, 0x2000
	s_add_u32 s82, s84, 0x40000
	s_addc_u32 s83, s85, 0
	s_add_i32 s93, s37, s14
	s_add_i32 s73, s93, 0x2000
	s_add_u32 s80, s86, 0x10080
	s_addc_u32 s81, s87, 0
	s_add_i32 s92, s26, s14
	s_add_i32 s61, s92, 0x2000
	v_lshl_add_u64 v[210:211], s[90:91], 0, v[150:151]
	global_load_lds_dwordx4 v[210:211], off
	v_lshl_add_u64 v[210:211], s[90:91], 0, v[146:147]
	s_mov_b32 m0, vcc_lo
	s_nop 0
	global_load_lds_dwordx4 v[210:211], off
	ds_read_b128 v[128:131], v163
	ds_read_b128 v[132:135], v163 offset:1024
	ds_read_b128 v[136:139], v163 offset:2048
	ds_read_b128 v[140:143], v163 offset:3072
	ds_read_b128 v[156:159], v164
	ds_read_b128 v[166:169], v164 offset:1024
	ds_read_b128 v[170:173], v164 offset:2048
	ds_read_b128 v[174:177], v164 offset:3072
	ds_read_b128 v[178:181], v165
	ds_read_b128 v[182:185], v165 offset:1024
	ds_read_b128 v[186:189], v165 offset:2048
	ds_read_b128 v[190:193], v165 offset:3072
	ds_read_b128 v[194:197], v165 offset:4096
	ds_read_b128 v[198:201], v165 offset:5120
	ds_read_b128 v[202:205], v165 offset:6144
	ds_read_b128 v[206:209], v165 offset:7168
	s_waitcnt vmcnt(8) lgkmcnt(0)
	s_barrier
	s_setprio 1
	v_mfma_f32_16x16x32_bf16 v[124:127], v[128:131], v[178:181], v[124:127]
	v_mfma_f32_16x16x32_bf16 v[120:123], v[136:139], v[178:181], v[120:123]
	v_mfma_f32_16x16x32_bf16 v[116:119], v[128:131], v[186:189], v[116:119]
	v_mfma_f32_16x16x32_bf16 v[112:115], v[136:139], v[186:189], v[112:115]
	v_mfma_f32_16x16x32_bf16 v[108:111], v[128:131], v[194:197], v[108:111]
	v_mfma_f32_16x16x32_bf16 v[100:103], v[136:139], v[194:197], v[100:103]
	v_mfma_f32_16x16x32_bf16 v[92:95], v[128:131], v[202:205], v[92:95]
	v_mfma_f32_16x16x32_bf16 v[84:87], v[136:139], v[202:205], v[84:87]
	v_mfma_f32_16x16x32_bf16 v[124:127], v[132:135], v[182:185], v[124:127]
	v_mfma_f32_16x16x32_bf16 v[120:123], v[140:143], v[182:185], v[120:123]
	v_mfma_f32_16x16x32_bf16 v[116:119], v[132:135], v[190:193], v[116:119]
	v_mfma_f32_16x16x32_bf16 v[112:115], v[140:143], v[190:193], v[112:115]
	v_mfma_f32_16x16x32_bf16 v[108:111], v[132:135], v[198:201], v[108:111]
	v_mfma_f32_16x16x32_bf16 v[100:103], v[140:143], v[198:201], v[100:103]
	v_mfma_f32_16x16x32_bf16 v[92:95], v[132:135], v[206:209], v[92:95]
	v_mfma_f32_16x16x32_bf16 v[84:87], v[140:143], v[206:209], v[84:87]
	s_setprio 0
	s_setprio 1
	v_mfma_f32_16x16x32_bf16 v[104:107], v[156:159], v[178:181], v[104:107]
	v_mfma_f32_16x16x32_bf16 v[96:99], v[170:173], v[178:181], v[96:99]
	v_mfma_f32_16x16x32_bf16 v[88:91], v[156:159], v[186:189], v[88:91]
	v_mfma_f32_16x16x32_bf16 v[80:83], v[170:173], v[186:189], v[80:83]
	v_mfma_f32_16x16x32_bf16 v[76:79], v[156:159], v[194:197], v[76:79]
	v_mfma_f32_16x16x32_bf16 v[72:75], v[170:173], v[194:197], v[72:75]
	v_mfma_f32_16x16x32_bf16 v[68:71], v[156:159], v[202:205], v[68:71]
	v_mfma_f32_16x16x32_bf16 v[64:67], v[170:173], v[202:205], v[64:67]
	v_mfma_f32_16x16x32_bf16 v[104:107], v[166:169], v[182:185], v[104:107]
	v_mfma_f32_16x16x32_bf16 v[96:99], v[174:177], v[182:185], v[96:99]
	v_mfma_f32_16x16x32_bf16 v[88:91], v[166:169], v[190:193], v[88:91]
	v_mfma_f32_16x16x32_bf16 v[80:83], v[174:177], v[190:193], v[80:83]
	v_mfma_f32_16x16x32_bf16 v[76:79], v[166:169], v[198:201], v[76:79]
	v_mfma_f32_16x16x32_bf16 v[72:75], v[174:177], v[198:201], v[72:75]
	v_mfma_f32_16x16x32_bf16 v[68:71], v[166:169], v[206:209], v[68:71]
	v_mfma_f32_16x16x32_bf16 v[64:67], v[174:177], v[206:209], v[64:67]
	s_setprio 0
	s_barrier
	s_mov_b32 m0, s97
	v_lshl_add_u64 v[210:211], s[86:87], 0, v[148:149]
	global_load_lds_dwordx4 v[210:211], off
	v_lshl_add_u64 v[216:217], s[86:87], 0, v[144:145]
	s_mov_b32 m0, s94
	v_lshl_add_u64 v[218:219], s[88:89], 0, v[148:149]
	global_load_lds_dwordx4 v[216:217], off
	s_mov_b32 m0, s96
	v_lshl_add_u64 v[220:221], s[84:85], 0, v[146:147]
	global_load_lds_dwordx4 v[218:219], off
	v_lshl_add_u64 v[218:219], s[88:89], 0, v[144:145]
	s_mov_b32 m0, s95
	s_nop 0
	global_load_lds_dwordx4 v[218:219], off
	v_lshl_add_u64 v[218:219], s[84:85], 0, v[150:151]
	s_mov_b32 m0, s15
	s_nop 0
	global_load_lds_dwordx4 v[218:219], off
	s_mov_b32 m0, s18
	s_nop 0
	global_load_lds_dwordx4 v[220:221], off
	ds_read_b128 v[178:181], v165 offset:16384
	ds_read_b128 v[182:185], v165 offset:17408
	ds_read_b128 v[186:189], v165 offset:18432
	ds_read_b128 v[190:193], v165 offset:19456
	ds_read_b128 v[194:197], v165 offset:20480
	ds_read_b128 v[198:201], v165 offset:21504
	ds_read_b128 v[202:205], v165 offset:22528
	ds_read_b128 v[206:209], v165 offset:23552
	s_waitcnt vmcnt(8) lgkmcnt(0)
	s_barrier
; #define PG8_STAGE(bufoff, gbase, voff) do { _Pragma("unroll") for (int _i = 0; _i < 2; ++_i) \
;         __builtin_amdgcn_global_load_lds((const unsigned*)((const char*)(gbase) + (voff)[_i]), (LAS unsigned*)(lds + (bufoff) + ldsw + _i * 8192), 16, 0, 0); } while (0)
; #define PG8_LDA(dst, b, h) do { _Pragma("unroll") for (int m = 0; m < 4; ++m) _Pragma("unroll") for (int k = 0; k < 2; ++k) dst[m][k] = *(const LAS bf16x8*)(lds + PG8_SA(b, h) + aoff + m * 2048 + k * 1024); } while (0)
; #define PG8_LDB(dst, b, h) do { _Pragma("unroll") for (int n = 0; n < 2; ++n) _Pragma("unroll") for (int k = 0; k < 2; ++k) dst[n][k] = *(const LAS bf16x8*)(lds + PG8_SB(b, h) + boff + n * 2048 + k * 1024); } while (0)
; #define PG8_MMA(ai, bj, At, Bt) do { __builtin_amdgcn_s_setprio(1); _Pragma("unroll") for (int m = 0; m < 4; ++m) _Pragma("unroll") for (int n = 0; n < 2; ++n) _Pragma("unroll") for (int k = 0; k < 2; ++k) \
;         acc[ai][bj][m][n] = __builtin_amdgcn_mfma_f32_16x16x32_bf16(Bt[n][k], At[m][k], acc[ai][bj][m][n], 0, 0, 0); __builtin_amdgcn_s_setprio(0); } while (0)
; #define PG8_WAIT_V(n) asm volatile("s_waitcnt vmcnt(" #n ")" ::: "memory")
; #define PG8_WAIT_L(n) asm volatile("s_waitcnt lgkmcnt(" #n ")" ::: "memory")
; #define PG8_BAR __builtin_amdgcn_s_barrier()
; #define PG8_SCHED __builtin_amdgcn_sched_barrier(0)
; template <class Epi, class Sched>
; __device__ __forceinline__ void gemm_phase(LAS unsigned char* lds, const Gemm g, const Sched& S, const Epi& E) {
;     ...
;             PG8_WAIT_V(8); PG8_WAIT_L(0); PG8_BAR; PG8_MMA(0, 0, At, B0); PG8_MMA(0, 1, At, B1); PG8_BAR; PG8_SCHED;
;             PG8_LDA(At, 0, 1); PG8_STAGE(PG8_SB(0, 0), b2, voffB); PG8_STAGE(PG8_SB(0, 1), b2 + hstepB, voffB); PG8_STAGE(PG8_SA(0, 0), a2, voffA);
;             PG8_WAIT_V(8); PG8_WAIT_L(0); PG8_BAR; PG8_MMA(1, 0, At, B0); PG8_MMA(1, 1, At, B1); PG8_BAR; PG8_SCHED;
;             PG8_LDB(B0, 1, 0); PG8_LDB(B1, 1, 1); PG8_SCHED; PG8_LDA(At, 1, 0); PG8_STAGE(PG8_SA(0, 1), a2 + hstepA, voffA);
;             PG8_WAIT_V(8); PG8_WAIT_L(0); PG8_BAR; PG8_MMA(0, 0, At, B0); PG8_MMA(0, 1, At, B1); PG8_BAR; PG8_SCHED;
	s_setprio 1
	v_mfma_f32_16x16x32_bf16 v[60:63], v[128:131], v[178:181], v[60:63]
	v_mfma_f32_16x16x32_bf16 v[56:59], v[136:139], v[178:181], v[56:59]
	v_mfma_f32_16x16x32_bf16 v[48:51], v[128:131], v[186:189], v[48:51]
	v_mfma_f32_16x16x32_bf16 v[40:43], v[136:139], v[186:189], v[40:43]
	v_mfma_f32_16x16x32_bf16 v[32:35], v[128:131], v[194:197], v[32:35]
	v_mfma_f32_16x16x32_bf16 v[24:27], v[136:139], v[194:197], v[24:27]
	v_mfma_f32_16x16x32_bf16 v[16:19], v[128:131], v[202:205], v[16:19]
	v_mfma_f32_16x16x32_bf16 v[8:11], v[136:139], v[202:205], v[8:11]
	v_mfma_f32_16x16x32_bf16 v[60:63], v[132:135], v[182:185], v[60:63]
	v_mfma_f32_16x16x32_bf16 v[56:59], v[140:143], v[182:185], v[56:59]
	v_mfma_f32_16x16x32_bf16 v[48:51], v[132:135], v[190:193], v[48:51]
	v_mfma_f32_16x16x32_bf16 v[40:43], v[140:143], v[190:193], v[40:43]
	v_mfma_f32_16x16x32_bf16 v[32:35], v[132:135], v[198:201], v[32:35]
	v_mfma_f32_16x16x32_bf16 v[24:27], v[140:143], v[198:201], v[24:27]
	v_mfma_f32_16x16x32_bf16 v[16:19], v[132:135], v[206:209], v[16:19]
	v_mfma_f32_16x16x32_bf16 v[8:11], v[140:143], v[206:209], v[8:11]
	s_setprio 0
	s_setprio 1
	v_mfma_f32_16x16x32_bf16 v[52:55], v[156:159], v[178:181], v[52:55]
	v_mfma_f32_16x16x32_bf16 v[44:47], v[170:173], v[178:181], v[44:47]
	v_mfma_f32_16x16x32_bf16 v[36:39], v[156:159], v[186:189], v[36:39]
	v_mfma_f32_16x16x32_bf16 v[28:31], v[170:173], v[186:189], v[28:31]
	v_mfma_f32_16x16x32_bf16 v[20:23], v[156:159], v[194:197], v[20:23]
	v_mfma_f32_16x16x32_bf16 v[12:15], v[170:173], v[194:197], v[12:15]
	v_mfma_f32_16x16x32_bf16 v[4:7], v[156:159], v[202:205], v[4:7]
	v_mfma_f32_16x16x32_bf16 v[0:3], v[170:173], v[202:205], v[0:3]
	v_mfma_f32_16x16x32_bf16 v[52:55], v[166:169], v[182:185], v[52:55]
	v_mfma_f32_16x16x32_bf16 v[44:47], v[174:177], v[182:185], v[44:47]
	v_mfma_f32_16x16x32_bf16 v[36:39], v[166:169], v[190:193], v[36:39]
	v_mfma_f32_16x16x32_bf16 v[28:31], v[174:177], v[190:193], v[28:31]
	v_mfma_f32_16x16x32_bf16 v[20:23], v[166:169], v[198:201], v[20:23]
	v_mfma_f32_16x16x32_bf16 v[12:15], v[174:177], v[198:201], v[12:15]
	v_mfma_f32_16x16x32_bf16 v[4:7], v[166:169], v[206:209], v[4:7]
	v_mfma_f32_16x16x32_bf16 v[0:3], v[174:177], v[206:209], v[0:3]
	s_setprio 0
	s_barrier
	v_add_u32_e32 v140, s37, v162
	v_add_u32_e32 v174, s26, v162
	s_mov_b32 m0, s19
	v_lshl_add_u64 v[222:223], s[82:83], 0, v[150:151]
	global_load_lds_dwordx4 v[222:223], off
	v_lshl_add_u64 v[222:223], s[82:83], 0, v[146:147]
	s_mov_b32 m0, s21
	s_nop 0
	global_load_lds_dwordx4 v[222:223], off
	ds_read_b128 v[128:131], v140
	ds_read_b128 v[132:135], v140 offset:1024
	ds_read_b128 v[136:139], v140 offset:2048
	ds_read_b128 v[140:143], v140 offset:3072
	ds_read_b128 v[156:159], v174
	ds_read_b128 v[166:169], v174 offset:1024
	ds_read_b128 v[170:173], v174 offset:2048
	ds_read_b128 v[174:177], v174 offset:3072
	ds_read_b128 v[178:181], v165 offset:32768
	ds_read_b128 v[182:185], v165 offset:33792
	ds_read_b128 v[186:189], v165 offset:34816
	ds_read_b128 v[190:193], v165 offset:35840
	ds_read_b128 v[194:197], v165 offset:36864
	ds_read_b128 v[198:201], v165 offset:37888
	ds_read_b128 v[202:205], v165 offset:38912
	ds_read_b128 v[206:209], v165 offset:39936
	s_waitcnt vmcnt(8) lgkmcnt(0)
	s_barrier
	s_setprio 1
	v_mfma_f32_16x16x32_bf16 v[124:127], v[128:131], v[178:181], v[124:127]
	v_mfma_f32_16x16x32_bf16 v[120:123], v[136:139], v[178:181], v[120:123]
	v_mfma_f32_16x16x32_bf16 v[116:119], v[128:131], v[186:189], v[116:119]
	v_mfma_f32_16x16x32_bf16 v[112:115], v[136:139], v[186:189], v[112:115]
	v_mfma_f32_16x16x32_bf16 v[108:111], v[128:131], v[194:197], v[108:111]
	v_mfma_f32_16x16x32_bf16 v[100:103], v[136:139], v[194:197], v[100:103]
	v_mfma_f32_16x16x32_bf16 v[92:95], v[128:131], v[202:205], v[92:95]
	v_mfma_f32_16x16x32_bf16 v[84:87], v[136:139], v[202:205], v[84:87]
	v_mfma_f32_16x16x32_bf16 v[124:127], v[132:135], v[182:185], v[124:127]
	v_mfma_f32_16x16x32_bf16 v[120:123], v[140:143], v[182:185], v[120:123]
	v_mfma_f32_16x16x32_bf16 v[116:119], v[132:135], v[190:193], v[116:119]
	v_mfma_f32_16x16x32_bf16 v[112:115], v[140:143], v[190:193], v[112:115]
	v_mfma_f32_16x16x32_bf16 v[108:111], v[132:135], v[198:201], v[108:111]
	v_mfma_f32_16x16x32_bf16 v[100:103], v[140:143], v[198:201], v[100:103]
	v_mfma_f32_16x16x32_bf16 v[92:95], v[132:135], v[206:209], v[92:95]
	v_mfma_f32_16x16x32_bf16 v[84:87], v[140:143], v[206:209], v[84:87]
	s_setprio 0
	s_setprio 1
	v_mfma_f32_16x16x32_bf16 v[104:107], v[156:159], v[178:181], v[104:107]
	v_mfma_f32_16x16x32_bf16 v[96:99], v[170:173], v[178:181], v[96:99]
	v_mfma_f32_16x16x32_bf16 v[88:91], v[156:159], v[186:189], v[88:91]
	v_mfma_f32_16x16x32_bf16 v[80:83], v[170:173], v[186:189], v[80:83]
	v_mfma_f32_16x16x32_bf16 v[76:79], v[156:159], v[194:197], v[76:79]
	v_mfma_f32_16x16x32_bf16 v[72:75], v[170:173], v[194:197], v[72:75]
	v_mfma_f32_16x16x32_bf16 v[68:71], v[156:159], v[202:205], v[68:71]
	v_mfma_f32_16x16x32_bf16 v[64:67], v[170:173], v[202:205], v[64:67]
	v_mfma_f32_16x16x32_bf16 v[104:107], v[166:169], v[182:185], v[104:107]
	v_mfma_f32_16x16x32_bf16 v[96:99], v[174:177], v[182:185], v[96:99]
	v_mfma_f32_16x16x32_bf16 v[88:91], v[166:169], v[190:193], v[88:91]
	v_mfma_f32_16x16x32_bf16 v[80:83], v[174:177], v[190:193], v[80:83]
	v_mfma_f32_16x16x32_bf16 v[76:79], v[166:169], v[198:201], v[76:79]
	v_mfma_f32_16x16x32_bf16 v[72:75], v[174:177], v[198:201], v[72:75]
	v_mfma_f32_16x16x32_bf16 v[68:71], v[166:169], v[206:209], v[68:71]
	v_mfma_f32_16x16x32_bf16 v[64:67], v[174:177], v[206:209], v[64:67]
	s_setprio 0
	s_barrier
; #define PG8_STAGE(bufoff, gbase, voff) do { _Pragma("unroll") for (int _i = 0; _i < 2; ++_i) \
;         __builtin_amdgcn_global_load_lds((const unsigned*)((const char*)(gbase) + (voff)[_i]), (LAS unsigned*)(lds + (bufoff) + ldsw + _i * 8192), 16, 0, 0); } while (0)
; #define PG8_LDA(dst, b, h) do { _Pragma("unroll") for (int m = 0; m < 4; ++m) _Pragma("unroll") for (int k = 0; k < 2; ++k) dst[m][k] = *(const LAS bf16x8*)(lds + PG8_SA(b, h) + aoff + m * 2048 + k * 1024); } while (0)
; #define PG8_MMA(ai, bj, At, Bt) do { __builtin_amdgcn_s_setprio(1); _Pragma("unroll") for (int m = 0; m < 4; ++m) _Pragma("unroll") for (int n = 0; n < 2; ++n) _Pragma("unroll") for (int k = 0; k < 2; ++k) \
;         acc[ai][bj][m][n] = __builtin_amdgcn_mfma_f32_16x16x32_bf16(Bt[n][k], At[m][k], acc[ai][bj][m][n], 0, 0, 0); __builtin_amdgcn_s_setprio(0); } while (0)
; #define PG8_WAIT_V(n) asm volatile("s_waitcnt vmcnt(" #n ")" ::: "memory")
; #define PG8_WAIT_L(n) asm volatile("s_waitcnt lgkmcnt(" #n ")" ::: "memory")
; #define PG8_BAR __builtin_amdgcn_s_barrier()
; #define PG8_SCHED __builtin_amdgcn_sched_barrier(0)
; template <class Epi, class Sched>
; __device__ __forceinline__ void gemm_phase(LAS unsigned char* lds, const Gemm g, const Sched& S, const Epi& E) {
;     ...
;             PG8_LDA(At, 1, 1); PG8_STAGE(PG8_SB(1, 0), b3, voffB); PG8_STAGE(PG8_SB(1, 1), b3 + hstepB, voffB); PG8_STAGE(PG8_SA(1, 0), a3, voffA);
;             PG8_WAIT_V(8); PG8_WAIT_L(0); PG8_BAR; PG8_MMA(1, 0, At, B0); PG8_MMA(1, 1, At, B1); PG8_BAR; PG8_SCHED;
;         }
;         if (wr == 0) PG8_BAR;
;         { int fr_e = fr, fq_e = fq; asm volatile("" : "+v"(fr_e), "+v"(fq_e));
;           E(acc, cur, wr, wc, fr_e, fq_e); }
;         if (!has_next) break;
	s_mov_b32 m0, s93
	v_lshl_add_u64 v[210:211], v[210:211], 0, s[8:9]
	global_load_lds_dwordx4 v[210:211], off
	v_lshl_add_u64 v[210:211], v[216:217], 0, s[8:9]
	s_mov_b32 m0, s73
	s_nop 0
	global_load_lds_dwordx4 v[210:211], off
	v_lshl_add_u64 v[210:211], s[80:81], 0, v[148:149]
	s_mov_b32 m0, s92
	s_nop 0
	global_load_lds_dwordx4 v[210:211], off
	v_lshl_add_u64 v[210:211], s[80:81], 0, v[144:145]
	s_mov_b32 m0, s61
	s_nop 0
	global_load_lds_dwordx4 v[210:211], off
	v_lshl_add_u64 v[210:211], v[218:219], 0, s[8:9]
	s_mov_b32 m0, s34
	s_nop 0
	global_load_lds_dwordx4 v[210:211], off
	v_lshl_add_u64 v[210:211], v[220:221], 0, s[8:9]
	s_mov_b32 m0, s35
	s_nop 0
	global_load_lds_dwordx4 v[210:211], off
	ds_read_b128 v[178:181], v165 offset:49152
	ds_read_b128 v[182:185], v165 offset:50176
	ds_read_b128 v[186:189], v165 offset:51200
	ds_read_b128 v[190:193], v165 offset:52224
	ds_read_b128 v[194:197], v165 offset:53248
	ds_read_b128 v[198:201], v165 offset:54272
	ds_read_b128 v[202:205], v165 offset:55296
	ds_read_b128 v[206:209], v165 offset:56320
	s_waitcnt vmcnt(8) lgkmcnt(0)
	s_barrier
	s_setprio 1
	v_mfma_f32_16x16x32_bf16 v[60:63], v[128:131], v[178:181], v[60:63]
	v_mfma_f32_16x16x32_bf16 v[56:59], v[136:139], v[178:181], v[56:59]
	v_mfma_f32_16x16x32_bf16 v[48:51], v[128:131], v[186:189], v[48:51]
	v_mfma_f32_16x16x32_bf16 v[40:43], v[136:139], v[186:189], v[40:43]
	v_mfma_f32_16x16x32_bf16 v[32:35], v[128:131], v[194:197], v[32:35]
	v_mfma_f32_16x16x32_bf16 v[24:27], v[136:139], v[194:197], v[24:27]
	v_mfma_f32_16x16x32_bf16 v[16:19], v[128:131], v[202:205], v[16:19]
	v_mfma_f32_16x16x32_bf16 v[8:11], v[136:139], v[202:205], v[8:11]
	v_mfma_f32_16x16x32_bf16 v[60:63], v[132:135], v[182:185], v[60:63]
	v_mfma_f32_16x16x32_bf16 v[56:59], v[140:143], v[182:185], v[56:59]
	v_mfma_f32_16x16x32_bf16 v[48:51], v[132:135], v[190:193], v[48:51]
	v_mfma_f32_16x16x32_bf16 v[40:43], v[140:143], v[190:193], v[40:43]
	v_mfma_f32_16x16x32_bf16 v[32:35], v[132:135], v[198:201], v[32:35]
	v_mfma_f32_16x16x32_bf16 v[24:27], v[140:143], v[198:201], v[24:27]
	v_mfma_f32_16x16x32_bf16 v[16:19], v[132:135], v[206:209], v[16:19]
	v_mfma_f32_16x16x32_bf16 v[8:11], v[140:143], v[206:209], v[8:11]
	s_setprio 0
	s_setprio 1
	v_mfma_f32_16x16x32_bf16 v[52:55], v[156:159], v[178:181], v[52:55]
	v_mfma_f32_16x16x32_bf16 v[44:47], v[170:173], v[178:181], v[44:47]
	v_mfma_f32_16x16x32_bf16 v[36:39], v[156:159], v[186:189], v[36:39]
	v_mfma_f32_16x16x32_bf16 v[28:31], v[170:173], v[186:189], v[28:31]
	v_mfma_f32_16x16x32_bf16 v[20:23], v[156:159], v[194:197], v[20:23]
	v_mfma_f32_16x16x32_bf16 v[12:15], v[170:173], v[194:197], v[12:15]
	v_mfma_f32_16x16x32_bf16 v[4:7], v[156:159], v[202:205], v[4:7]
	v_mfma_f32_16x16x32_bf16 v[0:3], v[170:173], v[202:205], v[0:3]
	v_mfma_f32_16x16x32_bf16 v[52:55], v[166:169], v[182:185], v[52:55]
	v_mfma_f32_16x16x32_bf16 v[44:47], v[174:177], v[182:185], v[44:47]
	v_mfma_f32_16x16x32_bf16 v[36:39], v[166:169], v[190:193], v[36:39]
	v_mfma_f32_16x16x32_bf16 v[28:31], v[174:177], v[190:193], v[28:31]
	v_mfma_f32_16x16x32_bf16 v[20:23], v[166:169], v[198:201], v[20:23]
	v_mfma_f32_16x16x32_bf16 v[12:15], v[174:177], v[198:201], v[12:15]
	v_mfma_f32_16x16x32_bf16 v[4:7], v[166:169], v[206:209], v[4:7]
	v_mfma_f32_16x16x32_bf16 v[0:3], v[174:177], v[206:209], v[0:3]
	s_setprio 0
	s_barrier
	s_andn2_b64 vcc, exec, s[78:79]
	s_mov_b64 s[80:81], -1
	s_mov_b64 s[78:79], 0
	s_mov_b64 s[82:83], 0x100
	s_cbranch_vccz .LBB0_531
	v_readlane_b32 s80, v248, 11
	s_and_b64 vcc, exec, s[56:57]
	v_readlane_b32 s81, v248, 12
	v_readlane_b32 s82, v248, 13
	v_readlane_b32 s83, v248, 14
	v_readlane_b32 s84, v248, 15
	v_readlane_b32 s85, v248, 16
	v_readlane_b32 s86, v248, 17
	v_readlane_b32 s87, v248, 18
	v_readlane_b32 s88, v248, 19
	v_readlane_b32 s89, v248, 20
	v_readlane_b32 s90, v248, 21
	v_readlane_b32 s91, v248, 22
	v_readlane_b32 s92, v248, 23
	v_readlane_b32 s93, v248, 24
	v_readlane_b32 s94, v248, 25
	v_readlane_b32 s95, v248, 26
	s_cbranch_vccz .LBB0_534
	s_barrier

; #define PG8_STAGE(bufoff, gbase, voff) do { _Pragma("unroll") for (int _i = 0; _i < 2; ++_i) \
;         __builtin_amdgcn_global_load_lds((const unsigned*)((const char*)(gbase) + (voff)[_i]), (LAS unsigned*)(lds + (bufoff) + ldsw + _i * 8192), 16, 0, 0); } while (0)
; #define PG8_LDA(dst, b, h) do { _Pragma("unroll") for (int m = 0; m < 4; ++m) _Pragma("unroll") for (int k = 0; k < 2; ++k) dst[m][k] = *(const LAS bf16x8*)(lds + PG8_SA(b, h) + aoff + m * 2048 + k * 1024); } while (0)
; #define PG8_LDB(dst, b, h) do { _Pragma("unroll") for (int n = 0; n < 2; ++n) _Pragma("unroll") for (int k = 0; k < 2; ++k) dst[n][k] = *(const LAS bf16x8*)(lds + PG8_SB(b, h) + boff + n * 2048 + k * 1024); } while (0)
; #define PG8_MMA(ai, bj, At, Bt) do { __builtin_amdgcn_s_setprio(1); _Pragma("unroll") for (int m = 0; m < 4; ++m) _Pragma("unroll") for (int n = 0; n < 2; ++n) _Pragma("unroll") for (int k = 0; k < 2; ++k) \
;         acc[ai][bj][m][n] = __builtin_amdgcn_mfma_f32_16x16x32_bf16(Bt[n][k], At[m][k], acc[ai][bj][m][n], 0, 0, 0); __builtin_amdgcn_s_setprio(0); } while (0)
; #define PG8_WAIT_V(n) asm volatile("s_waitcnt vmcnt(" #n ")" ::: "memory")
; #define PG8_WAIT_L(n) asm volatile("s_waitcnt lgkmcnt(" #n ")" ::: "memory")
; #define PG8_BAR __builtin_amdgcn_s_barrier()
; #define PG8_SCHED __builtin_amdgcn_sched_barrier(0)
; template <class Epi, class Sched>
; __device__ __forceinline__ void gemm_phase(LAS unsigned char* lds, const Gemm g, const Sched& S, const Epi& E) {
;     ...
;             const bool last = (t == nt - 2);
;             const char* a1 = cA + (size_t)(t + 1) * kstep;
;             const char* a2 = last ? nA : cA + (size_t)(t + 2) * kstep; const char* b2 = last ? nB : cB + (size_t)(t + 2) * kstep;
;             const char* a3 = a2 + kstep; const char* b3 = b2 + kstep;
;             PG8_LDB(B0, 0, 0); PG8_LDB(B1, 0, 1); PG8_SCHED; PG8_LDA(At, 0, 0); PG8_STAGE(PG8_SA(1, 1), a1 + hstepA, voffA);
;             PG8_WAIT_V(8); PG8_WAIT_L(0); PG8_BAR; PG8_MMA(0, 0, At, B0); PG8_MMA(0, 1, At, B1); PG8_BAR; PG8_SCHED;
;             PG8_LDA(At, 0, 1); PG8_STAGE(PG8_SB(0, 0), b2, voffB); PG8_STAGE(PG8_SB(0, 1), b2 + hstepB, voffB); PG8_STAGE(PG8_SA(0, 0), a2, voffA);
;             PG8_WAIT_V(8); PG8_WAIT_L(0); PG8_BAR; PG8_MMA(1, 0, At, B0); PG8_MMA(1, 1, At, B1); PG8_BAR; PG8_SCHED;
.LBB0_553:
	s_add_u32 s35, s78, s82
	s_addc_u32 s45, s79, s83
	s_add_u32 s63, s35, 0x100
	s_addc_u32 s65, s45, 0
	s_and_b64 s[48:49], s[80:81], exec
	s_cselect_b32 s85, s71, s65
	s_cselect_b32 s84, s70, s63
	s_add_u32 s48, s76, s82
	s_addc_u32 s49, s77, s83
	s_add_u32 s63, s48, 0x100
	s_addc_u32 s65, s49, 0
	s_and_b64 s[48:49], s[80:81], exec
	s_cselect_b32 s87, s31, s65
	s_cselect_b32 s86, s34, s63
	s_add_u32 s90, s35, 0x80080
	s_addc_u32 s91, s45, 0
	s_add_i32 s75, s33, s12
	s_add_i32 m0, s13, 0xc000
	s_add_i32 s92, s13, 0xe000
	s_add_i32 s63, s75, 0x2000
	s_add_u32 s88, s86, 0x10000
	s_addc_u32 s89, s87, 0
	s_add_i32 s67, s36, s12
	s_add_i32 s65, s67, 0x2000
	s_add_u32 s82, s84, 0x80000
	s_addc_u32 s83, s85, 0
	s_add_i32 s49, s37, s12
	s_add_i32 s45, s49, 0x2000
	s_add_u32 s80, s86, 0x10080
	s_addc_u32 s81, s87, 0
	s_add_i32 s48, s26, s12
	s_add_i32 s35, s48, 0x2000
	v_lshl_add_u64 v[204:205], s[90:91], 0, v[190:191]
	global_load_lds_dwordx4 v[204:205], off
	v_lshl_add_u64 v[204:205], s[90:91], 0, v[186:187]
	s_mov_b32 m0, s92
	s_nop 0
	global_load_lds_dwordx4 v[204:205], off
	ds_read_b128 v[64:67], v218
	ds_read_b128 v[68:71], v218 offset:1024
	ds_read_b128 v[72:75], v218 offset:2048
	ds_read_b128 v[80:83], v218 offset:3072
	ds_read_b128 v[88:91], v219
	ds_read_b128 v[92:95], v219 offset:1024
	ds_read_b128 v[100:103], v219 offset:2048
	ds_read_b128 v[108:111], v219 offset:3072
	ds_read_b128 v[128:131], v220
	ds_read_b128 v[148:151], v220 offset:1024
	ds_read_b128 v[164:167], v220 offset:2048
	ds_read_b128 v[172:175], v220 offset:3072
	ds_read_b128 v[176:179], v220 offset:4096
	ds_read_b128 v[180:183], v220 offset:5120
	ds_read_b128 v[196:199], v220 offset:6144
	ds_read_b128 v[200:203], v220 offset:7168
	s_waitcnt vmcnt(8) lgkmcnt(0)
	s_barrier
	s_setprio 1
	v_mfma_f32_16x16x32_bf16 v[168:171], v[64:67], v[128:131], v[168:171]
	v_mfma_f32_16x16x32_bf16 v[156:159], v[72:75], v[128:131], v[156:159]
	v_mfma_f32_16x16x32_bf16 v[144:147], v[64:67], v[164:167], v[144:147]
	v_mfma_f32_16x16x32_bf16 v[136:139], v[72:75], v[164:167], v[136:139]
	v_mfma_f32_16x16x32_bf16 v[124:127], v[64:67], v[176:179], v[124:127]
	v_mfma_f32_16x16x32_bf16 v[116:119], v[72:75], v[176:179], v[116:119]
	v_mfma_f32_16x16x32_bf16 v[104:107], v[64:67], v[196:199], v[104:107]
	v_mfma_f32_16x16x32_bf16 v[84:87], v[72:75], v[196:199], v[84:87]
	v_mfma_f32_16x16x32_bf16 v[168:171], v[68:71], v[148:151], v[168:171]
	v_mfma_f32_16x16x32_bf16 v[156:159], v[80:83], v[148:151], v[156:159]
	v_mfma_f32_16x16x32_bf16 v[144:147], v[68:71], v[172:175], v[144:147]
	v_mfma_f32_16x16x32_bf16 v[136:139], v[80:83], v[172:175], v[136:139]
	v_mfma_f32_16x16x32_bf16 v[124:127], v[68:71], v[180:183], v[124:127]
	v_mfma_f32_16x16x32_bf16 v[116:119], v[80:83], v[180:183], v[116:119]
	v_mfma_f32_16x16x32_bf16 v[104:107], v[68:71], v[200:203], v[104:107]
	v_mfma_f32_16x16x32_bf16 v[84:87], v[80:83], v[200:203], v[84:87]
	s_setprio 0
	s_setprio 1
	v_mfma_f32_16x16x32_bf16 v[160:163], v[88:91], v[128:131], v[160:163]
	v_mfma_f32_16x16x32_bf16 v[140:143], v[88:91], v[164:167], v[140:143]
	v_mfma_f32_16x16x32_bf16 v[132:135], v[100:103], v[164:167], v[132:135]
	v_mfma_f32_16x16x32_bf16 v[120:123], v[88:91], v[176:179], v[120:123]
	v_mfma_f32_16x16x32_bf16 v[112:115], v[100:103], v[176:179], v[112:115]
	v_mfma_f32_16x16x32_bf16 v[96:99], v[88:91], v[196:199], v[96:99]
	v_mfma_f32_16x16x32_bf16 v[76:79], v[100:103], v[196:199], v[76:79]
	v_mfma_f32_16x16x32_bf16 v[160:163], v[92:95], v[148:151], v[160:163]
	v_mfma_f32_16x16x32_bf16 v[128:131], v[100:103], v[128:131], v[152:155]
	v_mfma_f32_16x16x32_bf16 v[140:143], v[92:95], v[172:175], v[140:143]
	v_mfma_f32_16x16x32_bf16 v[132:135], v[108:111], v[172:175], v[132:135]
	v_mfma_f32_16x16x32_bf16 v[120:123], v[92:95], v[180:183], v[120:123]
	v_mfma_f32_16x16x32_bf16 v[112:115], v[108:111], v[180:183], v[112:115]
	v_mfma_f32_16x16x32_bf16 v[96:99], v[92:95], v[200:203], v[96:99]
	v_mfma_f32_16x16x32_bf16 v[76:79], v[108:111], v[200:203], v[76:79]
	v_mfma_f32_16x16x32_bf16 v[128:131], v[108:111], v[148:151], v[128:131]
	s_setprio 0
	s_barrier
	s_mov_b32 m0, s75
	v_lshl_add_u64 v[204:205], s[86:87], 0, v[188:189]
	global_load_lds_dwordx4 v[204:205], off
	v_lshl_add_u64 v[206:207], s[86:87], 0, v[184:185]
	s_mov_b32 m0, s63
	v_lshl_add_u64 v[208:209], s[88:89], 0, v[188:189]
	global_load_lds_dwordx4 v[206:207], off
	s_mov_b32 m0, s67
	v_lshl_add_u64 v[210:211], s[84:85], 0, v[186:187]
	global_load_lds_dwordx4 v[208:209], off
	v_lshl_add_u64 v[208:209], s[88:89], 0, v[184:185]
	s_mov_b32 m0, s65
	s_nop 0
	global_load_lds_dwordx4 v[208:209], off
	v_lshl_add_u64 v[208:209], s[84:85], 0, v[190:191]
	s_mov_b32 m0, s13
	s_nop 0
	global_load_lds_dwordx4 v[208:209], off
	s_mov_b32 m0, s14
	s_nop 0
	global_load_lds_dwordx4 v[210:211], off
	ds_read_b128 v[148:151], v220 offset:16384
	ds_read_b128 v[152:155], v220 offset:17408
	ds_read_b128 v[164:167], v220 offset:18432
	ds_read_b128 v[172:175], v220 offset:19456
	ds_read_b128 v[176:179], v220 offset:20480
	ds_read_b128 v[180:183], v220 offset:21504
	ds_read_b128 v[196:199], v220 offset:22528
	ds_read_b128 v[200:203], v220 offset:23552
	s_waitcnt vmcnt(8) lgkmcnt(0)
	s_barrier
; #define PG8_STAGE(bufoff, gbase, voff) do { _Pragma("unroll") for (int _i = 0; _i < 2; ++_i) \
;         __builtin_amdgcn_global_load_lds((const unsigned*)((const char*)(gbase) + (voff)[_i]), (LAS unsigned*)(lds + (bufoff) + ldsw + _i * 8192), 16, 0, 0); } while (0)
; #define PG8_LDA(dst, b, h) do { _Pragma("unroll") for (int m = 0; m < 4; ++m) _Pragma("unroll") for (int k = 0; k < 2; ++k) dst[m][k] = *(const LAS bf16x8*)(lds + PG8_SA(b, h) + aoff + m * 2048 + k * 1024); } while (0)
; #define PG8_LDB(dst, b, h) do { _Pragma("unroll") for (int n = 0; n < 2; ++n) _Pragma("unroll") for (int k = 0; k < 2; ++k) dst[n][k] = *(const LAS bf16x8*)(lds + PG8_SB(b, h) + boff + n * 2048 + k * 1024); } while (0)
; #define PG8_MMA(ai, bj, At, Bt) do { __builtin_amdgcn_s_setprio(1); _Pragma("unroll") for (int m = 0; m < 4; ++m) _Pragma("unroll") for (int n = 0; n < 2; ++n) _Pragma("unroll") for (int k = 0; k < 2; ++k) \
;         acc[ai][bj][m][n] = __builtin_amdgcn_mfma_f32_16x16x32_bf16(Bt[n][k], At[m][k], acc[ai][bj][m][n], 0, 0, 0); __builtin_amdgcn_s_setprio(0); } while (0)
; #define PG8_WAIT_V(n) asm volatile("s_waitcnt vmcnt(" #n ")" ::: "memory")
; #define PG8_WAIT_L(n) asm volatile("s_waitcnt lgkmcnt(" #n ")" ::: "memory")
; #define PG8_BAR __builtin_amdgcn_s_barrier()
; #define PG8_SCHED __builtin_amdgcn_sched_barrier(0)
; template <class Epi, class Sched>
; __device__ __forceinline__ void gemm_phase(LAS unsigned char* lds, const Gemm g, const Sched& S, const Epi& E) {
;     ...
;             PG8_WAIT_V(8); PG8_WAIT_L(0); PG8_BAR; PG8_MMA(1, 0, At, B0); PG8_MMA(1, 1, At, B1); PG8_BAR; PG8_SCHED;
;             PG8_LDB(B0, 1, 0); PG8_LDB(B1, 1, 1); PG8_SCHED; PG8_LDA(At, 1, 0); PG8_STAGE(PG8_SA(0, 1), a2 + hstepA, voffA);
;             PG8_WAIT_V(8); PG8_WAIT_L(0); PG8_BAR; PG8_MMA(0, 0, At, B0); PG8_MMA(0, 1, At, B1); PG8_BAR; PG8_SCHED;
	s_setprio 1
	v_mfma_f32_16x16x32_bf16 v[60:63], v[64:67], v[148:151], v[60:63]
	v_mfma_f32_16x16x32_bf16 v[52:55], v[72:75], v[148:151], v[52:55]
	v_mfma_f32_16x16x32_bf16 v[44:47], v[64:67], v[164:167], v[44:47]
	v_mfma_f32_16x16x32_bf16 v[36:39], v[72:75], v[164:167], v[36:39]
	v_mfma_f32_16x16x32_bf16 v[28:31], v[64:67], v[176:179], v[28:31]
	v_mfma_f32_16x16x32_bf16 v[20:23], v[72:75], v[176:179], v[20:23]
	v_mfma_f32_16x16x32_bf16 v[12:15], v[64:67], v[196:199], v[12:15]
	v_mfma_f32_16x16x32_bf16 v[4:7], v[72:75], v[196:199], v[4:7]
	v_mfma_f32_16x16x32_bf16 v[60:63], v[68:71], v[152:155], v[60:63]
	v_mfma_f32_16x16x32_bf16 v[52:55], v[80:83], v[152:155], v[52:55]
	v_mfma_f32_16x16x32_bf16 v[44:47], v[68:71], v[172:175], v[44:47]
	v_mfma_f32_16x16x32_bf16 v[36:39], v[80:83], v[172:175], v[36:39]
	v_mfma_f32_16x16x32_bf16 v[28:31], v[68:71], v[180:183], v[28:31]
	v_mfma_f32_16x16x32_bf16 v[20:23], v[80:83], v[180:183], v[20:23]
	v_mfma_f32_16x16x32_bf16 v[12:15], v[68:71], v[200:203], v[12:15]
	v_mfma_f32_16x16x32_bf16 v[4:7], v[80:83], v[200:203], v[4:7]
	s_setprio 0
	s_setprio 1
	v_mfma_f32_16x16x32_bf16 v[56:59], v[88:91], v[148:151], v[56:59]
	v_mfma_f32_16x16x32_bf16 v[48:51], v[100:103], v[148:151], v[48:51]
	v_mfma_f32_16x16x32_bf16 v[40:43], v[88:91], v[164:167], v[40:43]
	v_mfma_f32_16x16x32_bf16 v[32:35], v[100:103], v[164:167], v[32:35]
	v_mfma_f32_16x16x32_bf16 v[24:27], v[88:91], v[176:179], v[24:27]
	v_mfma_f32_16x16x32_bf16 v[16:19], v[100:103], v[176:179], v[16:19]
	v_mfma_f32_16x16x32_bf16 v[8:11], v[88:91], v[196:199], v[8:11]
	v_mfma_f32_16x16x32_bf16 v[0:3], v[100:103], v[196:199], v[0:3]
	v_mfma_f32_16x16x32_bf16 v[56:59], v[92:95], v[152:155], v[56:59]
	v_mfma_f32_16x16x32_bf16 v[48:51], v[108:111], v[152:155], v[48:51]
	v_mfma_f32_16x16x32_bf16 v[40:43], v[92:95], v[172:175], v[40:43]
	v_mfma_f32_16x16x32_bf16 v[32:35], v[108:111], v[172:175], v[32:35]
	v_mfma_f32_16x16x32_bf16 v[24:27], v[92:95], v[180:183], v[24:27]
	v_mfma_f32_16x16x32_bf16 v[16:19], v[108:111], v[180:183], v[16:19]
	v_mfma_f32_16x16x32_bf16 v[8:11], v[92:95], v[200:203], v[8:11]
	v_mfma_f32_16x16x32_bf16 v[0:3], v[108:111], v[200:203], v[0:3]
	s_setprio 0
	s_barrier
	v_add_u32_e32 v80, s37, v217
	v_add_u32_e32 v108, s26, v217
	s_mov_b32 m0, s15
	v_lshl_add_u64 v[222:223], s[82:83], 0, v[190:191]
	global_load_lds_dwordx4 v[222:223], off
	v_lshl_add_u64 v[222:223], s[82:83], 0, v[186:187]
	s_mov_b32 m0, s18
	s_nop 0
	global_load_lds_dwordx4 v[222:223], off
	ds_read_b128 v[64:67], v80
	ds_read_b128 v[68:71], v80 offset:1024
	ds_read_b128 v[72:75], v80 offset:2048
	ds_read_b128 v[80:83], v80 offset:3072
	ds_read_b128 v[88:91], v108
	ds_read_b128 v[92:95], v108 offset:1024
	ds_read_b128 v[100:103], v108 offset:2048
	ds_read_b128 v[108:111], v108 offset:3072
	ds_read_b128 v[148:151], v220 offset:32768
	ds_read_b128 v[152:155], v220 offset:33792
	ds_read_b128 v[164:167], v220 offset:34816
	ds_read_b128 v[172:175], v220 offset:35840
	ds_read_b128 v[176:179], v220 offset:36864
	ds_read_b128 v[180:183], v220 offset:37888
	ds_read_b128 v[196:199], v220 offset:38912
	ds_read_b128 v[200:203], v220 offset:39936
	s_waitcnt vmcnt(8) lgkmcnt(0)
	s_barrier
	s_setprio 1
	v_mfma_f32_16x16x32_bf16 v[168:171], v[64:67], v[148:151], v[168:171]
	v_mfma_f32_16x16x32_bf16 v[156:159], v[72:75], v[148:151], v[156:159]
	v_mfma_f32_16x16x32_bf16 v[144:147], v[64:67], v[164:167], v[144:147]
	v_mfma_f32_16x16x32_bf16 v[136:139], v[72:75], v[164:167], v[136:139]
	v_mfma_f32_16x16x32_bf16 v[124:127], v[64:67], v[176:179], v[124:127]
	v_mfma_f32_16x16x32_bf16 v[116:119], v[72:75], v[176:179], v[116:119]
	v_mfma_f32_16x16x32_bf16 v[104:107], v[64:67], v[196:199], v[104:107]
	v_mfma_f32_16x16x32_bf16 v[84:87], v[72:75], v[196:199], v[84:87]
	v_mfma_f32_16x16x32_bf16 v[168:171], v[68:71], v[152:155], v[168:171]
	v_mfma_f32_16x16x32_bf16 v[156:159], v[80:83], v[152:155], v[156:159]
	v_mfma_f32_16x16x32_bf16 v[144:147], v[68:71], v[172:175], v[144:147]
	v_mfma_f32_16x16x32_bf16 v[136:139], v[80:83], v[172:175], v[136:139]
	v_mfma_f32_16x16x32_bf16 v[124:127], v[68:71], v[180:183], v[124:127]
	v_mfma_f32_16x16x32_bf16 v[116:119], v[80:83], v[180:183], v[116:119]
	v_mfma_f32_16x16x32_bf16 v[104:107], v[68:71], v[200:203], v[104:107]
	v_mfma_f32_16x16x32_bf16 v[84:87], v[80:83], v[200:203], v[84:87]
	s_setprio 0
	s_setprio 1
	v_mfma_f32_16x16x32_bf16 v[160:163], v[88:91], v[148:151], v[160:163]
	v_mfma_f32_16x16x32_bf16 v[128:131], v[100:103], v[148:151], v[128:131]
	v_mfma_f32_16x16x32_bf16 v[160:163], v[92:95], v[152:155], v[160:163]
	v_mfma_f32_16x16x32_bf16 v[152:155], v[108:111], v[152:155], v[128:131]
	v_mfma_f32_16x16x32_bf16 v[128:131], v[88:91], v[164:167], v[140:143]
	v_mfma_f32_16x16x32_bf16 v[140:143], v[92:95], v[172:175], v[128:131]
	v_mfma_f32_16x16x32_bf16 v[128:131], v[100:103], v[164:167], v[132:135]
	v_mfma_f32_16x16x32_bf16 v[120:123], v[88:91], v[176:179], v[120:123]
	v_mfma_f32_16x16x32_bf16 v[112:115], v[100:103], v[176:179], v[112:115]
	v_mfma_f32_16x16x32_bf16 v[96:99], v[88:91], v[196:199], v[96:99]
	v_mfma_f32_16x16x32_bf16 v[76:79], v[100:103], v[196:199], v[76:79]
	v_mfma_f32_16x16x32_bf16 v[132:135], v[108:111], v[172:175], v[128:131]
	v_mfma_f32_16x16x32_bf16 v[120:123], v[92:95], v[180:183], v[120:123]
	v_mfma_f32_16x16x32_bf16 v[112:115], v[108:111], v[180:183], v[112:115]
	v_mfma_f32_16x16x32_bf16 v[96:99], v[92:95], v[200:203], v[96:99]
	v_mfma_f32_16x16x32_bf16 v[76:79], v[108:111], v[200:203], v[76:79]
	s_setprio 0
	s_barrier
; #define PG8_STAGE(bufoff, gbase, voff) do { _Pragma("unroll") for (int _i = 0; _i < 2; ++_i) \
;         __builtin_amdgcn_global_load_lds((const unsigned*)((const char*)(gbase) + (voff)[_i]), (LAS unsigned*)(lds + (bufoff) + ldsw + _i * 8192), 16, 0, 0); } while (0)
; #define PG8_LDA(dst, b, h) do { _Pragma("unroll") for (int m = 0; m < 4; ++m) _Pragma("unroll") for (int k = 0; k < 2; ++k) dst[m][k] = *(const LAS bf16x8*)(lds + PG8_SA(b, h) + aoff + m * 2048 + k * 1024); } while (0)
; #define PG8_MMA(ai, bj, At, Bt) do { __builtin_amdgcn_s_setprio(1); _Pragma("unroll") for (int m = 0; m < 4; ++m) _Pragma("unroll") for (int n = 0; n < 2; ++n) _Pragma("unroll") for (int k = 0; k < 2; ++k) \
;         acc[ai][bj][m][n] = __builtin_amdgcn_mfma_f32_16x16x32_bf16(Bt[n][k], At[m][k], acc[ai][bj][m][n], 0, 0, 0); __builtin_amdgcn_s_setprio(0); } while (0)
; #define PG8_WAIT_V(n) asm volatile("s_waitcnt vmcnt(" #n ")" ::: "memory")
; #define PG8_WAIT_L(n) asm volatile("s_waitcnt lgkmcnt(" #n ")" ::: "memory")
; #define PG8_BAR __builtin_amdgcn_s_barrier()
; #define PG8_SCHED __builtin_amdgcn_sched_barrier(0)
; template <class Epi, class Sched>
; __device__ __forceinline__ void gemm_phase(LAS unsigned char* lds, const Gemm g, const Sched& S, const Epi& E) {
;     ...
;             PG8_LDA(At, 1, 1); PG8_STAGE(PG8_SB(1, 0), b3, voffB); PG8_STAGE(PG8_SB(1, 1), b3 + hstepB, voffB); PG8_STAGE(PG8_SA(1, 0), a3, voffA);
;             PG8_WAIT_V(8); PG8_WAIT_L(0); PG8_BAR; PG8_MMA(1, 0, At, B0); PG8_MMA(1, 1, At, B1); PG8_BAR; PG8_SCHED;
;         }
;         if (wr == 0) PG8_BAR;
	s_mov_b32 m0, s49
	v_lshl_add_u64 v[204:205], v[204:205], 0, s[58:59]
	global_load_lds_dwordx4 v[204:205], off
	v_lshl_add_u64 v[204:205], v[206:207], 0, s[58:59]
	s_mov_b32 m0, s45
	s_nop 0
	global_load_lds_dwordx4 v[204:205], off
	v_lshl_add_u64 v[204:205], s[80:81], 0, v[188:189]
	s_mov_b32 m0, s48
	s_nop 0
	global_load_lds_dwordx4 v[204:205], off
	v_lshl_add_u64 v[204:205], s[80:81], 0, v[184:185]
	s_mov_b32 m0, s35
	s_nop 0
	global_load_lds_dwordx4 v[204:205], off
	v_lshl_add_u64 v[204:205], v[208:209], 0, s[58:59]
	s_mov_b32 m0, s24
	s_nop 0
	global_load_lds_dwordx4 v[204:205], off
	v_lshl_add_u64 v[204:205], v[210:211], 0, s[58:59]
	s_mov_b32 m0, s25
	s_nop 0
	global_load_lds_dwordx4 v[204:205], off
	ds_read_b128 v[128:131], v220 offset:49152
	ds_read_b128 v[148:151], v220 offset:50176
	ds_read_b128 v[164:167], v220 offset:51200
	ds_read_b128 v[172:175], v220 offset:52224
	ds_read_b128 v[176:179], v220 offset:53248
	ds_read_b128 v[180:183], v220 offset:54272
	ds_read_b128 v[196:199], v220 offset:55296
	ds_read_b128 v[200:203], v220 offset:56320
	s_waitcnt vmcnt(8) lgkmcnt(0)
	s_barrier
	s_setprio 1
	v_mfma_f32_16x16x32_bf16 v[60:63], v[64:67], v[128:131], v[60:63]
	v_mfma_f32_16x16x32_bf16 v[52:55], v[72:75], v[128:131], v[52:55]
	v_mfma_f32_16x16x32_bf16 v[44:47], v[64:67], v[164:167], v[44:47]
	v_mfma_f32_16x16x32_bf16 v[36:39], v[72:75], v[164:167], v[36:39]
	v_mfma_f32_16x16x32_bf16 v[28:31], v[64:67], v[176:179], v[28:31]
	v_mfma_f32_16x16x32_bf16 v[20:23], v[72:75], v[176:179], v[20:23]
	v_mfma_f32_16x16x32_bf16 v[12:15], v[64:67], v[196:199], v[12:15]
	v_mfma_f32_16x16x32_bf16 v[4:7], v[72:75], v[196:199], v[4:7]
	v_mfma_f32_16x16x32_bf16 v[60:63], v[68:71], v[148:151], v[60:63]
	v_mfma_f32_16x16x32_bf16 v[52:55], v[80:83], v[148:151], v[52:55]
	v_mfma_f32_16x16x32_bf16 v[44:47], v[68:71], v[172:175], v[44:47]
	v_mfma_f32_16x16x32_bf16 v[36:39], v[80:83], v[172:175], v[36:39]
	v_mfma_f32_16x16x32_bf16 v[28:31], v[68:71], v[180:183], v[28:31]
	v_mfma_f32_16x16x32_bf16 v[20:23], v[80:83], v[180:183], v[20:23]
	v_mfma_f32_16x16x32_bf16 v[12:15], v[68:71], v[200:203], v[12:15]
	v_mfma_f32_16x16x32_bf16 v[4:7], v[80:83], v[200:203], v[4:7]
	s_setprio 0
	s_setprio 1
	v_mfma_f32_16x16x32_bf16 v[56:59], v[88:91], v[128:131], v[56:59]
	v_mfma_f32_16x16x32_bf16 v[48:51], v[100:103], v[128:131], v[48:51]
	v_mfma_f32_16x16x32_bf16 v[40:43], v[88:91], v[164:167], v[40:43]
	v_mfma_f32_16x16x32_bf16 v[32:35], v[100:103], v[164:167], v[32:35]
	v_mfma_f32_16x16x32_bf16 v[24:27], v[88:91], v[176:179], v[24:27]
	v_mfma_f32_16x16x32_bf16 v[16:19], v[100:103], v[176:179], v[16:19]
	v_mfma_f32_16x16x32_bf16 v[8:11], v[88:91], v[196:199], v[8:11]
	v_mfma_f32_16x16x32_bf16 v[0:3], v[100:103], v[196:199], v[0:3]
	v_mfma_f32_16x16x32_bf16 v[56:59], v[92:95], v[148:151], v[56:59]
	v_mfma_f32_16x16x32_bf16 v[48:51], v[108:111], v[148:151], v[48:51]
	v_mfma_f32_16x16x32_bf16 v[40:43], v[92:95], v[172:175], v[40:43]
	v_mfma_f32_16x16x32_bf16 v[32:35], v[108:111], v[172:175], v[32:35]
	v_mfma_f32_16x16x32_bf16 v[24:27], v[92:95], v[180:183], v[24:27]
	v_mfma_f32_16x16x32_bf16 v[16:19], v[108:111], v[180:183], v[16:19]
	v_mfma_f32_16x16x32_bf16 v[8:11], v[92:95], v[200:203], v[8:11]
	v_mfma_f32_16x16x32_bf16 v[0:3], v[108:111], v[200:203], v[0:3]
	s_setprio 0
	s_barrier
	s_andn2_b64 vcc, exec, s[0:1]
	s_mov_b64 s[80:81], -1
	s_mov_b64 s[0:1], 0
	s_mov_b64 s[82:83], 0x100
	s_cbranch_vccz .LBB0_553
	s_and_b64 vcc, exec, s[60:61]
	s_cbranch_vccz .LBB0_556
	s_barrier

; #define PG8_STAGE(bufoff, gbase, voff) do { _Pragma("unroll") for (int _i = 0; _i < 2; ++_i) \
;         __builtin_amdgcn_global_load_lds((const unsigned*)((const char*)(gbase) + (voff)[_i]), (LAS unsigned*)(lds + (bufoff) + ldsw + _i * 8192), 16, 0, 0); } while (0)
; #define PG8_LDA(dst, b, h) do { _Pragma("unroll") for (int m = 0; m < 4; ++m) _Pragma("unroll") for (int k = 0; k < 2; ++k) dst[m][k] = *(const LAS bf16x8*)(lds + PG8_SA(b, h) + aoff + m * 2048 + k * 1024); } while (0)
; #define PG8_LDB(dst, b, h) do { _Pragma("unroll") for (int n = 0; n < 2; ++n) _Pragma("unroll") for (int k = 0; k < 2; ++k) dst[n][k] = *(const LAS bf16x8*)(lds + PG8_SB(b, h) + boff + n * 2048 + k * 1024); } while (0)
; #define PG8_MMA(ai, bj, At, Bt) do { __builtin_amdgcn_s_setprio(1); _Pragma("unroll") for (int m = 0; m < 4; ++m) _Pragma("unroll") for (int n = 0; n < 2; ++n) _Pragma("unroll") for (int k = 0; k < 2; ++k) \
;         acc[ai][bj][m][n] = __builtin_amdgcn_mfma_f32_16x16x32_bf16(Bt[n][k], At[m][k], acc[ai][bj][m][n], 0, 0, 0); __builtin_amdgcn_s_setprio(0); } while (0)
; #define PG8_WAIT_V(n) asm volatile("s_waitcnt vmcnt(" #n ")" ::: "memory")
; #define PG8_WAIT_L(n) asm volatile("s_waitcnt lgkmcnt(" #n ")" ::: "memory")
; #define PG8_BAR __builtin_amdgcn_s_barrier()
; #define PG8_SCHED __builtin_amdgcn_sched_barrier(0)
; template <class Epi, class Sched>
; __device__ __forceinline__ void gemm_phase(LAS unsigned char* lds, const Gemm g, const Sched& S, const Epi& E) {
;     ...
;             const bool last = (t == nt - 2);
;             const char* a1 = cA + (size_t)(t + 1) * kstep;
;             const char* a2 = last ? nA : cA + (size_t)(t + 2) * kstep; const char* b2 = last ? nB : cB + (size_t)(t + 2) * kstep;
;             const char* a3 = a2 + kstep; const char* b3 = b2 + kstep;
;             PG8_LDB(B0, 0, 0); PG8_LDB(B1, 0, 1); PG8_SCHED; PG8_LDA(At, 0, 0); PG8_STAGE(PG8_SA(1, 1), a1 + hstepA, voffA);
;             PG8_WAIT_V(8); PG8_WAIT_L(0); PG8_BAR; PG8_MMA(0, 0, At, B0); PG8_MMA(0, 1, At, B1); PG8_BAR; PG8_SCHED;
;             PG8_LDA(At, 0, 1); PG8_STAGE(PG8_SB(0, 0), b2, voffB); PG8_STAGE(PG8_SB(0, 1), b2 + hstepB, voffB); PG8_STAGE(PG8_SA(0, 0), a2, voffA);
.LBB0_752:
	v_add_u32_e32 v1, s33, v166
	ds_read_b128 v[152:155], v1
	ds_read_b128 v[156:159], v1 offset:1024
	ds_read_b128 v[160:163], v1 offset:2048
	ds_read_b128 v[168:171], v1 offset:3072
	v_add_u32_e32 v1, s36, v166
	s_add_u32 s64, s60, s62
	ds_read_b128 v[172:175], v1
	ds_read_b128 v[176:179], v1 offset:1024
	ds_read_b128 v[180:183], v1 offset:2048
	ds_read_b128 v[184:187], v1 offset:3072
	s_addc_u32 s65, s61, s63
	s_add_u32 s64, s64, 0x100
	s_addc_u32 s65, s65, 0
	s_add_u32 s75, s72, s62
	s_addc_u32 s76, s73, s63
	s_cmpk_eq_i32 s62, 0x1700
	s_cselect_b32 s67, s1, s65
	s_cselect_b32 s66, s0, s64
	s_cselect_b32 s65, s59, s76
	s_cselect_b32 s64, s58, s75
	v_lshl_add_u64 v[2:3], v[148:149], 0, s[62:63]
	s_add_i32 m0, s13, 0xc000
	ds_read_b128 v[188:191], v167
	ds_read_b128 v[192:195], v167 offset:1024
	ds_read_b128 v[196:199], v167 offset:2048
	ds_read_b128 v[200:203], v167 offset:3072
	ds_read_b128 v[204:207], v167 offset:4096
	ds_read_b128 v[208:211], v167 offset:5120
	ds_read_b128 v[216:219], v167 offset:6144
	ds_read_b128 v[220:223], v167 offset:7168
	global_load_lds_dwordx4 v[2:3], off
	v_lshl_add_u64 v[2:3], v[150:151], 0, s[62:63]
	s_add_i32 m0, s13, 0xe000
	s_nop 0
	global_load_lds_dwordx4 v[2:3], off
	s_waitcnt vmcnt(8) lgkmcnt(0)
	s_barrier
	s_setprio 1
	v_mfma_f32_16x16x32_bf16 v[128:131], v[152:155], v[188:191], v[128:131]
	v_mfma_f32_16x16x32_bf16 v[124:127], v[160:163], v[188:191], v[124:127]
	v_mfma_f32_16x16x32_bf16 v[112:115], v[152:155], v[196:199], v[112:115]
	v_mfma_f32_16x16x32_bf16 v[108:111], v[160:163], v[196:199], v[108:111]
	v_mfma_f32_16x16x32_bf16 v[96:99], v[152:155], v[204:207], v[96:99]
	v_mfma_f32_16x16x32_bf16 v[92:95], v[160:163], v[204:207], v[92:95]
	v_mfma_f32_16x16x32_bf16 v[80:83], v[152:155], v[216:219], v[80:83]
	v_mfma_f32_16x16x32_bf16 v[76:79], v[160:163], v[216:219], v[76:79]
	v_mfma_f32_16x16x32_bf16 v[128:131], v[156:159], v[192:195], v[128:131]
	v_mfma_f32_16x16x32_bf16 v[124:127], v[168:171], v[192:195], v[124:127]
	v_mfma_f32_16x16x32_bf16 v[112:115], v[156:159], v[200:203], v[112:115]
	v_mfma_f32_16x16x32_bf16 v[108:111], v[168:171], v[200:203], v[108:111]
	v_mfma_f32_16x16x32_bf16 v[96:99], v[156:159], v[208:211], v[96:99]
	v_mfma_f32_16x16x32_bf16 v[92:95], v[168:171], v[208:211], v[92:95]
	v_mfma_f32_16x16x32_bf16 v[80:83], v[156:159], v[220:223], v[80:83]
	v_mfma_f32_16x16x32_bf16 v[76:79], v[168:171], v[220:223], v[76:79]
	s_setprio 0
	s_setprio 1
	v_mfma_f32_16x16x32_bf16 v[120:123], v[172:175], v[188:191], v[120:123]
	v_mfma_f32_16x16x32_bf16 v[116:119], v[180:183], v[188:191], v[116:119]
	v_mfma_f32_16x16x32_bf16 v[104:107], v[172:175], v[196:199], v[104:107]
	v_mfma_f32_16x16x32_bf16 v[100:103], v[180:183], v[196:199], v[100:103]
	v_mfma_f32_16x16x32_bf16 v[88:91], v[172:175], v[204:207], v[88:91]
	v_mfma_f32_16x16x32_bf16 v[84:87], v[180:183], v[204:207], v[84:87]
	v_mfma_f32_16x16x32_bf16 v[72:75], v[172:175], v[216:219], v[72:75]
	v_mfma_f32_16x16x32_bf16 v[68:71], v[180:183], v[216:219], v[68:71]
	v_mfma_f32_16x16x32_bf16 v[120:123], v[176:179], v[192:195], v[120:123]
	v_mfma_f32_16x16x32_bf16 v[116:119], v[184:187], v[192:195], v[116:119]
	v_mfma_f32_16x16x32_bf16 v[104:107], v[176:179], v[200:203], v[104:107]
	v_mfma_f32_16x16x32_bf16 v[100:103], v[184:187], v[200:203], v[100:103]
	v_mfma_f32_16x16x32_bf16 v[88:91], v[176:179], v[208:211], v[88:91]
	v_mfma_f32_16x16x32_bf16 v[84:87], v[184:187], v[208:211], v[84:87]
	v_mfma_f32_16x16x32_bf16 v[72:75], v[176:179], v[220:223], v[72:75]
	v_mfma_f32_16x16x32_bf16 v[68:71], v[184:187], v[220:223], v[68:71]
	s_setprio 0
	s_barrier
	s_add_i32 s75, s33, s12
	v_lshl_add_u64 v[224:225], s[64:65], 0, v[136:137]
	s_mov_b32 m0, s75
	s_nop 0
	global_load_lds_dwordx4 v[224:225], off
	s_add_i32 m0, s75, 0x2000
	s_add_u32 s76, s64, 0xc0000
	v_lshl_add_u64 v[226:227], s[64:65], 0, v[132:133]
	s_addc_u32 s77, s65, 0
	s_add_i32 s75, s36, s12
	global_load_lds_dwordx4 v[226:227], off
	v_lshl_add_u64 v[2:3], s[76:77], 0, v[136:137]
	s_mov_b32 m0, s75
	v_lshl_add_u64 v[228:229], s[66:67], 0, v[138:139]
	global_load_lds_dwordx4 v[2:3], off
	v_lshl_add_u64 v[2:3], s[76:77], 0, v[132:133]
	s_add_i32 m0, s75, 0x2000
	v_lshl_add_u64 v[230:231], s[66:67], 0, v[134:135]
	global_load_lds_dwordx4 v[2:3], off
	s_mov_b32 m0, s13
	s_nop 0
	global_load_lds_dwordx4 v[228:229], off
	s_mov_b32 m0, s14
	s_nop 0
	global_load_lds_dwordx4 v[230:231], off
	ds_read_b128 v[188:191], v167 offset:16384
	ds_read_b128 v[192:195], v167 offset:17408
	ds_read_b128 v[196:199], v167 offset:18432
	ds_read_b128 v[200:203], v167 offset:19456
	ds_read_b128 v[204:207], v167 offset:20480
	ds_read_b128 v[208:211], v167 offset:21504
	ds_read_b128 v[216:219], v167 offset:22528
	ds_read_b128 v[220:223], v167 offset:23552
	s_waitcnt vmcnt(8) lgkmcnt(0)
	s_barrier
; #define PG8_STAGE(bufoff, gbase, voff) do { _Pragma("unroll") for (int _i = 0; _i < 2; ++_i) \
;         __builtin_amdgcn_global_load_lds((const unsigned*)((const char*)(gbase) + (voff)[_i]), (LAS unsigned*)(lds + (bufoff) + ldsw + _i * 8192), 16, 0, 0); } while (0)
; #define PG8_LDA(dst, b, h) do { _Pragma("unroll") for (int m = 0; m < 4; ++m) _Pragma("unroll") for (int k = 0; k < 2; ++k) dst[m][k] = *(const LAS bf16x8*)(lds + PG8_SA(b, h) + aoff + m * 2048 + k * 1024); } while (0)
; #define PG8_LDB(dst, b, h) do { _Pragma("unroll") for (int n = 0; n < 2; ++n) _Pragma("unroll") for (int k = 0; k < 2; ++k) dst[n][k] = *(const LAS bf16x8*)(lds + PG8_SB(b, h) + boff + n * 2048 + k * 1024); } while (0)
; #define PG8_MMA(ai, bj, At, Bt) do { __builtin_amdgcn_s_setprio(1); _Pragma("unroll") for (int m = 0; m < 4; ++m) _Pragma("unroll") for (int n = 0; n < 2; ++n) _Pragma("unroll") for (int k = 0; k < 2; ++k) \
;         acc[ai][bj][m][n] = __builtin_amdgcn_mfma_f32_16x16x32_bf16(Bt[n][k], At[m][k], acc[ai][bj][m][n], 0, 0, 0); __builtin_amdgcn_s_setprio(0); } while (0)
; #define PG8_WAIT_V(n) asm volatile("s_waitcnt vmcnt(" #n ")" ::: "memory")
; #define PG8_WAIT_L(n) asm volatile("s_waitcnt lgkmcnt(" #n ")" ::: "memory")
; #define PG8_BAR __builtin_amdgcn_s_barrier()
; #define PG8_SCHED __builtin_amdgcn_sched_barrier(0)
; template <class Epi, class Sched>
; __device__ __forceinline__ void gemm_phase(LAS unsigned char* lds, const Gemm g, const Sched& S, const Epi& E) {
;     ...
;             PG8_WAIT_V(8); PG8_WAIT_L(0); PG8_BAR; PG8_MMA(1, 0, At, B0); PG8_MMA(1, 1, At, B1); PG8_BAR; PG8_SCHED;
;             PG8_LDB(B0, 1, 0); PG8_LDB(B1, 1, 1); PG8_SCHED; PG8_LDA(At, 1, 0); PG8_STAGE(PG8_SA(0, 1), a2 + hstepA, voffA);
;             PG8_WAIT_V(8); PG8_WAIT_L(0); PG8_BAR; PG8_MMA(0, 0, At, B0); PG8_MMA(0, 1, At, B1); PG8_BAR; PG8_SCHED;
	s_setprio 1
	v_mfma_f32_16x16x32_bf16 v[64:67], v[152:155], v[188:191], v[64:67]
	v_mfma_f32_16x16x32_bf16 v[60:63], v[160:163], v[188:191], v[60:63]
	v_mfma_f32_16x16x32_bf16 v[48:51], v[152:155], v[196:199], v[48:51]
	v_mfma_f32_16x16x32_bf16 v[44:47], v[160:163], v[196:199], v[44:47]
	v_mfma_f32_16x16x32_bf16 v[32:35], v[152:155], v[204:207], v[32:35]
	v_mfma_f32_16x16x32_bf16 v[28:31], v[160:163], v[204:207], v[28:31]
	v_mfma_f32_16x16x32_bf16 v[16:19], v[152:155], v[216:219], v[16:19]
	v_mfma_f32_16x16x32_bf16 v[12:15], v[160:163], v[216:219], v[12:15]
	v_mfma_f32_16x16x32_bf16 v[64:67], v[156:159], v[192:195], v[64:67]
	v_mfma_f32_16x16x32_bf16 v[60:63], v[168:171], v[192:195], v[60:63]
	v_mfma_f32_16x16x32_bf16 v[48:51], v[156:159], v[200:203], v[48:51]
	v_mfma_f32_16x16x32_bf16 v[44:47], v[168:171], v[200:203], v[44:47]
	v_mfma_f32_16x16x32_bf16 v[32:35], v[156:159], v[208:211], v[32:35]
	v_mfma_f32_16x16x32_bf16 v[28:31], v[168:171], v[208:211], v[28:31]
	v_mfma_f32_16x16x32_bf16 v[16:19], v[156:159], v[220:223], v[16:19]
	v_mfma_f32_16x16x32_bf16 v[12:15], v[168:171], v[220:223], v[12:15]
	s_setprio 0
	s_setprio 1
	v_mfma_f32_16x16x32_bf16 v[56:59], v[172:175], v[188:191], v[56:59]
	v_mfma_f32_16x16x32_bf16 v[52:55], v[180:183], v[188:191], v[52:55]
	v_mfma_f32_16x16x32_bf16 v[40:43], v[172:175], v[196:199], v[40:43]
	v_mfma_f32_16x16x32_bf16 v[36:39], v[180:183], v[196:199], v[36:39]
	v_mfma_f32_16x16x32_bf16 v[24:27], v[172:175], v[204:207], v[24:27]
	v_mfma_f32_16x16x32_bf16 v[20:23], v[180:183], v[204:207], v[20:23]
	v_mfma_f32_16x16x32_bf16 v[8:11], v[172:175], v[216:219], v[8:11]
	v_mfma_f32_16x16x32_bf16 v[2:5], v[180:183], v[216:219], v[4:7]
	v_mfma_f32_16x16x32_bf16 v[56:59], v[176:179], v[192:195], v[56:59]
	v_mfma_f32_16x16x32_bf16 v[52:55], v[184:187], v[192:195], v[52:55]
	v_mfma_f32_16x16x32_bf16 v[40:43], v[176:179], v[200:203], v[40:43]
	v_mfma_f32_16x16x32_bf16 v[36:39], v[184:187], v[200:203], v[36:39]
	v_mfma_f32_16x16x32_bf16 v[24:27], v[176:179], v[208:211], v[24:27]
	v_mfma_f32_16x16x32_bf16 v[20:23], v[184:187], v[208:211], v[20:23]
	v_mfma_f32_16x16x32_bf16 v[8:11], v[176:179], v[220:223], v[8:11]
	v_mfma_f32_16x16x32_bf16 v[2:5], v[184:187], v[220:223], v[2:5]
	s_setprio 0
	s_barrier
	v_add_u32_e32 v1, s37, v166
	ds_read_b128 v[152:155], v1
	ds_read_b128 v[156:159], v1 offset:1024
	ds_read_b128 v[160:163], v1 offset:2048
	ds_read_b128 v[168:171], v1 offset:3072
	v_add_u32_e32 v1, s26, v166
	ds_read_b128 v[172:175], v1
	ds_read_b128 v[176:179], v1 offset:1024
	ds_read_b128 v[180:183], v1 offset:2048
	ds_read_b128 v[184:187], v1 offset:3072
	s_add_u32 s66, s66, 0xc0000
	s_addc_u32 s67, s67, 0
	s_mov_b32 m0, s15
	v_lshl_add_u64 v[6:7], s[66:67], 0, v[138:139]
	ds_read_b128 v[188:191], v167 offset:32768
	ds_read_b128 v[192:195], v167 offset:33792
	ds_read_b128 v[196:199], v167 offset:34816
	ds_read_b128 v[200:203], v167 offset:35840
	ds_read_b128 v[204:207], v167 offset:36864
	ds_read_b128 v[208:211], v167 offset:37888
	ds_read_b128 v[216:219], v167 offset:38912
	ds_read_b128 v[220:223], v167 offset:39936
	global_load_lds_dwordx4 v[6:7], off
	v_lshl_add_u64 v[6:7], s[66:67], 0, v[134:135]
	s_mov_b32 m0, s19
	s_nop 0
	global_load_lds_dwordx4 v[6:7], off
	s_waitcnt vmcnt(8) lgkmcnt(0)
	s_barrier
	s_setprio 1
	v_mfma_f32_16x16x32_bf16 v[128:131], v[152:155], v[188:191], v[128:131]
	v_mfma_f32_16x16x32_bf16 v[124:127], v[160:163], v[188:191], v[124:127]
	v_mfma_f32_16x16x32_bf16 v[112:115], v[152:155], v[196:199], v[112:115]
	v_mfma_f32_16x16x32_bf16 v[108:111], v[160:163], v[196:199], v[108:111]
	v_mfma_f32_16x16x32_bf16 v[96:99], v[152:155], v[204:207], v[96:99]
	v_mfma_f32_16x16x32_bf16 v[92:95], v[160:163], v[204:207], v[92:95]
	v_mfma_f32_16x16x32_bf16 v[80:83], v[152:155], v[216:219], v[80:83]
	v_mfma_f32_16x16x32_bf16 v[76:79], v[160:163], v[216:219], v[76:79]
	v_mfma_f32_16x16x32_bf16 v[128:131], v[156:159], v[192:195], v[128:131]
	v_mfma_f32_16x16x32_bf16 v[124:127], v[168:171], v[192:195], v[124:127]
	v_mfma_f32_16x16x32_bf16 v[112:115], v[156:159], v[200:203], v[112:115]
	v_mfma_f32_16x16x32_bf16 v[108:111], v[168:171], v[200:203], v[108:111]
	v_mfma_f32_16x16x32_bf16 v[96:99], v[156:159], v[208:211], v[96:99]
	v_mfma_f32_16x16x32_bf16 v[92:95], v[168:171], v[208:211], v[92:95]
	v_mfma_f32_16x16x32_bf16 v[80:83], v[156:159], v[220:223], v[80:83]
	v_mfma_f32_16x16x32_bf16 v[76:79], v[168:171], v[220:223], v[76:79]
	s_setprio 0
	s_setprio 1
	v_mfma_f32_16x16x32_bf16 v[120:123], v[172:175], v[188:191], v[120:123]
	v_mfma_f32_16x16x32_bf16 v[116:119], v[180:183], v[188:191], v[116:119]
	v_mfma_f32_16x16x32_bf16 v[104:107], v[172:175], v[196:199], v[104:107]
	v_mfma_f32_16x16x32_bf16 v[100:103], v[180:183], v[196:199], v[100:103]
	v_mfma_f32_16x16x32_bf16 v[88:91], v[172:175], v[204:207], v[88:91]
	v_mfma_f32_16x16x32_bf16 v[84:87], v[180:183], v[204:207], v[84:87]
	v_mfma_f32_16x16x32_bf16 v[72:75], v[172:175], v[216:219], v[72:75]
	v_mfma_f32_16x16x32_bf16 v[68:71], v[180:183], v[216:219], v[68:71]
	v_mfma_f32_16x16x32_bf16 v[120:123], v[176:179], v[192:195], v[120:123]
	v_mfma_f32_16x16x32_bf16 v[116:119], v[184:187], v[192:195], v[116:119]
	v_mfma_f32_16x16x32_bf16 v[104:107], v[176:179], v[200:203], v[104:107]
	v_mfma_f32_16x16x32_bf16 v[100:103], v[184:187], v[200:203], v[100:103]
	v_mfma_f32_16x16x32_bf16 v[88:91], v[176:179], v[208:211], v[88:91]
	v_mfma_f32_16x16x32_bf16 v[84:87], v[184:187], v[208:211], v[84:87]
	v_mfma_f32_16x16x32_bf16 v[72:75], v[176:179], v[220:223], v[72:75]
	v_mfma_f32_16x16x32_bf16 v[68:71], v[184:187], v[220:223], v[68:71]
	s_setprio 0
	s_barrier
; #define PG8_STAGE(bufoff, gbase, voff) do { _Pragma("unroll") for (int _i = 0; _i < 2; ++_i) \
;         __builtin_amdgcn_global_load_lds((const unsigned*)((const char*)(gbase) + (voff)[_i]), (LAS unsigned*)(lds + (bufoff) + ldsw + _i * 8192), 16, 0, 0); } while (0)
; #define PG8_LDA(dst, b, h) do { _Pragma("unroll") for (int m = 0; m < 4; ++m) _Pragma("unroll") for (int k = 0; k < 2; ++k) dst[m][k] = *(const LAS bf16x8*)(lds + PG8_SA(b, h) + aoff + m * 2048 + k * 1024); } while (0)
; #define PG8_MMA(ai, bj, At, Bt) do { __builtin_amdgcn_s_setprio(1); _Pragma("unroll") for (int m = 0; m < 4; ++m) _Pragma("unroll") for (int n = 0; n < 2; ++n) _Pragma("unroll") for (int k = 0; k < 2; ++k) \
;         acc[ai][bj][m][n] = __builtin_amdgcn_mfma_f32_16x16x32_bf16(Bt[n][k], At[m][k], acc[ai][bj][m][n], 0, 0, 0); __builtin_amdgcn_s_setprio(0); } while (0)
; #define PG8_WAIT_V(n) asm volatile("s_waitcnt vmcnt(" #n ")" ::: "memory")
; #define PG8_WAIT_L(n) asm volatile("s_waitcnt lgkmcnt(" #n ")" ::: "memory")
; #define PG8_BAR __builtin_amdgcn_s_barrier()
; #define PG8_SCHED __builtin_amdgcn_sched_barrier(0)
; template <class Epi, class Sched>
; __device__ __forceinline__ void gemm_phase(LAS unsigned char* lds, const Gemm g, const Sched& S, const Epi& E) {
;     ...
;             PG8_LDA(At, 1, 1); PG8_STAGE(PG8_SB(1, 0), b3, voffB); PG8_STAGE(PG8_SB(1, 1), b3 + hstepB, voffB); PG8_STAGE(PG8_SA(1, 0), a3, voffA);
;             PG8_WAIT_V(8); PG8_WAIT_L(0); PG8_BAR; PG8_MMA(1, 0, At, B0); PG8_MMA(1, 1, At, B1); PG8_BAR; PG8_SCHED;
	s_add_i32 s66, s37, s12
	v_lshl_add_u64 v[6:7], v[224:225], 0, s[42:43]
	s_mov_b32 m0, s66
	s_nop 0
	global_load_lds_dwordx4 v[6:7], off
	s_add_i32 m0, s66, 0x2000
	s_add_u32 s64, s64, 0xc0080
	v_lshl_add_u64 v[6:7], v[226:227], 0, s[42:43]
	s_addc_u32 s65, s65, 0
	s_add_i32 s66, s26, s12
	global_load_lds_dwordx4 v[6:7], off
	v_lshl_add_u64 v[6:7], s[64:65], 0, v[136:137]
	s_mov_b32 m0, s66
	s_nop 0
	global_load_lds_dwordx4 v[6:7], off
	v_lshl_add_u64 v[6:7], s[64:65], 0, v[132:133]
	s_add_i32 m0, s66, 0x2000
	s_nop 0
	global_load_lds_dwordx4 v[6:7], off
	v_lshl_add_u64 v[6:7], v[228:229], 0, s[42:43]
	s_mov_b32 m0, s23
	s_nop 0
	global_load_lds_dwordx4 v[6:7], off
	v_lshl_add_u64 v[6:7], v[230:231], 0, s[42:43]
	s_mov_b32 m0, s24
	s_nop 0
	global_load_lds_dwordx4 v[6:7], off
	ds_read_b128 v[188:191], v167 offset:49152
	ds_read_b128 v[192:195], v167 offset:50176
	ds_read_b128 v[196:199], v167 offset:51200
	ds_read_b128 v[200:203], v167 offset:52224
	ds_read_b128 v[204:207], v167 offset:53248
	ds_read_b128 v[208:211], v167 offset:54272
	ds_read_b128 v[216:219], v167 offset:55296
	ds_read_b128 v[220:223], v167 offset:56320
	s_waitcnt vmcnt(8) lgkmcnt(0)
	s_barrier
	s_setprio 1
	v_mfma_f32_16x16x32_bf16 v[64:67], v[152:155], v[188:191], v[64:67]
	v_mfma_f32_16x16x32_bf16 v[60:63], v[160:163], v[188:191], v[60:63]
	v_mfma_f32_16x16x32_bf16 v[48:51], v[152:155], v[196:199], v[48:51]
	v_mfma_f32_16x16x32_bf16 v[44:47], v[160:163], v[196:199], v[44:47]
	v_mfma_f32_16x16x32_bf16 v[32:35], v[152:155], v[204:207], v[32:35]
	v_mfma_f32_16x16x32_bf16 v[28:31], v[160:163], v[204:207], v[28:31]
	v_mfma_f32_16x16x32_bf16 v[16:19], v[152:155], v[216:219], v[16:19]
	v_mfma_f32_16x16x32_bf16 v[12:15], v[160:163], v[216:219], v[12:15]
	v_mfma_f32_16x16x32_bf16 v[64:67], v[156:159], v[192:195], v[64:67]
	v_mfma_f32_16x16x32_bf16 v[60:63], v[168:171], v[192:195], v[60:63]
	v_mfma_f32_16x16x32_bf16 v[48:51], v[156:159], v[200:203], v[48:51]
	v_mfma_f32_16x16x32_bf16 v[44:47], v[168:171], v[200:203], v[44:47]
	v_mfma_f32_16x16x32_bf16 v[32:35], v[156:159], v[208:211], v[32:35]
	v_mfma_f32_16x16x32_bf16 v[28:31], v[168:171], v[208:211], v[28:31]
	v_mfma_f32_16x16x32_bf16 v[16:19], v[156:159], v[220:223], v[16:19]
	v_mfma_f32_16x16x32_bf16 v[12:15], v[168:171], v[220:223], v[12:15]
	s_setprio 0
	s_setprio 1
	v_mfma_f32_16x16x32_bf16 v[56:59], v[172:175], v[188:191], v[56:59]
	v_mfma_f32_16x16x32_bf16 v[52:55], v[180:183], v[188:191], v[52:55]
	v_mfma_f32_16x16x32_bf16 v[40:43], v[172:175], v[196:199], v[40:43]
	v_mfma_f32_16x16x32_bf16 v[36:39], v[180:183], v[196:199], v[36:39]
	v_mfma_f32_16x16x32_bf16 v[24:27], v[172:175], v[204:207], v[24:27]
	v_mfma_f32_16x16x32_bf16 v[20:23], v[180:183], v[204:207], v[20:23]
	v_mfma_f32_16x16x32_bf16 v[6:9], v[172:175], v[216:219], v[8:11]
	v_mfma_f32_16x16x32_bf16 v[2:5], v[180:183], v[216:219], v[2:5]
	v_mfma_f32_16x16x32_bf16 v[56:59], v[176:179], v[192:195], v[56:59]
	v_mfma_f32_16x16x32_bf16 v[52:55], v[184:187], v[192:195], v[52:55]
	v_mfma_f32_16x16x32_bf16 v[40:43], v[176:179], v[200:203], v[40:43]
	v_mfma_f32_16x16x32_bf16 v[36:39], v[184:187], v[200:203], v[36:39]
	v_mfma_f32_16x16x32_bf16 v[24:27], v[176:179], v[208:211], v[24:27]
	v_mfma_f32_16x16x32_bf16 v[20:23], v[184:187], v[208:211], v[20:23]
	v_mfma_f32_16x16x32_bf16 v[8:11], v[176:179], v[220:223], v[6:9]
	v_mfma_f32_16x16x32_bf16 v[4:7], v[184:187], v[220:223], v[2:5]
	s_setprio 0
	s_barrier
	s_add_i32 s74, s74, 2
	s_add_u32 s62, s62, 0x100
	s_addc_u32 s63, s63, 0
	s_cmp_gt_u32 s74, 45
	s_cbranch_scc1 .LBB0_755

; #define PG8_STAGE(bufoff, gbase, voff) do { _Pragma("unroll") for (int _i = 0; _i < 2; ++_i) \
;         __builtin_amdgcn_global_load_lds((const unsigned*)((const char*)(gbase) + (voff)[_i]), (LAS unsigned*)(lds + (bufoff) + ldsw + _i * 8192), 16, 0, 0); } while (0)
; #define PG8_LDA(dst, b, h) do { _Pragma("unroll") for (int m = 0; m < 4; ++m) _Pragma("unroll") for (int k = 0; k < 2; ++k) dst[m][k] = *(const LAS bf16x8*)(lds + PG8_SA(b, h) + aoff + m * 2048 + k * 1024); } while (0)
; #define PG8_LDB(dst, b, h) do { _Pragma("unroll") for (int n = 0; n < 2; ++n) _Pragma("unroll") for (int k = 0; k < 2; ++k) dst[n][k] = *(const LAS bf16x8*)(lds + PG8_SB(b, h) + boff + n * 2048 + k * 1024); } while (0)
; #define PG8_MMA(ai, bj, At, Bt) do { __builtin_amdgcn_s_setprio(1); _Pragma("unroll") for (int m = 0; m < 4; ++m) _Pragma("unroll") for (int n = 0; n < 2; ++n) _Pragma("unroll") for (int k = 0; k < 2; ++k) \
;         acc[ai][bj][m][n] = __builtin_amdgcn_mfma_f32_16x16x32_bf16(Bt[n][k], At[m][k], acc[ai][bj][m][n], 0, 0, 0); __builtin_amdgcn_s_setprio(0); } while (0)
; #define PG8_WAIT_V(n) asm volatile("s_waitcnt vmcnt(" #n ")" ::: "memory")
; #define PG8_WAIT_L(n) asm volatile("s_waitcnt lgkmcnt(" #n ")" ::: "memory")
; #define PG8_BAR __builtin_amdgcn_s_barrier()
; #define PG8_SCHED __builtin_amdgcn_sched_barrier(0)
; template <class Epi, class Sched>
; __device__ __forceinline__ void gemm_phase(LAS unsigned char* lds, const Gemm g, const Sched& S, const Epi& E) {
;     ...
;             const bool last = (t == nt - 2);
;             const char* a1 = cA + (size_t)(t + 1) * kstep;
;             const char* a2 = last ? nA : cA + (size_t)(t + 2) * kstep; const char* b2 = last ? nB : cB + (size_t)(t + 2) * kstep;
;             const char* a3 = a2 + kstep; const char* b3 = b2 + kstep;
;             PG8_LDB(B0, 0, 0); PG8_LDB(B1, 0, 1); PG8_SCHED; PG8_LDA(At, 0, 0); PG8_STAGE(PG8_SA(1, 1), a1 + hstepA, voffA);
;             PG8_WAIT_V(8); PG8_WAIT_L(0); PG8_BAR; PG8_MMA(0, 0, At, B0); PG8_MMA(0, 1, At, B1); PG8_BAR; PG8_SCHED;
;             PG8_LDA(At, 0, 1); PG8_STAGE(PG8_SB(0, 0), b2, voffB); PG8_STAGE(PG8_SB(0, 1), b2 + hstepB, voffB); PG8_STAGE(PG8_SA(0, 0), a2, voffA);
.LBB0_829:
	s_add_u32 s39, s60, 0xfff80080
	s_addc_u32 s43, s61, -1
	s_cmp_eq_u32 s35, 28
	s_cselect_b32 s65, s12, s43
	s_cselect_b32 s64, s13, s39
	s_cselect_b32 s63, s29, s34
	s_cselect_b32 s62, s30, s31
	v_lshl_add_u64 v[152:153], s[60:61], 0, v[144:145]
	s_add_i32 m0, s18, 0xc000
	s_nop 0
	global_load_lds_dwordx4 v[152:153], off
	v_lshl_add_u64 v[152:153], s[60:61], 0, v[146:147]
	s_add_i32 m0, s18, 0xe000
	s_nop 0
	global_load_lds_dwordx4 v[152:153], off
	ds_read_b128 v[128:131], v167
	ds_read_b128 v[132:135], v167 offset:1024
	ds_read_b128 v[170:173], v167 offset:2048
	ds_read_b128 v[176:179], v167 offset:3072
	ds_read_b128 v[180:183], v169
	ds_read_b128 v[184:187], v169 offset:1024
	ds_read_b128 v[188:191], v169 offset:2048
	ds_read_b128 v[192:195], v169 offset:3072
	ds_read_b128 v[196:199], v175
	ds_read_b128 v[200:203], v175 offset:1024
	ds_read_b128 v[204:207], v175 offset:2048
	ds_read_b128 v[208:211], v175 offset:3072
	ds_read_b128 v[216:219], v175 offset:4096
	ds_read_b128 v[220:223], v175 offset:5120
	ds_read_b128 v[224:227], v175 offset:6144
	ds_read_b128 v[228:231], v175 offset:7168
	s_waitcnt vmcnt(8) lgkmcnt(0)
	s_barrier
	s_setprio 1
	v_mfma_f32_16x16x32_bf16 v[124:127], v[128:131], v[196:199], v[124:127]
	v_mfma_f32_16x16x32_bf16 v[120:123], v[170:173], v[196:199], v[120:123]
	v_mfma_f32_16x16x32_bf16 v[108:111], v[128:131], v[204:207], v[108:111]
	v_mfma_f32_16x16x32_bf16 v[104:107], v[170:173], v[204:207], v[104:107]
	v_mfma_f32_16x16x32_bf16 v[92:95], v[128:131], v[216:219], v[92:95]
	v_mfma_f32_16x16x32_bf16 v[88:91], v[170:173], v[216:219], v[88:91]
	v_mfma_f32_16x16x32_bf16 v[76:79], v[128:131], v[224:227], v[76:79]
	v_mfma_f32_16x16x32_bf16 v[72:75], v[170:173], v[224:227], v[72:75]
	v_mfma_f32_16x16x32_bf16 v[124:127], v[132:135], v[200:203], v[124:127]
	v_mfma_f32_16x16x32_bf16 v[120:123], v[176:179], v[200:203], v[120:123]
	v_mfma_f32_16x16x32_bf16 v[108:111], v[132:135], v[208:211], v[108:111]
	v_mfma_f32_16x16x32_bf16 v[104:107], v[176:179], v[208:211], v[104:107]
	v_mfma_f32_16x16x32_bf16 v[92:95], v[132:135], v[220:223], v[92:95]
	v_mfma_f32_16x16x32_bf16 v[88:91], v[176:179], v[220:223], v[88:91]
	v_mfma_f32_16x16x32_bf16 v[76:79], v[132:135], v[228:231], v[76:79]
	v_mfma_f32_16x16x32_bf16 v[72:75], v[176:179], v[228:231], v[72:75]
	s_setprio 0
	s_setprio 1
	v_mfma_f32_16x16x32_bf16 v[116:119], v[180:183], v[196:199], v[116:119]
	v_mfma_f32_16x16x32_bf16 v[112:115], v[188:191], v[196:199], v[112:115]
	v_mfma_f32_16x16x32_bf16 v[100:103], v[180:183], v[204:207], v[100:103]
	v_mfma_f32_16x16x32_bf16 v[96:99], v[188:191], v[204:207], v[96:99]
	v_mfma_f32_16x16x32_bf16 v[84:87], v[180:183], v[216:219], v[84:87]
	v_mfma_f32_16x16x32_bf16 v[80:83], v[188:191], v[216:219], v[80:83]
	v_mfma_f32_16x16x32_bf16 v[68:71], v[180:183], v[224:227], v[68:71]
	v_mfma_f32_16x16x32_bf16 v[64:67], v[188:191], v[224:227], v[64:67]
	v_mfma_f32_16x16x32_bf16 v[116:119], v[184:187], v[200:203], v[116:119]
	v_mfma_f32_16x16x32_bf16 v[112:115], v[192:195], v[200:203], v[112:115]
	v_mfma_f32_16x16x32_bf16 v[100:103], v[184:187], v[208:211], v[100:103]
	v_mfma_f32_16x16x32_bf16 v[96:99], v[192:195], v[208:211], v[96:99]
	v_mfma_f32_16x16x32_bf16 v[84:87], v[184:187], v[220:223], v[84:87]
	v_mfma_f32_16x16x32_bf16 v[80:83], v[192:195], v[220:223], v[80:83]
	v_mfma_f32_16x16x32_bf16 v[68:71], v[184:187], v[228:231], v[68:71]
	v_mfma_f32_16x16x32_bf16 v[64:67], v[192:195], v[228:231], v[64:67]
	s_setprio 0
	s_barrier
	s_add_i32 s39, s33, s15
	v_lshl_add_u64 v[152:153], s[62:63], 0, v[138:139]
	s_mov_b32 m0, s39
	s_nop 0
	global_load_lds_dwordx4 v[152:153], off
	s_add_i32 m0, s39, 0x2000
	s_add_u32 s48, s62, 0x80000
	v_lshl_add_u64 v[156:157], s[62:63], 0, v[142:143]
	s_addc_u32 s49, s63, 0
	s_add_i32 s39, s36, s15
	global_load_lds_dwordx4 v[156:157], off
	v_lshl_add_u64 v[160:161], s[48:49], 0, v[138:139]
	s_mov_b32 m0, s39
	v_lshl_add_u64 v[232:233], s[64:65], 0, v[140:141]
	global_load_lds_dwordx4 v[160:161], off
	v_lshl_add_u64 v[160:161], s[48:49], 0, v[142:143]
	s_add_i32 m0, s39, 0x2000
	s_nop 0
	global_load_lds_dwordx4 v[160:161], off
	v_lshl_add_u64 v[160:161], s[64:65], 0, v[136:137]
	s_mov_b32 m0, s18
	s_nop 0
	global_load_lds_dwordx4 v[160:161], off
	s_mov_b32 m0, s19
	s_nop 0
	global_load_lds_dwordx4 v[232:233], off
	ds_read_b128 v[196:199], v175 offset:16384
	ds_read_b128 v[200:203], v175 offset:17408
	ds_read_b128 v[204:207], v175 offset:18432
	ds_read_b128 v[208:211], v175 offset:19456
	ds_read_b128 v[216:219], v175 offset:20480
	ds_read_b128 v[220:223], v175 offset:21504
	ds_read_b128 v[224:227], v175 offset:22528
	ds_read_b128 v[228:231], v175 offset:23552
	s_waitcnt vmcnt(8) lgkmcnt(0)
	s_barrier
; #define PG8_STAGE(bufoff, gbase, voff) do { _Pragma("unroll") for (int _i = 0; _i < 2; ++_i) \
;         __builtin_amdgcn_global_load_lds((const unsigned*)((const char*)(gbase) + (voff)[_i]), (LAS unsigned*)(lds + (bufoff) + ldsw + _i * 8192), 16, 0, 0); } while (0)
; #define PG8_LDA(dst, b, h) do { _Pragma("unroll") for (int m = 0; m < 4; ++m) _Pragma("unroll") for (int k = 0; k < 2; ++k) dst[m][k] = *(const LAS bf16x8*)(lds + PG8_SA(b, h) + aoff + m * 2048 + k * 1024); } while (0)
; #define PG8_LDB(dst, b, h) do { _Pragma("unroll") for (int n = 0; n < 2; ++n) _Pragma("unroll") for (int k = 0; k < 2; ++k) dst[n][k] = *(const LAS bf16x8*)(lds + PG8_SB(b, h) + boff + n * 2048 + k * 1024); } while (0)
; #define PG8_MMA(ai, bj, At, Bt) do { __builtin_amdgcn_s_setprio(1); _Pragma("unroll") for (int m = 0; m < 4; ++m) _Pragma("unroll") for (int n = 0; n < 2; ++n) _Pragma("unroll") for (int k = 0; k < 2; ++k) \
;         acc[ai][bj][m][n] = __builtin_amdgcn_mfma_f32_16x16x32_bf16(Bt[n][k], At[m][k], acc[ai][bj][m][n], 0, 0, 0); __builtin_amdgcn_s_setprio(0); } while (0)
; #define PG8_WAIT_V(n) asm volatile("s_waitcnt vmcnt(" #n ")" ::: "memory")
; #define PG8_WAIT_L(n) asm volatile("s_waitcnt lgkmcnt(" #n ")" ::: "memory")
; #define PG8_BAR __builtin_amdgcn_s_barrier()
; #define PG8_SCHED __builtin_amdgcn_sched_barrier(0)
; template <class Epi, class Sched>
; __device__ __forceinline__ void gemm_phase(LAS unsigned char* lds, const Gemm g, const Sched& S, const Epi& E) {
;     ...
;             PG8_WAIT_V(8); PG8_WAIT_L(0); PG8_BAR; PG8_MMA(1, 0, At, B0); PG8_MMA(1, 1, At, B1); PG8_BAR; PG8_SCHED;
;             PG8_LDB(B0, 1, 0); PG8_LDB(B1, 1, 1); PG8_SCHED; PG8_LDA(At, 1, 0); PG8_STAGE(PG8_SA(0, 1), a2 + hstepA, voffA);
;             PG8_WAIT_V(8); PG8_WAIT_L(0); PG8_BAR; PG8_MMA(0, 0, At, B0); PG8_MMA(0, 1, At, B1); PG8_BAR; PG8_SCHED;
	s_setprio 1
	v_mfma_f32_16x16x32_bf16 v[60:63], v[128:131], v[196:199], v[60:63]
	v_mfma_f32_16x16x32_bf16 v[56:59], v[170:173], v[196:199], v[56:59]
	v_mfma_f32_16x16x32_bf16 v[44:47], v[128:131], v[204:207], v[44:47]
	v_mfma_f32_16x16x32_bf16 v[40:43], v[170:173], v[204:207], v[40:43]
	v_mfma_f32_16x16x32_bf16 v[28:31], v[128:131], v[216:219], v[28:31]
	v_mfma_f32_16x16x32_bf16 v[24:27], v[170:173], v[216:219], v[24:27]
	v_mfma_f32_16x16x32_bf16 v[12:15], v[128:131], v[224:227], v[12:15]
	v_mfma_f32_16x16x32_bf16 v[8:11], v[170:173], v[224:227], v[8:11]
	v_mfma_f32_16x16x32_bf16 v[60:63], v[132:135], v[200:203], v[60:63]
	v_mfma_f32_16x16x32_bf16 v[56:59], v[176:179], v[200:203], v[56:59]
	v_mfma_f32_16x16x32_bf16 v[44:47], v[132:135], v[208:211], v[44:47]
	v_mfma_f32_16x16x32_bf16 v[40:43], v[176:179], v[208:211], v[40:43]
	v_mfma_f32_16x16x32_bf16 v[28:31], v[132:135], v[220:223], v[28:31]
	v_mfma_f32_16x16x32_bf16 v[24:27], v[176:179], v[220:223], v[24:27]
	v_mfma_f32_16x16x32_bf16 v[12:15], v[132:135], v[228:231], v[12:15]
	v_mfma_f32_16x16x32_bf16 v[8:11], v[176:179], v[228:231], v[8:11]
	s_setprio 0
	s_setprio 1
	v_mfma_f32_16x16x32_bf16 v[52:55], v[180:183], v[196:199], v[52:55]
	v_mfma_f32_16x16x32_bf16 v[48:51], v[188:191], v[196:199], v[48:51]
	v_mfma_f32_16x16x32_bf16 v[36:39], v[180:183], v[204:207], v[36:39]
	v_mfma_f32_16x16x32_bf16 v[32:35], v[188:191], v[204:207], v[32:35]
	v_mfma_f32_16x16x32_bf16 v[20:23], v[180:183], v[216:219], v[20:23]
	v_mfma_f32_16x16x32_bf16 v[16:19], v[188:191], v[216:219], v[16:19]
	v_mfma_f32_16x16x32_bf16 v[4:7], v[180:183], v[224:227], v[4:7]
	v_mfma_f32_16x16x32_bf16 v[0:3], v[188:191], v[224:227], v[0:3]
	v_mfma_f32_16x16x32_bf16 v[52:55], v[184:187], v[200:203], v[52:55]
	v_mfma_f32_16x16x32_bf16 v[48:51], v[192:195], v[200:203], v[48:51]
	v_mfma_f32_16x16x32_bf16 v[36:39], v[184:187], v[208:211], v[36:39]
	v_mfma_f32_16x16x32_bf16 v[32:35], v[192:195], v[208:211], v[32:35]
	v_mfma_f32_16x16x32_bf16 v[20:23], v[184:187], v[220:223], v[20:23]
	v_mfma_f32_16x16x32_bf16 v[16:19], v[192:195], v[220:223], v[16:19]
	v_mfma_f32_16x16x32_bf16 v[4:7], v[184:187], v[228:231], v[4:7]
	v_mfma_f32_16x16x32_bf16 v[0:3], v[192:195], v[228:231], v[0:3]
	s_setprio 0
	s_barrier
	v_add_u32_e32 v154, s37, v165
	ds_read_b128 v[128:131], v154
	ds_read_b128 v[132:135], v154 offset:1024
	ds_read_b128 v[170:173], v154 offset:2048
	ds_read_b128 v[176:179], v154 offset:3072
	v_add_u32_e32 v154, s26, v165
	ds_read_b128 v[180:183], v154
	ds_read_b128 v[184:187], v154 offset:1024
	ds_read_b128 v[188:191], v154 offset:2048
	ds_read_b128 v[192:195], v154 offset:3072
	s_add_u32 s48, s64, 0x80000
	s_addc_u32 s49, s65, 0
	s_mov_b32 m0, s21
	v_lshl_add_u64 v[234:235], s[48:49], 0, v[136:137]
	ds_read_b128 v[196:199], v175 offset:32768
	ds_read_b128 v[200:203], v175 offset:33792
	ds_read_b128 v[204:207], v175 offset:34816
	ds_read_b128 v[208:211], v175 offset:35840
	ds_read_b128 v[216:219], v175 offset:36864
	ds_read_b128 v[220:223], v175 offset:37888
	ds_read_b128 v[224:227], v175 offset:38912
	ds_read_b128 v[228:231], v175 offset:39936
	global_load_lds_dwordx4 v[234:235], off
	v_lshl_add_u64 v[234:235], s[48:49], 0, v[140:141]
	s_mov_b32 m0, s22
	s_nop 0
	global_load_lds_dwordx4 v[234:235], off
	s_waitcnt vmcnt(8) lgkmcnt(0)
	s_barrier
	s_setprio 1
	v_mfma_f32_16x16x32_bf16 v[124:127], v[128:131], v[196:199], v[124:127]
	v_mfma_f32_16x16x32_bf16 v[120:123], v[170:173], v[196:199], v[120:123]
	v_mfma_f32_16x16x32_bf16 v[108:111], v[128:131], v[204:207], v[108:111]
	v_mfma_f32_16x16x32_bf16 v[104:107], v[170:173], v[204:207], v[104:107]
	v_mfma_f32_16x16x32_bf16 v[92:95], v[128:131], v[216:219], v[92:95]
	v_mfma_f32_16x16x32_bf16 v[88:91], v[170:173], v[216:219], v[88:91]
	v_mfma_f32_16x16x32_bf16 v[76:79], v[128:131], v[224:227], v[76:79]
	v_mfma_f32_16x16x32_bf16 v[72:75], v[170:173], v[224:227], v[72:75]
	v_mfma_f32_16x16x32_bf16 v[124:127], v[132:135], v[200:203], v[124:127]
	v_mfma_f32_16x16x32_bf16 v[120:123], v[176:179], v[200:203], v[120:123]
	v_mfma_f32_16x16x32_bf16 v[108:111], v[132:135], v[208:211], v[108:111]
	v_mfma_f32_16x16x32_bf16 v[104:107], v[176:179], v[208:211], v[104:107]
	v_mfma_f32_16x16x32_bf16 v[92:95], v[132:135], v[220:223], v[92:95]
	v_mfma_f32_16x16x32_bf16 v[88:91], v[176:179], v[220:223], v[88:91]
	v_mfma_f32_16x16x32_bf16 v[76:79], v[132:135], v[228:231], v[76:79]
	v_mfma_f32_16x16x32_bf16 v[72:75], v[176:179], v[228:231], v[72:75]
	s_setprio 0
	s_setprio 1
	v_mfma_f32_16x16x32_bf16 v[116:119], v[180:183], v[196:199], v[116:119]
	v_mfma_f32_16x16x32_bf16 v[112:115], v[188:191], v[196:199], v[112:115]
	v_mfma_f32_16x16x32_bf16 v[100:103], v[180:183], v[204:207], v[100:103]
	v_mfma_f32_16x16x32_bf16 v[96:99], v[188:191], v[204:207], v[96:99]
	v_mfma_f32_16x16x32_bf16 v[84:87], v[180:183], v[216:219], v[84:87]
	v_mfma_f32_16x16x32_bf16 v[80:83], v[188:191], v[216:219], v[80:83]
	v_mfma_f32_16x16x32_bf16 v[68:71], v[180:183], v[224:227], v[68:71]
	v_mfma_f32_16x16x32_bf16 v[64:67], v[188:191], v[224:227], v[64:67]
	v_mfma_f32_16x16x32_bf16 v[116:119], v[184:187], v[200:203], v[116:119]
	v_mfma_f32_16x16x32_bf16 v[112:115], v[192:195], v[200:203], v[112:115]
	v_mfma_f32_16x16x32_bf16 v[100:103], v[184:187], v[208:211], v[100:103]
	v_mfma_f32_16x16x32_bf16 v[96:99], v[192:195], v[208:211], v[96:99]
	v_mfma_f32_16x16x32_bf16 v[84:87], v[184:187], v[220:223], v[84:87]
	v_mfma_f32_16x16x32_bf16 v[80:83], v[192:195], v[220:223], v[80:83]
	v_mfma_f32_16x16x32_bf16 v[68:71], v[184:187], v[228:231], v[68:71]
	v_mfma_f32_16x16x32_bf16 v[64:67], v[192:195], v[228:231], v[64:67]
	s_setprio 0
	s_barrier
; #define PG8_STAGE(bufoff, gbase, voff) do { _Pragma("unroll") for (int _i = 0; _i < 2; ++_i) \
;         __builtin_amdgcn_global_load_lds((const unsigned*)((const char*)(gbase) + (voff)[_i]), (LAS unsigned*)(lds + (bufoff) + ldsw + _i * 8192), 16, 0, 0); } while (0)
; #define PG8_LDA(dst, b, h) do { _Pragma("unroll") for (int m = 0; m < 4; ++m) _Pragma("unroll") for (int k = 0; k < 2; ++k) dst[m][k] = *(const LAS bf16x8*)(lds + PG8_SA(b, h) + aoff + m * 2048 + k * 1024); } while (0)
; #define PG8_MMA(ai, bj, At, Bt) do { __builtin_amdgcn_s_setprio(1); _Pragma("unroll") for (int m = 0; m < 4; ++m) _Pragma("unroll") for (int n = 0; n < 2; ++n) _Pragma("unroll") for (int k = 0; k < 2; ++k) \
;         acc[ai][bj][m][n] = __builtin_amdgcn_mfma_f32_16x16x32_bf16(Bt[n][k], At[m][k], acc[ai][bj][m][n], 0, 0, 0); __builtin_amdgcn_s_setprio(0); } while (0)
; #define PG8_WAIT_V(n) asm volatile("s_waitcnt vmcnt(" #n ")" ::: "memory")
; #define PG8_WAIT_L(n) asm volatile("s_waitcnt lgkmcnt(" #n ")" ::: "memory")
; #define PG8_BAR __builtin_amdgcn_s_barrier()
; #define PG8_SCHED __builtin_amdgcn_sched_barrier(0)
; template <class Epi, class Sched>
; __device__ __forceinline__ void gemm_phase(LAS unsigned char* lds, const Gemm g, const Sched& S, const Epi& E) {
;     ...
;             PG8_LDA(At, 1, 1); PG8_STAGE(PG8_SB(1, 0), b3, voffB); PG8_STAGE(PG8_SB(1, 1), b3 + hstepB, voffB); PG8_STAGE(PG8_SA(1, 0), a3, voffA);
;             PG8_WAIT_V(8); PG8_WAIT_L(0); PG8_BAR; PG8_MMA(1, 0, At, B0); PG8_MMA(1, 1, At, B1); PG8_BAR; PG8_SCHED;
;         }
;         if (wr == 0) PG8_BAR;
	s_add_i32 s39, s37, s15
	v_lshl_add_u64 v[152:153], v[152:153], 0, s[8:9]
	s_mov_b32 m0, s39
	s_nop 0
	global_load_lds_dwordx4 v[152:153], off
	s_add_i32 m0, s39, 0x2000
	s_add_u32 s48, s62, 0x80080
	v_lshl_add_u64 v[152:153], v[156:157], 0, s[8:9]
	s_addc_u32 s49, s63, 0
	s_add_i32 s39, s26, s15
	global_load_lds_dwordx4 v[152:153], off
	v_lshl_add_u64 v[152:153], s[48:49], 0, v[138:139]
	s_mov_b32 m0, s39
	s_nop 0
	global_load_lds_dwordx4 v[152:153], off
	v_lshl_add_u64 v[152:153], s[48:49], 0, v[142:143]
	s_add_i32 m0, s39, 0x2000
	s_nop 0
	global_load_lds_dwordx4 v[152:153], off
	v_lshl_add_u64 v[152:153], v[160:161], 0, s[8:9]
	s_mov_b32 m0, s25
	s_nop 0
	global_load_lds_dwordx4 v[152:153], off
	v_lshl_add_u64 v[152:153], v[232:233], 0, s[8:9]
	s_mov_b32 m0, s27
	s_nop 0
	global_load_lds_dwordx4 v[152:153], off
	ds_read_b128 v[196:199], v175 offset:49152
	ds_read_b128 v[200:203], v175 offset:50176
	ds_read_b128 v[204:207], v175 offset:51200
	ds_read_b128 v[208:211], v175 offset:52224
	ds_read_b128 v[216:219], v175 offset:53248
	ds_read_b128 v[220:223], v175 offset:54272
	ds_read_b128 v[224:227], v175 offset:55296
	ds_read_b128 v[228:231], v175 offset:56320
	s_waitcnt vmcnt(8) lgkmcnt(0)
	s_barrier
	s_setprio 1
	v_mfma_f32_16x16x32_bf16 v[60:63], v[128:131], v[196:199], v[60:63]
	v_mfma_f32_16x16x32_bf16 v[56:59], v[170:173], v[196:199], v[56:59]
	v_mfma_f32_16x16x32_bf16 v[44:47], v[128:131], v[204:207], v[44:47]
	v_mfma_f32_16x16x32_bf16 v[40:43], v[170:173], v[204:207], v[40:43]
	v_mfma_f32_16x16x32_bf16 v[28:31], v[128:131], v[216:219], v[28:31]
	v_mfma_f32_16x16x32_bf16 v[24:27], v[170:173], v[216:219], v[24:27]
	v_mfma_f32_16x16x32_bf16 v[12:15], v[128:131], v[224:227], v[12:15]
	v_mfma_f32_16x16x32_bf16 v[8:11], v[170:173], v[224:227], v[8:11]
	v_mfma_f32_16x16x32_bf16 v[60:63], v[132:135], v[200:203], v[60:63]
	v_mfma_f32_16x16x32_bf16 v[56:59], v[176:179], v[200:203], v[56:59]
	v_mfma_f32_16x16x32_bf16 v[44:47], v[132:135], v[208:211], v[44:47]
	v_mfma_f32_16x16x32_bf16 v[40:43], v[176:179], v[208:211], v[40:43]
	v_mfma_f32_16x16x32_bf16 v[28:31], v[132:135], v[220:223], v[28:31]
	v_mfma_f32_16x16x32_bf16 v[24:27], v[176:179], v[220:223], v[24:27]
	v_mfma_f32_16x16x32_bf16 v[12:15], v[132:135], v[228:231], v[12:15]
	v_mfma_f32_16x16x32_bf16 v[8:11], v[176:179], v[228:231], v[8:11]
	s_setprio 0
	s_setprio 1
	v_mfma_f32_16x16x32_bf16 v[52:55], v[180:183], v[196:199], v[52:55]
	v_mfma_f32_16x16x32_bf16 v[48:51], v[188:191], v[196:199], v[48:51]
	v_mfma_f32_16x16x32_bf16 v[36:39], v[180:183], v[204:207], v[36:39]
	v_mfma_f32_16x16x32_bf16 v[32:35], v[188:191], v[204:207], v[32:35]
	v_mfma_f32_16x16x32_bf16 v[20:23], v[180:183], v[216:219], v[20:23]
	v_mfma_f32_16x16x32_bf16 v[16:19], v[188:191], v[216:219], v[16:19]
	v_mfma_f32_16x16x32_bf16 v[4:7], v[180:183], v[224:227], v[4:7]
	v_mfma_f32_16x16x32_bf16 v[0:3], v[188:191], v[224:227], v[0:3]
	v_mfma_f32_16x16x32_bf16 v[52:55], v[184:187], v[200:203], v[52:55]
	v_mfma_f32_16x16x32_bf16 v[48:51], v[192:195], v[200:203], v[48:51]
	v_mfma_f32_16x16x32_bf16 v[36:39], v[184:187], v[208:211], v[36:39]
	v_mfma_f32_16x16x32_bf16 v[32:35], v[192:195], v[208:211], v[32:35]
	v_mfma_f32_16x16x32_bf16 v[20:23], v[184:187], v[220:223], v[20:23]
	v_mfma_f32_16x16x32_bf16 v[16:19], v[192:195], v[220:223], v[16:19]
	v_mfma_f32_16x16x32_bf16 v[4:7], v[184:187], v[228:231], v[4:7]
	v_mfma_f32_16x16x32_bf16 v[0:3], v[192:195], v[228:231], v[0:3]
	s_setprio 0
	s_barrier
	s_add_i32 s35, s35, 2
	s_add_u32 s60, s60, 0x100
	s_addc_u32 s61, s61, 0
	s_add_u32 s31, s31, 0x100
	s_addc_u32 s34, s34, 0
	s_cmp_gt_u32 s35, 29
	s_cbranch_scc0 .LBB0_829
	s_and_b64 vcc, exec, s[10:11]
	s_cbranch_vccz .LBB0_832
	s_barrier

; #define PG8_STAGE(bufoff, gbase, voff) do { _Pragma("unroll") for (int _i = 0; _i < 2; ++_i) \
;         __builtin_amdgcn_global_load_lds((const unsigned*)((const char*)(gbase) + (voff)[_i]), (LAS unsigned*)(lds + (bufoff) + ldsw + _i * 8192), 16, 0, 0); } while (0)
; #define PG8_LDA(dst, b, h) do { _Pragma("unroll") for (int m = 0; m < 4; ++m) _Pragma("unroll") for (int k = 0; k < 2; ++k) dst[m][k] = *(const LAS bf16x8*)(lds + PG8_SA(b, h) + aoff + m * 2048 + k * 1024); } while (0)
; #define PG8_LDB(dst, b, h) do { _Pragma("unroll") for (int n = 0; n < 2; ++n) _Pragma("unroll") for (int k = 0; k < 2; ++k) dst[n][k] = *(const LAS bf16x8*)(lds + PG8_SB(b, h) + boff + n * 2048 + k * 1024); } while (0)
; #define PG8_MMA(ai, bj, At, Bt) do { __builtin_amdgcn_s_setprio(1); _Pragma("unroll") for (int m = 0; m < 4; ++m) _Pragma("unroll") for (int n = 0; n < 2; ++n) _Pragma("unroll") for (int k = 0; k < 2; ++k) \
;         acc[ai][bj][m][n] = __builtin_amdgcn_mfma_f32_16x16x32_bf16(Bt[n][k], At[m][k], acc[ai][bj][m][n], 0, 0, 0); __builtin_amdgcn_s_setprio(0); } while (0)
; #define PG8_WAIT_V(n) asm volatile("s_waitcnt vmcnt(" #n ")" ::: "memory")
; #define PG8_WAIT_L(n) asm volatile("s_waitcnt lgkmcnt(" #n ")" ::: "memory")
; #define PG8_BAR __builtin_amdgcn_s_barrier()
; #define PG8_SCHED __builtin_amdgcn_sched_barrier(0)
; template <class Epi, class Sched>
; __device__ __forceinline__ void gemm_phase(LAS unsigned char* lds, const Gemm g, const Sched& S, const Epi& E) {
;     ...
;             const bool last = (t == nt - 2);
;             const char* a1 = cA + (size_t)(t + 1) * kstep;
;             const char* a2 = last ? nA : cA + (size_t)(t + 2) * kstep; const char* b2 = last ? nB : cB + (size_t)(t + 2) * kstep;
;             const char* a3 = a2 + kstep; const char* b3 = b2 + kstep;
;             PG8_LDB(B0, 0, 0); PG8_LDB(B1, 0, 1); PG8_SCHED; PG8_LDA(At, 0, 0); PG8_STAGE(PG8_SA(1, 1), a1 + hstepA, voffA);
;             PG8_WAIT_V(8); PG8_WAIT_L(0); PG8_BAR; PG8_MMA(0, 0, At, B0); PG8_MMA(0, 1, At, B1); PG8_BAR; PG8_SCHED;
;             PG8_LDA(At, 0, 1); PG8_STAGE(PG8_SB(0, 0), b2, voffB); PG8_STAGE(PG8_SB(0, 1), b2 + hstepB, voffB); PG8_STAGE(PG8_SA(0, 0), a2, voffA);
.LBB0_923:
	s_add_u32 s4, s0, 0xfff80080
	s_addc_u32 s5, s1, -1
	s_cmp_eq_u32 s62, 28
	s_cselect_b32 s7, s12, s5
	s_cselect_b32 s6, s13, s4
	s_cselect_b32 s5, s53, s61
	s_cselect_b32 s4, s55, s60
	v_lshl_add_u64 v[218:219], s[0:1], 0, v[170:171]
	s_add_i32 m0, s15, 0xc000
	s_nop 0
	global_load_lds_dwordx4 v[218:219], off
	v_lshl_add_u64 v[218:219], s[0:1], 0, v[172:173]
	s_add_i32 m0, s15, 0xe000
	s_nop 0
	global_load_lds_dwordx4 v[218:219], off
	ds_read_b128 v[64:67], v209
	ds_read_b128 v[68:71], v209 offset:1024
	ds_read_b128 v[72:75], v209 offset:2048
	ds_read_b128 v[76:79], v209 offset:3072
	ds_read_b128 v[84:87], v210
	ds_read_b128 v[88:91], v210 offset:1024
	ds_read_b128 v[92:95], v210 offset:2048
	ds_read_b128 v[96:99], v210 offset:3072
	ds_read_b128 v[174:177], v211
	ds_read_b128 v[178:181], v211 offset:1024
	ds_read_b128 v[182:185], v211 offset:2048
	ds_read_b128 v[186:189], v211 offset:3072
	ds_read_b128 v[190:193], v211 offset:4096
	ds_read_b128 v[194:197], v211 offset:5120
	ds_read_b128 v[198:201], v211 offset:6144
	ds_read_b128 v[202:205], v211 offset:7168
	s_waitcnt vmcnt(8) lgkmcnt(0)
	s_barrier
	s_setprio 1
	v_mfma_f32_16x16x32_bf16 v[156:159], v[64:67], v[174:177], v[156:159]
	v_mfma_f32_16x16x32_bf16 v[148:151], v[72:75], v[174:177], v[148:151]
	v_mfma_f32_16x16x32_bf16 v[140:143], v[64:67], v[182:185], v[140:143]
	v_mfma_f32_16x16x32_bf16 v[136:139], v[72:75], v[182:185], v[136:139]
	v_mfma_f32_16x16x32_bf16 v[124:127], v[64:67], v[190:193], v[124:127]
	v_mfma_f32_16x16x32_bf16 v[120:123], v[72:75], v[190:193], v[120:123]
	v_mfma_f32_16x16x32_bf16 v[108:111], v[64:67], v[198:201], v[108:111]
	v_mfma_f32_16x16x32_bf16 v[104:107], v[72:75], v[198:201], v[104:107]
	v_mfma_f32_16x16x32_bf16 v[156:159], v[68:71], v[178:181], v[156:159]
	v_mfma_f32_16x16x32_bf16 v[148:151], v[76:79], v[178:181], v[148:151]
	v_mfma_f32_16x16x32_bf16 v[140:143], v[68:71], v[186:189], v[140:143]
	v_mfma_f32_16x16x32_bf16 v[136:139], v[76:79], v[186:189], v[136:139]
	v_mfma_f32_16x16x32_bf16 v[124:127], v[68:71], v[194:197], v[124:127]
	v_mfma_f32_16x16x32_bf16 v[120:123], v[76:79], v[194:197], v[120:123]
	v_mfma_f32_16x16x32_bf16 v[108:111], v[68:71], v[202:205], v[108:111]
	v_mfma_f32_16x16x32_bf16 v[104:107], v[76:79], v[202:205], v[104:107]
	s_setprio 0
	s_setprio 1
	v_mfma_f32_16x16x32_bf16 v[152:155], v[84:87], v[174:177], v[152:155]
	v_mfma_f32_16x16x32_bf16 v[144:147], v[92:95], v[174:177], v[144:147]
	v_mfma_f32_16x16x32_bf16 v[132:135], v[84:87], v[182:185], v[132:135]
	v_mfma_f32_16x16x32_bf16 v[128:131], v[92:95], v[182:185], v[128:131]
	v_mfma_f32_16x16x32_bf16 v[116:119], v[84:87], v[190:193], v[116:119]
	v_mfma_f32_16x16x32_bf16 v[112:115], v[92:95], v[190:193], v[112:115]
	v_mfma_f32_16x16x32_bf16 v[80:83], v[84:87], v[198:201], v[80:83]
	v_mfma_f32_16x16x32_bf16 v[100:103], v[92:95], v[198:201], v[100:103]
	v_mfma_f32_16x16x32_bf16 v[152:155], v[88:91], v[178:181], v[152:155]
	v_mfma_f32_16x16x32_bf16 v[144:147], v[96:99], v[178:181], v[144:147]
	v_mfma_f32_16x16x32_bf16 v[132:135], v[88:91], v[186:189], v[132:135]
	v_mfma_f32_16x16x32_bf16 v[128:131], v[96:99], v[186:189], v[128:131]
	v_mfma_f32_16x16x32_bf16 v[116:119], v[88:91], v[194:197], v[116:119]
	v_mfma_f32_16x16x32_bf16 v[112:115], v[96:99], v[194:197], v[112:115]
	v_mfma_f32_16x16x32_bf16 v[80:83], v[88:91], v[202:205], v[80:83]
	v_mfma_f32_16x16x32_bf16 v[100:103], v[96:99], v[202:205], v[100:103]
	s_setprio 0
	s_barrier
	s_add_i32 s63, s33, s14
	v_lshl_add_u64 v[218:219], s[4:5], 0, v[162:163]
	s_mov_b32 m0, s63
	s_nop 0
	global_load_lds_dwordx4 v[218:219], off
	s_add_i32 m0, s63, 0x2000
	s_add_u32 s70, s4, 0x80000
	v_lshl_add_u64 v[220:221], s[4:5], 0, v[166:167]
	s_addc_u32 s71, s5, 0
	s_add_i32 s63, s36, s14
	global_load_lds_dwordx4 v[220:221], off
	v_lshl_add_u64 v[222:223], s[70:71], 0, v[162:163]
	s_mov_b32 m0, s63
	v_lshl_add_u64 v[224:225], s[6:7], 0, v[164:165]
	global_load_lds_dwordx4 v[222:223], off
	v_lshl_add_u64 v[222:223], s[70:71], 0, v[166:167]
	s_add_i32 m0, s63, 0x2000
	s_nop 0
	global_load_lds_dwordx4 v[222:223], off
	v_lshl_add_u64 v[222:223], s[6:7], 0, v[160:161]
	s_mov_b32 m0, s15
	s_nop 0
	global_load_lds_dwordx4 v[222:223], off
	s_mov_b32 m0, s21
	s_nop 0
	global_load_lds_dwordx4 v[224:225], off
	ds_read_b128 v[174:177], v211 offset:16384
	ds_read_b128 v[178:181], v211 offset:17408
	ds_read_b128 v[182:185], v211 offset:18432
	ds_read_b128 v[186:189], v211 offset:19456
	ds_read_b128 v[190:193], v211 offset:20480
	ds_read_b128 v[194:197], v211 offset:21504
	ds_read_b128 v[198:201], v211 offset:22528
	ds_read_b128 v[202:205], v211 offset:23552
	s_waitcnt vmcnt(8) lgkmcnt(0)
	s_barrier
; #define PG8_STAGE(bufoff, gbase, voff) do { _Pragma("unroll") for (int _i = 0; _i < 2; ++_i) \
;         __builtin_amdgcn_global_load_lds((const unsigned*)((const char*)(gbase) + (voff)[_i]), (LAS unsigned*)(lds + (bufoff) + ldsw + _i * 8192), 16, 0, 0); } while (0)
; #define PG8_LDA(dst, b, h) do { _Pragma("unroll") for (int m = 0; m < 4; ++m) _Pragma("unroll") for (int k = 0; k < 2; ++k) dst[m][k] = *(const LAS bf16x8*)(lds + PG8_SA(b, h) + aoff + m * 2048 + k * 1024); } while (0)
; #define PG8_LDB(dst, b, h) do { _Pragma("unroll") for (int n = 0; n < 2; ++n) _Pragma("unroll") for (int k = 0; k < 2; ++k) dst[n][k] = *(const LAS bf16x8*)(lds + PG8_SB(b, h) + boff + n * 2048 + k * 1024); } while (0)
; #define PG8_MMA(ai, bj, At, Bt) do { __builtin_amdgcn_s_setprio(1); _Pragma("unroll") for (int m = 0; m < 4; ++m) _Pragma("unroll") for (int n = 0; n < 2; ++n) _Pragma("unroll") for (int k = 0; k < 2; ++k) \
;         acc[ai][bj][m][n] = __builtin_amdgcn_mfma_f32_16x16x32_bf16(Bt[n][k], At[m][k], acc[ai][bj][m][n], 0, 0, 0); __builtin_amdgcn_s_setprio(0); } while (0)
; #define PG8_WAIT_V(n) asm volatile("s_waitcnt vmcnt(" #n ")" ::: "memory")
; #define PG8_WAIT_L(n) asm volatile("s_waitcnt lgkmcnt(" #n ")" ::: "memory")
; #define PG8_BAR __builtin_amdgcn_s_barrier()
; #define PG8_SCHED __builtin_amdgcn_sched_barrier(0)
; template <class Epi, class Sched>
; __device__ __forceinline__ void gemm_phase(LAS unsigned char* lds, const Gemm g, const Sched& S, const Epi& E) {
;     ...
;             PG8_WAIT_V(8); PG8_WAIT_L(0); PG8_BAR; PG8_MMA(1, 0, At, B0); PG8_MMA(1, 1, At, B1); PG8_BAR; PG8_SCHED;
;             PG8_LDB(B0, 1, 0); PG8_LDB(B1, 1, 1); PG8_SCHED; PG8_LDA(At, 1, 0); PG8_STAGE(PG8_SA(0, 1), a2 + hstepA, voffA);
;             PG8_WAIT_V(8); PG8_WAIT_L(0); PG8_BAR; PG8_MMA(0, 0, At, B0); PG8_MMA(0, 1, At, B1); PG8_BAR; PG8_SCHED;
	s_setprio 1
	v_mfma_f32_16x16x32_bf16 v[60:63], v[64:67], v[174:177], v[60:63]
	v_mfma_f32_16x16x32_bf16 v[56:59], v[72:75], v[174:177], v[56:59]
	v_mfma_f32_16x16x32_bf16 v[44:47], v[64:67], v[182:185], v[44:47]
	v_mfma_f32_16x16x32_bf16 v[40:43], v[72:75], v[182:185], v[40:43]
	v_mfma_f32_16x16x32_bf16 v[28:31], v[64:67], v[190:193], v[28:31]
	v_mfma_f32_16x16x32_bf16 v[24:27], v[72:75], v[190:193], v[24:27]
	v_mfma_f32_16x16x32_bf16 v[12:15], v[64:67], v[198:201], v[12:15]
	v_mfma_f32_16x16x32_bf16 v[8:11], v[72:75], v[198:201], v[8:11]
	v_mfma_f32_16x16x32_bf16 v[60:63], v[68:71], v[178:181], v[60:63]
	v_mfma_f32_16x16x32_bf16 v[56:59], v[76:79], v[178:181], v[56:59]
	v_mfma_f32_16x16x32_bf16 v[44:47], v[68:71], v[186:189], v[44:47]
	v_mfma_f32_16x16x32_bf16 v[40:43], v[76:79], v[186:189], v[40:43]
	v_mfma_f32_16x16x32_bf16 v[28:31], v[68:71], v[194:197], v[28:31]
	v_mfma_f32_16x16x32_bf16 v[24:27], v[76:79], v[194:197], v[24:27]
	v_mfma_f32_16x16x32_bf16 v[12:15], v[68:71], v[202:205], v[12:15]
	v_mfma_f32_16x16x32_bf16 v[8:11], v[76:79], v[202:205], v[8:11]
	s_setprio 0
	s_setprio 1
	v_mfma_f32_16x16x32_bf16 v[52:55], v[84:87], v[174:177], v[52:55]
	v_mfma_f32_16x16x32_bf16 v[48:51], v[92:95], v[174:177], v[48:51]
	v_mfma_f32_16x16x32_bf16 v[36:39], v[84:87], v[182:185], v[36:39]
	v_mfma_f32_16x16x32_bf16 v[32:35], v[92:95], v[182:185], v[32:35]
	v_mfma_f32_16x16x32_bf16 v[20:23], v[84:87], v[190:193], v[20:23]
	v_mfma_f32_16x16x32_bf16 v[16:19], v[92:95], v[190:193], v[16:19]
	v_mfma_f32_16x16x32_bf16 v[0:3], v[84:87], v[198:201], v[0:3]
	v_mfma_f32_16x16x32_bf16 v[4:7], v[92:95], v[198:201], v[4:7]
	v_mfma_f32_16x16x32_bf16 v[52:55], v[88:91], v[178:181], v[52:55]
	v_mfma_f32_16x16x32_bf16 v[48:51], v[96:99], v[178:181], v[48:51]
	v_mfma_f32_16x16x32_bf16 v[36:39], v[88:91], v[186:189], v[36:39]
	v_mfma_f32_16x16x32_bf16 v[32:35], v[96:99], v[186:189], v[32:35]
	v_mfma_f32_16x16x32_bf16 v[20:23], v[88:91], v[194:197], v[20:23]
	v_mfma_f32_16x16x32_bf16 v[16:19], v[96:99], v[194:197], v[16:19]
	v_mfma_f32_16x16x32_bf16 v[0:3], v[88:91], v[202:205], v[0:3]
	v_mfma_f32_16x16x32_bf16 v[4:7], v[96:99], v[202:205], v[4:7]
	s_setprio 0
	s_barrier
	v_add_u32_e32 v76, s37, v208
	v_add_u32_e32 v96, s26, v208
	s_add_u32 s6, s6, 0x80000
	s_addc_u32 s7, s7, 0
	s_mov_b32 m0, s22
	v_lshl_add_u64 v[226:227], s[6:7], 0, v[160:161]
	global_load_lds_dwordx4 v[226:227], off
	v_lshl_add_u64 v[226:227], s[6:7], 0, v[164:165]
	s_mov_b32 m0, s23
	s_nop 0
	global_load_lds_dwordx4 v[226:227], off
	ds_read_b128 v[64:67], v76
	ds_read_b128 v[68:71], v76 offset:1024
	ds_read_b128 v[72:75], v76 offset:2048
	ds_read_b128 v[76:79], v76 offset:3072
	ds_read_b128 v[84:87], v96
	ds_read_b128 v[88:91], v96 offset:1024
	ds_read_b128 v[92:95], v96 offset:2048
	ds_read_b128 v[96:99], v96 offset:3072
	ds_read_b128 v[174:177], v211 offset:32768
	ds_read_b128 v[178:181], v211 offset:33792
	ds_read_b128 v[182:185], v211 offset:34816
	ds_read_b128 v[186:189], v211 offset:35840
	ds_read_b128 v[190:193], v211 offset:36864
	ds_read_b128 v[194:197], v211 offset:37888
	ds_read_b128 v[198:201], v211 offset:38912
	ds_read_b128 v[202:205], v211 offset:39936
	s_waitcnt vmcnt(8) lgkmcnt(0)
	s_barrier
	s_setprio 1
	v_mfma_f32_16x16x32_bf16 v[156:159], v[64:67], v[174:177], v[156:159]
	v_mfma_f32_16x16x32_bf16 v[148:151], v[72:75], v[174:177], v[148:151]
	v_mfma_f32_16x16x32_bf16 v[140:143], v[64:67], v[182:185], v[140:143]
	v_mfma_f32_16x16x32_bf16 v[136:139], v[72:75], v[182:185], v[136:139]
	v_mfma_f32_16x16x32_bf16 v[124:127], v[64:67], v[190:193], v[124:127]
	v_mfma_f32_16x16x32_bf16 v[120:123], v[72:75], v[190:193], v[120:123]
	v_mfma_f32_16x16x32_bf16 v[108:111], v[64:67], v[198:201], v[108:111]
	v_mfma_f32_16x16x32_bf16 v[104:107], v[72:75], v[198:201], v[104:107]
	v_mfma_f32_16x16x32_bf16 v[156:159], v[68:71], v[178:181], v[156:159]
	v_mfma_f32_16x16x32_bf16 v[148:151], v[76:79], v[178:181], v[148:151]
	v_mfma_f32_16x16x32_bf16 v[140:143], v[68:71], v[186:189], v[140:143]
	v_mfma_f32_16x16x32_bf16 v[136:139], v[76:79], v[186:189], v[136:139]
	v_mfma_f32_16x16x32_bf16 v[124:127], v[68:71], v[194:197], v[124:127]
	v_mfma_f32_16x16x32_bf16 v[120:123], v[76:79], v[194:197], v[120:123]
	v_mfma_f32_16x16x32_bf16 v[108:111], v[68:71], v[202:205], v[108:111]
	v_mfma_f32_16x16x32_bf16 v[104:107], v[76:79], v[202:205], v[104:107]
	s_setprio 0
	s_setprio 1
	v_mfma_f32_16x16x32_bf16 v[152:155], v[84:87], v[174:177], v[152:155]
	v_mfma_f32_16x16x32_bf16 v[144:147], v[92:95], v[174:177], v[144:147]
	v_mfma_f32_16x16x32_bf16 v[132:135], v[84:87], v[182:185], v[132:135]
	v_mfma_f32_16x16x32_bf16 v[128:131], v[92:95], v[182:185], v[128:131]
	v_mfma_f32_16x16x32_bf16 v[116:119], v[84:87], v[190:193], v[116:119]
	v_mfma_f32_16x16x32_bf16 v[112:115], v[92:95], v[190:193], v[112:115]
	v_mfma_f32_16x16x32_bf16 v[80:83], v[84:87], v[198:201], v[80:83]
	v_mfma_f32_16x16x32_bf16 v[100:103], v[92:95], v[198:201], v[100:103]
	v_mfma_f32_16x16x32_bf16 v[152:155], v[88:91], v[178:181], v[152:155]
	v_mfma_f32_16x16x32_bf16 v[144:147], v[96:99], v[178:181], v[144:147]
	v_mfma_f32_16x16x32_bf16 v[132:135], v[88:91], v[186:189], v[132:135]
	v_mfma_f32_16x16x32_bf16 v[128:131], v[96:99], v[186:189], v[128:131]
	v_mfma_f32_16x16x32_bf16 v[116:119], v[88:91], v[194:197], v[116:119]
	v_mfma_f32_16x16x32_bf16 v[112:115], v[96:99], v[194:197], v[112:115]
	v_mfma_f32_16x16x32_bf16 v[80:83], v[88:91], v[202:205], v[80:83]
	v_mfma_f32_16x16x32_bf16 v[100:103], v[96:99], v[202:205], v[100:103]
	s_setprio 0
	s_barrier
; #define PG8_STAGE(bufoff, gbase, voff) do { _Pragma("unroll") for (int _i = 0; _i < 2; ++_i) \
;         __builtin_amdgcn_global_load_lds((const unsigned*)((const char*)(gbase) + (voff)[_i]), (LAS unsigned*)(lds + (bufoff) + ldsw + _i * 8192), 16, 0, 0); } while (0)
; #define PG8_LDA(dst, b, h) do { _Pragma("unroll") for (int m = 0; m < 4; ++m) _Pragma("unroll") for (int k = 0; k < 2; ++k) dst[m][k] = *(const LAS bf16x8*)(lds + PG8_SA(b, h) + aoff + m * 2048 + k * 1024); } while (0)
; #define PG8_MMA(ai, bj, At, Bt) do { __builtin_amdgcn_s_setprio(1); _Pragma("unroll") for (int m = 0; m < 4; ++m) _Pragma("unroll") for (int n = 0; n < 2; ++n) _Pragma("unroll") for (int k = 0; k < 2; ++k) \
;         acc[ai][bj][m][n] = __builtin_amdgcn_mfma_f32_16x16x32_bf16(Bt[n][k], At[m][k], acc[ai][bj][m][n], 0, 0, 0); __builtin_amdgcn_s_setprio(0); } while (0)
; #define PG8_WAIT_V(n) asm volatile("s_waitcnt vmcnt(" #n ")" ::: "memory")
; #define PG8_WAIT_L(n) asm volatile("s_waitcnt lgkmcnt(" #n ")" ::: "memory")
; #define PG8_BAR __builtin_amdgcn_s_barrier()
; #define PG8_SCHED __builtin_amdgcn_sched_barrier(0)
; template <class Epi, class Sched>
; __device__ __forceinline__ void gemm_phase(LAS unsigned char* lds, const Gemm g, const Sched& S, const Epi& E) {
;     ...
;             PG8_LDA(At, 1, 1); PG8_STAGE(PG8_SB(1, 0), b3, voffB); PG8_STAGE(PG8_SB(1, 1), b3 + hstepB, voffB); PG8_STAGE(PG8_SA(1, 0), a3, voffA);
;             PG8_WAIT_V(8); PG8_WAIT_L(0); PG8_BAR; PG8_MMA(1, 0, At, B0); PG8_MMA(1, 1, At, B1); PG8_BAR; PG8_SCHED;
;         }
;         if (wr == 0) PG8_BAR;
	s_add_i32 s6, s37, s14
	v_lshl_add_u64 v[218:219], v[218:219], 0, s[48:49]
	s_mov_b32 m0, s6
	s_nop 0
	global_load_lds_dwordx4 v[218:219], off
	s_add_i32 m0, s6, 0x2000
	s_add_u32 s4, s4, 0x80080
	v_lshl_add_u64 v[218:219], v[220:221], 0, s[48:49]
	s_addc_u32 s5, s5, 0
	s_add_i32 s6, s26, s14
	global_load_lds_dwordx4 v[218:219], off
	v_lshl_add_u64 v[218:219], s[4:5], 0, v[162:163]
	s_mov_b32 m0, s6
	s_nop 0
	global_load_lds_dwordx4 v[218:219], off
	v_lshl_add_u64 v[218:219], s[4:5], 0, v[166:167]
	s_add_i32 m0, s6, 0x2000
	s_nop 0
	global_load_lds_dwordx4 v[218:219], off
	v_lshl_add_u64 v[218:219], v[222:223], 0, s[48:49]
	s_mov_b32 m0, s45
	s_nop 0
	global_load_lds_dwordx4 v[218:219], off
	v_lshl_add_u64 v[218:219], v[224:225], 0, s[48:49]
	s_mov_b32 m0, s64
	s_nop 0
	global_load_lds_dwordx4 v[218:219], off
	ds_read_b128 v[174:177], v211 offset:49152
	ds_read_b128 v[178:181], v211 offset:50176
	ds_read_b128 v[182:185], v211 offset:51200
	ds_read_b128 v[186:189], v211 offset:52224
	ds_read_b128 v[190:193], v211 offset:53248
	ds_read_b128 v[194:197], v211 offset:54272
	ds_read_b128 v[198:201], v211 offset:55296
	ds_read_b128 v[202:205], v211 offset:56320
	s_waitcnt vmcnt(8) lgkmcnt(0)
	s_barrier
	s_setprio 1
	v_mfma_f32_16x16x32_bf16 v[60:63], v[64:67], v[174:177], v[60:63]
	v_mfma_f32_16x16x32_bf16 v[56:59], v[72:75], v[174:177], v[56:59]
	v_mfma_f32_16x16x32_bf16 v[44:47], v[64:67], v[182:185], v[44:47]
	v_mfma_f32_16x16x32_bf16 v[40:43], v[72:75], v[182:185], v[40:43]
	v_mfma_f32_16x16x32_bf16 v[28:31], v[64:67], v[190:193], v[28:31]
	v_mfma_f32_16x16x32_bf16 v[24:27], v[72:75], v[190:193], v[24:27]
	v_mfma_f32_16x16x32_bf16 v[12:15], v[64:67], v[198:201], v[12:15]
	v_mfma_f32_16x16x32_bf16 v[8:11], v[72:75], v[198:201], v[8:11]
	v_mfma_f32_16x16x32_bf16 v[60:63], v[68:71], v[178:181], v[60:63]
	v_mfma_f32_16x16x32_bf16 v[56:59], v[76:79], v[178:181], v[56:59]
	v_mfma_f32_16x16x32_bf16 v[44:47], v[68:71], v[186:189], v[44:47]
	v_mfma_f32_16x16x32_bf16 v[40:43], v[76:79], v[186:189], v[40:43]
	v_mfma_f32_16x16x32_bf16 v[28:31], v[68:71], v[194:197], v[28:31]
	v_mfma_f32_16x16x32_bf16 v[24:27], v[76:79], v[194:197], v[24:27]
	v_mfma_f32_16x16x32_bf16 v[12:15], v[68:71], v[202:205], v[12:15]
	v_mfma_f32_16x16x32_bf16 v[8:11], v[76:79], v[202:205], v[8:11]
	s_setprio 0
	s_setprio 1
	v_mfma_f32_16x16x32_bf16 v[52:55], v[84:87], v[174:177], v[52:55]
	v_mfma_f32_16x16x32_bf16 v[48:51], v[92:95], v[174:177], v[48:51]
	v_mfma_f32_16x16x32_bf16 v[36:39], v[84:87], v[182:185], v[36:39]
	v_mfma_f32_16x16x32_bf16 v[32:35], v[92:95], v[182:185], v[32:35]
	v_mfma_f32_16x16x32_bf16 v[20:23], v[84:87], v[190:193], v[20:23]
	v_mfma_f32_16x16x32_bf16 v[16:19], v[92:95], v[190:193], v[16:19]
	v_mfma_f32_16x16x32_bf16 v[0:3], v[84:87], v[198:201], v[0:3]
	v_mfma_f32_16x16x32_bf16 v[4:7], v[92:95], v[198:201], v[4:7]
	v_mfma_f32_16x16x32_bf16 v[52:55], v[88:91], v[178:181], v[52:55]
	v_mfma_f32_16x16x32_bf16 v[48:51], v[96:99], v[178:181], v[48:51]
	v_mfma_f32_16x16x32_bf16 v[36:39], v[88:91], v[186:189], v[36:39]
	v_mfma_f32_16x16x32_bf16 v[32:35], v[96:99], v[186:189], v[32:35]
	v_mfma_f32_16x16x32_bf16 v[20:23], v[88:91], v[194:197], v[20:23]
	v_mfma_f32_16x16x32_bf16 v[16:19], v[96:99], v[194:197], v[16:19]
	v_mfma_f32_16x16x32_bf16 v[0:3], v[88:91], v[202:205], v[0:3]
	v_mfma_f32_16x16x32_bf16 v[4:7], v[96:99], v[202:205], v[4:7]
	s_setprio 0
	s_barrier
	s_add_i32 s62, s62, 2
	s_add_u32 s0, s0, 0x100
	s_addc_u32 s1, s1, 0
	s_add_u32 s60, s60, 0x100
	s_addc_u32 s61, s61, 0
	s_cmp_gt_u32 s62, 29
	s_cbranch_scc0 .LBB0_923
	s_and_b64 vcc, exec, s[50:51]
	s_cbranch_vccz .LBB0_926
	s_barrier

; #define PG8_STAGE(bufoff, gbase, voff) do { _Pragma("unroll") for (int _i = 0; _i < 2; ++_i) \
;         __builtin_amdgcn_global_load_lds((const unsigned*)((const char*)(gbase) + (voff)[_i]), (LAS unsigned*)(lds + (bufoff) + ldsw + _i * 8192), 16, 0, 0); } while (0)
; #define PG8_LDA(dst, b, h) do { _Pragma("unroll") for (int m = 0; m < 4; ++m) _Pragma("unroll") for (int k = 0; k < 2; ++k) dst[m][k] = *(const LAS bf16x8*)(lds + PG8_SA(b, h) + aoff + m * 2048 + k * 1024); } while (0)
; #define PG8_LDB(dst, b, h) do { _Pragma("unroll") for (int n = 0; n < 2; ++n) _Pragma("unroll") for (int k = 0; k < 2; ++k) dst[n][k] = *(const LAS bf16x8*)(lds + PG8_SB(b, h) + boff + n * 2048 + k * 1024); } while (0)
; #define PG8_MMA(ai, bj, At, Bt) do { __builtin_amdgcn_s_setprio(1); _Pragma("unroll") for (int m = 0; m < 4; ++m) _Pragma("unroll") for (int n = 0; n < 2; ++n) _Pragma("unroll") for (int k = 0; k < 2; ++k) \
;         acc[ai][bj][m][n] = __builtin_amdgcn_mfma_f32_16x16x32_bf16(Bt[n][k], At[m][k], acc[ai][bj][m][n], 0, 0, 0); __builtin_amdgcn_s_setprio(0); } while (0)
; #define PG8_WAIT_V(n) asm volatile("s_waitcnt vmcnt(" #n ")" ::: "memory")
; #define PG8_WAIT_L(n) asm volatile("s_waitcnt lgkmcnt(" #n ")" ::: "memory")
; #define PG8_BAR __builtin_amdgcn_s_barrier()
; #define PG8_SCHED __builtin_amdgcn_sched_barrier(0)
; template <class Epi, class Sched>
; __device__ __forceinline__ void gemm_phase(LAS unsigned char* lds, const Gemm g, const Sched& S, const Epi& E) {
;     ...
;             const bool last = (t == nt - 2);
;             const char* a1 = cA + (size_t)(t + 1) * kstep;
;             const char* a2 = last ? nA : cA + (size_t)(t + 2) * kstep; const char* b2 = last ? nB : cB + (size_t)(t + 2) * kstep;
;             const char* a3 = a2 + kstep; const char* b3 = b2 + kstep;
;             PG8_LDB(B0, 0, 0); PG8_LDB(B1, 0, 1); PG8_SCHED; PG8_LDA(At, 0, 0); PG8_STAGE(PG8_SA(1, 1), a1 + hstepA, voffA);
;             PG8_WAIT_V(8); PG8_WAIT_L(0); PG8_BAR; PG8_MMA(0, 0, At, B0); PG8_MMA(0, 1, At, B1); PG8_BAR; PG8_SCHED;
;             PG8_LDA(At, 0, 1); PG8_STAGE(PG8_SB(0, 0), b2, voffB); PG8_STAGE(PG8_SB(0, 1), b2 + hstepB, voffB); PG8_STAGE(PG8_SA(0, 0), a2, voffA);
.LBB0_1077:
	s_add_u32 s30, s24, 0x100
	s_addc_u32 s31, s25, 0
	s_cmpk_eq_i32 s1, 0x5c
	s_cselect_b32 s39, s23, s31
	s_cselect_b32 s38, s22, s30
	s_cselect_b32 s35, s7, s5
	s_cselect_b32 s34, s6, s4
	v_lshl_add_u64 v[214:215], s[24:25], 0, v[144:145]
	s_add_i32 m0, s28, 0xc000
	s_nop 0
	global_load_lds_dwordx4 v[214:215], off
	v_lshl_add_u64 v[214:215], s[24:25], 0, v[146:147]
	s_add_i32 m0, s28, 0xe000
	s_nop 0
	global_load_lds_dwordx4 v[214:215], off
	ds_read_b128 v[128:131], v193
	ds_read_b128 v[132:135], v193 offset:1024
	ds_read_b128 v[148:151], v193 offset:2048
	ds_read_b128 v[152:155], v193 offset:3072
	ds_read_b128 v[156:159], v194
	ds_read_b128 v[160:163], v194 offset:1024
	ds_read_b128 v[164:167], v194 offset:2048
	ds_read_b128 v[168:171], v194 offset:3072
	ds_read_b128 v[172:175], v195
	ds_read_b128 v[176:179], v195 offset:1024
	ds_read_b128 v[180:183], v195 offset:2048
	ds_read_b128 v[184:187], v195 offset:3072
	ds_read_b128 v[198:201], v195 offset:4096
	ds_read_b128 v[202:205], v195 offset:5120
	ds_read_b128 v[206:209], v195 offset:6144
	ds_read_b128 v[210:213], v195 offset:7168
	s_waitcnt vmcnt(8) lgkmcnt(0)
	s_barrier
	s_setprio 1
	v_mfma_f32_16x16x32_bf16 v[124:127], v[128:131], v[172:175], v[124:127]
	v_mfma_f32_16x16x32_bf16 v[120:123], v[148:151], v[172:175], v[120:123]
	v_mfma_f32_16x16x32_bf16 v[108:111], v[128:131], v[180:183], v[108:111]
	v_mfma_f32_16x16x32_bf16 v[104:107], v[148:151], v[180:183], v[104:107]
	v_mfma_f32_16x16x32_bf16 v[92:95], v[128:131], v[198:201], v[92:95]
	v_mfma_f32_16x16x32_bf16 v[88:91], v[148:151], v[198:201], v[88:91]
	v_mfma_f32_16x16x32_bf16 v[76:79], v[128:131], v[206:209], v[76:79]
	v_mfma_f32_16x16x32_bf16 v[72:75], v[148:151], v[206:209], v[72:75]
	v_mfma_f32_16x16x32_bf16 v[124:127], v[132:135], v[176:179], v[124:127]
	v_mfma_f32_16x16x32_bf16 v[120:123], v[152:155], v[176:179], v[120:123]
	v_mfma_f32_16x16x32_bf16 v[108:111], v[132:135], v[184:187], v[108:111]
	v_mfma_f32_16x16x32_bf16 v[104:107], v[152:155], v[184:187], v[104:107]
	v_mfma_f32_16x16x32_bf16 v[92:95], v[132:135], v[202:205], v[92:95]
	v_mfma_f32_16x16x32_bf16 v[88:91], v[152:155], v[202:205], v[88:91]
	v_mfma_f32_16x16x32_bf16 v[76:79], v[132:135], v[210:213], v[76:79]
	v_mfma_f32_16x16x32_bf16 v[72:75], v[152:155], v[210:213], v[72:75]
	s_setprio 0
	s_setprio 1
	v_mfma_f32_16x16x32_bf16 v[116:119], v[156:159], v[172:175], v[116:119]
	v_mfma_f32_16x16x32_bf16 v[112:115], v[164:167], v[172:175], v[112:115]
	v_mfma_f32_16x16x32_bf16 v[100:103], v[156:159], v[180:183], v[100:103]
	v_mfma_f32_16x16x32_bf16 v[96:99], v[164:167], v[180:183], v[96:99]
	v_mfma_f32_16x16x32_bf16 v[84:87], v[156:159], v[198:201], v[84:87]
	v_mfma_f32_16x16x32_bf16 v[80:83], v[164:167], v[198:201], v[80:83]
	v_mfma_f32_16x16x32_bf16 v[68:71], v[156:159], v[206:209], v[68:71]
	v_mfma_f32_16x16x32_bf16 v[64:67], v[164:167], v[206:209], v[64:67]
	v_mfma_f32_16x16x32_bf16 v[116:119], v[160:163], v[176:179], v[116:119]
	v_mfma_f32_16x16x32_bf16 v[112:115], v[168:171], v[176:179], v[112:115]
	v_mfma_f32_16x16x32_bf16 v[100:103], v[160:163], v[184:187], v[100:103]
	v_mfma_f32_16x16x32_bf16 v[96:99], v[168:171], v[184:187], v[96:99]
	v_mfma_f32_16x16x32_bf16 v[84:87], v[160:163], v[202:205], v[84:87]
	v_mfma_f32_16x16x32_bf16 v[80:83], v[168:171], v[202:205], v[80:83]
	v_mfma_f32_16x16x32_bf16 v[68:71], v[160:163], v[210:213], v[68:71]
	v_mfma_f32_16x16x32_bf16 v[64:67], v[168:171], v[210:213], v[64:67]
	s_setprio 0
	s_barrier
	s_add_i32 s12, s33, s27
	v_lshl_add_u64 v[214:215], s[34:35], 0, v[138:139]
	s_mov_b32 m0, s12
	s_nop 0
	global_load_lds_dwordx4 v[214:215], off
	s_add_i32 m0, s12, 0x2000
	s_add_u32 s12, s34, 0x180000
	v_lshl_add_u64 v[216:217], s[34:35], 0, v[142:143]
	s_addc_u32 s13, s35, 0
	s_add_i32 s24, s36, s27
	global_load_lds_dwordx4 v[216:217], off
	v_lshl_add_u64 v[218:219], s[12:13], 0, v[138:139]
	s_mov_b32 m0, s24
	v_lshl_add_u64 v[220:221], s[38:39], 0, v[140:141]
	global_load_lds_dwordx4 v[218:219], off
	v_lshl_add_u64 v[218:219], s[12:13], 0, v[142:143]
	s_add_i32 m0, s24, 0x2000
	s_nop 0
	global_load_lds_dwordx4 v[218:219], off
	v_lshl_add_u64 v[218:219], s[38:39], 0, v[136:137]
	s_mov_b32 m0, s28
	s_nop 0
	global_load_lds_dwordx4 v[218:219], off
	s_mov_b32 m0, s40
	s_nop 0
	global_load_lds_dwordx4 v[220:221], off
	ds_read_b128 v[172:175], v195 offset:16384
	ds_read_b128 v[176:179], v195 offset:17408
	ds_read_b128 v[180:183], v195 offset:18432
	ds_read_b128 v[184:187], v195 offset:19456
	ds_read_b128 v[198:201], v195 offset:20480
	ds_read_b128 v[202:205], v195 offset:21504
	ds_read_b128 v[206:209], v195 offset:22528
	ds_read_b128 v[210:213], v195 offset:23552
	s_waitcnt vmcnt(8) lgkmcnt(0)
	s_barrier
; #define PG8_STAGE(bufoff, gbase, voff) do { _Pragma("unroll") for (int _i = 0; _i < 2; ++_i) \
;         __builtin_amdgcn_global_load_lds((const unsigned*)((const char*)(gbase) + (voff)[_i]), (LAS unsigned*)(lds + (bufoff) + ldsw + _i * 8192), 16, 0, 0); } while (0)
; #define PG8_LDA(dst, b, h) do { _Pragma("unroll") for (int m = 0; m < 4; ++m) _Pragma("unroll") for (int k = 0; k < 2; ++k) dst[m][k] = *(const LAS bf16x8*)(lds + PG8_SA(b, h) + aoff + m * 2048 + k * 1024); } while (0)
; #define PG8_LDB(dst, b, h) do { _Pragma("unroll") for (int n = 0; n < 2; ++n) _Pragma("unroll") for (int k = 0; k < 2; ++k) dst[n][k] = *(const LAS bf16x8*)(lds + PG8_SB(b, h) + boff + n * 2048 + k * 1024); } while (0)
; #define PG8_MMA(ai, bj, At, Bt) do { __builtin_amdgcn_s_setprio(1); _Pragma("unroll") for (int m = 0; m < 4; ++m) _Pragma("unroll") for (int n = 0; n < 2; ++n) _Pragma("unroll") for (int k = 0; k < 2; ++k) \
;         acc[ai][bj][m][n] = __builtin_amdgcn_mfma_f32_16x16x32_bf16(Bt[n][k], At[m][k], acc[ai][bj][m][n], 0, 0, 0); __builtin_amdgcn_s_setprio(0); } while (0)
; #define PG8_WAIT_V(n) asm volatile("s_waitcnt vmcnt(" #n ")" ::: "memory")
; #define PG8_WAIT_L(n) asm volatile("s_waitcnt lgkmcnt(" #n ")" ::: "memory")
; #define PG8_BAR __builtin_amdgcn_s_barrier()
; #define PG8_SCHED __builtin_amdgcn_sched_barrier(0)
; template <class Epi, class Sched>
; __device__ __forceinline__ void gemm_phase(LAS unsigned char* lds, const Gemm g, const Sched& S, const Epi& E) {
;     ...
;             PG8_WAIT_V(8); PG8_WAIT_L(0); PG8_BAR; PG8_MMA(1, 0, At, B0); PG8_MMA(1, 1, At, B1); PG8_BAR; PG8_SCHED;
;             PG8_LDB(B0, 1, 0); PG8_LDB(B1, 1, 1); PG8_SCHED; PG8_LDA(At, 1, 0); PG8_STAGE(PG8_SA(0, 1), a2 + hstepA, voffA);
;             PG8_WAIT_V(8); PG8_WAIT_L(0); PG8_BAR; PG8_MMA(0, 0, At, B0); PG8_MMA(0, 1, At, B1); PG8_BAR; PG8_SCHED;
	s_setprio 1
	v_mfma_f32_16x16x32_bf16 v[60:63], v[128:131], v[172:175], v[60:63]
	v_mfma_f32_16x16x32_bf16 v[56:59], v[148:151], v[172:175], v[56:59]
	v_mfma_f32_16x16x32_bf16 v[44:47], v[128:131], v[180:183], v[44:47]
	v_mfma_f32_16x16x32_bf16 v[40:43], v[148:151], v[180:183], v[40:43]
	v_mfma_f32_16x16x32_bf16 v[28:31], v[128:131], v[198:201], v[28:31]
	v_mfma_f32_16x16x32_bf16 v[24:27], v[148:151], v[198:201], v[24:27]
	v_mfma_f32_16x16x32_bf16 v[12:15], v[128:131], v[206:209], v[12:15]
	v_mfma_f32_16x16x32_bf16 v[8:11], v[148:151], v[206:209], v[8:11]
	v_mfma_f32_16x16x32_bf16 v[60:63], v[132:135], v[176:179], v[60:63]
	v_mfma_f32_16x16x32_bf16 v[56:59], v[152:155], v[176:179], v[56:59]
	v_mfma_f32_16x16x32_bf16 v[44:47], v[132:135], v[184:187], v[44:47]
	v_mfma_f32_16x16x32_bf16 v[40:43], v[152:155], v[184:187], v[40:43]
	v_mfma_f32_16x16x32_bf16 v[28:31], v[132:135], v[202:205], v[28:31]
	v_mfma_f32_16x16x32_bf16 v[24:27], v[152:155], v[202:205], v[24:27]
	v_mfma_f32_16x16x32_bf16 v[12:15], v[132:135], v[210:213], v[12:15]
	v_mfma_f32_16x16x32_bf16 v[8:11], v[152:155], v[210:213], v[8:11]
	s_setprio 0
	s_setprio 1
	v_mfma_f32_16x16x32_bf16 v[52:55], v[156:159], v[172:175], v[52:55]
	v_mfma_f32_16x16x32_bf16 v[48:51], v[164:167], v[172:175], v[48:51]
	v_mfma_f32_16x16x32_bf16 v[36:39], v[156:159], v[180:183], v[36:39]
	v_mfma_f32_16x16x32_bf16 v[32:35], v[164:167], v[180:183], v[32:35]
	v_mfma_f32_16x16x32_bf16 v[20:23], v[156:159], v[198:201], v[20:23]
	v_mfma_f32_16x16x32_bf16 v[16:19], v[164:167], v[198:201], v[16:19]
	v_mfma_f32_16x16x32_bf16 v[4:7], v[156:159], v[206:209], v[4:7]
	v_mfma_f32_16x16x32_bf16 v[0:3], v[164:167], v[206:209], v[0:3]
	v_mfma_f32_16x16x32_bf16 v[52:55], v[160:163], v[176:179], v[52:55]
	v_mfma_f32_16x16x32_bf16 v[48:51], v[168:171], v[176:179], v[48:51]
	v_mfma_f32_16x16x32_bf16 v[36:39], v[160:163], v[184:187], v[36:39]
	v_mfma_f32_16x16x32_bf16 v[32:35], v[168:171], v[184:187], v[32:35]
	v_mfma_f32_16x16x32_bf16 v[20:23], v[160:163], v[202:205], v[20:23]
	v_mfma_f32_16x16x32_bf16 v[16:19], v[168:171], v[202:205], v[16:19]
	v_mfma_f32_16x16x32_bf16 v[4:7], v[160:163], v[210:213], v[4:7]
	v_mfma_f32_16x16x32_bf16 v[0:3], v[168:171], v[210:213], v[0:3]
	s_setprio 0
	s_barrier
	v_add_u32_e32 v152, s37, v190
	v_add_u32_e32 v168, s26, v190
	s_add_u32 s12, s38, 0x180000
	s_addc_u32 s13, s39, 0
	s_mov_b32 m0, s41
	v_lshl_add_u64 v[222:223], s[12:13], 0, v[136:137]
	global_load_lds_dwordx4 v[222:223], off
	v_lshl_add_u64 v[222:223], s[12:13], 0, v[140:141]
	s_mov_b32 m0, s42
	s_nop 0
	global_load_lds_dwordx4 v[222:223], off
	ds_read_b128 v[128:131], v152
	ds_read_b128 v[132:135], v152 offset:1024
	ds_read_b128 v[148:151], v152 offset:2048
	ds_read_b128 v[152:155], v152 offset:3072
	ds_read_b128 v[156:159], v168
	ds_read_b128 v[160:163], v168 offset:1024
	ds_read_b128 v[164:167], v168 offset:2048
	ds_read_b128 v[168:171], v168 offset:3072
	ds_read_b128 v[172:175], v195 offset:32768
	ds_read_b128 v[176:179], v195 offset:33792
	ds_read_b128 v[180:183], v195 offset:34816
	ds_read_b128 v[184:187], v195 offset:35840
	ds_read_b128 v[198:201], v195 offset:36864
	ds_read_b128 v[202:205], v195 offset:37888
	ds_read_b128 v[206:209], v195 offset:38912
	ds_read_b128 v[210:213], v195 offset:39936
	s_waitcnt vmcnt(8) lgkmcnt(0)
	s_barrier
	s_setprio 1
	v_mfma_f32_16x16x32_bf16 v[124:127], v[128:131], v[172:175], v[124:127]
	v_mfma_f32_16x16x32_bf16 v[120:123], v[148:151], v[172:175], v[120:123]
	v_mfma_f32_16x16x32_bf16 v[108:111], v[128:131], v[180:183], v[108:111]
	v_mfma_f32_16x16x32_bf16 v[104:107], v[148:151], v[180:183], v[104:107]
	v_mfma_f32_16x16x32_bf16 v[92:95], v[128:131], v[198:201], v[92:95]
	v_mfma_f32_16x16x32_bf16 v[88:91], v[148:151], v[198:201], v[88:91]
	v_mfma_f32_16x16x32_bf16 v[76:79], v[128:131], v[206:209], v[76:79]
	v_mfma_f32_16x16x32_bf16 v[72:75], v[148:151], v[206:209], v[72:75]
	v_mfma_f32_16x16x32_bf16 v[124:127], v[132:135], v[176:179], v[124:127]
	v_mfma_f32_16x16x32_bf16 v[120:123], v[152:155], v[176:179], v[120:123]
	v_mfma_f32_16x16x32_bf16 v[108:111], v[132:135], v[184:187], v[108:111]
	v_mfma_f32_16x16x32_bf16 v[104:107], v[152:155], v[184:187], v[104:107]
	v_mfma_f32_16x16x32_bf16 v[92:95], v[132:135], v[202:205], v[92:95]
	v_mfma_f32_16x16x32_bf16 v[88:91], v[152:155], v[202:205], v[88:91]
	v_mfma_f32_16x16x32_bf16 v[76:79], v[132:135], v[210:213], v[76:79]
	v_mfma_f32_16x16x32_bf16 v[72:75], v[152:155], v[210:213], v[72:75]
	s_setprio 0
	s_setprio 1
	v_mfma_f32_16x16x32_bf16 v[116:119], v[156:159], v[172:175], v[116:119]
	v_mfma_f32_16x16x32_bf16 v[112:115], v[164:167], v[172:175], v[112:115]
	v_mfma_f32_16x16x32_bf16 v[100:103], v[156:159], v[180:183], v[100:103]
	v_mfma_f32_16x16x32_bf16 v[96:99], v[164:167], v[180:183], v[96:99]
	v_mfma_f32_16x16x32_bf16 v[84:87], v[156:159], v[198:201], v[84:87]
	v_mfma_f32_16x16x32_bf16 v[80:83], v[164:167], v[198:201], v[80:83]
	v_mfma_f32_16x16x32_bf16 v[68:71], v[156:159], v[206:209], v[68:71]
	v_mfma_f32_16x16x32_bf16 v[64:67], v[164:167], v[206:209], v[64:67]
	v_mfma_f32_16x16x32_bf16 v[116:119], v[160:163], v[176:179], v[116:119]
	v_mfma_f32_16x16x32_bf16 v[112:115], v[168:171], v[176:179], v[112:115]
	v_mfma_f32_16x16x32_bf16 v[100:103], v[160:163], v[184:187], v[100:103]
	v_mfma_f32_16x16x32_bf16 v[96:99], v[168:171], v[184:187], v[96:99]
	v_mfma_f32_16x16x32_bf16 v[84:87], v[160:163], v[202:205], v[84:87]
	v_mfma_f32_16x16x32_bf16 v[80:83], v[168:171], v[202:205], v[80:83]
	v_mfma_f32_16x16x32_bf16 v[68:71], v[160:163], v[210:213], v[68:71]
	v_mfma_f32_16x16x32_bf16 v[64:67], v[168:171], v[210:213], v[64:67]
	s_setprio 0
	s_barrier
; #define PG8_STAGE(bufoff, gbase, voff) do { _Pragma("unroll") for (int _i = 0; _i < 2; ++_i) \
;         __builtin_amdgcn_global_load_lds((const unsigned*)((const char*)(gbase) + (voff)[_i]), (LAS unsigned*)(lds + (bufoff) + ldsw + _i * 8192), 16, 0, 0); } while (0)
; #define PG8_LDA(dst, b, h) do { _Pragma("unroll") for (int m = 0; m < 4; ++m) _Pragma("unroll") for (int k = 0; k < 2; ++k) dst[m][k] = *(const LAS bf16x8*)(lds + PG8_SA(b, h) + aoff + m * 2048 + k * 1024); } while (0)
; #define PG8_MMA(ai, bj, At, Bt) do { __builtin_amdgcn_s_setprio(1); _Pragma("unroll") for (int m = 0; m < 4; ++m) _Pragma("unroll") for (int n = 0; n < 2; ++n) _Pragma("unroll") for (int k = 0; k < 2; ++k) \
;         acc[ai][bj][m][n] = __builtin_amdgcn_mfma_f32_16x16x32_bf16(Bt[n][k], At[m][k], acc[ai][bj][m][n], 0, 0, 0); __builtin_amdgcn_s_setprio(0); } while (0)
; #define PG8_WAIT_V(n) asm volatile("s_waitcnt vmcnt(" #n ")" ::: "memory")
; #define PG8_WAIT_L(n) asm volatile("s_waitcnt lgkmcnt(" #n ")" ::: "memory")
; #define PG8_BAR __builtin_amdgcn_s_barrier()
; #define PG8_SCHED __builtin_amdgcn_sched_barrier(0)
; template <class Epi, class Sched>
; __device__ __forceinline__ void gemm_phase(LAS unsigned char* lds, const Gemm g, const Sched& S, const Epi& E) {
;     ...
;             PG8_LDA(At, 1, 1); PG8_STAGE(PG8_SB(1, 0), b3, voffB); PG8_STAGE(PG8_SB(1, 1), b3 + hstepB, voffB); PG8_STAGE(PG8_SA(1, 0), a3, voffA);
;             PG8_WAIT_V(8); PG8_WAIT_L(0); PG8_BAR; PG8_MMA(1, 0, At, B0); PG8_MMA(1, 1, At, B1); PG8_BAR; PG8_SCHED;
;         }
;         if (wr == 0) PG8_BAR;
	s_add_i32 s12, s37, s27
	v_lshl_add_u64 v[214:215], v[214:215], 0, s[16:17]
	s_mov_b32 m0, s12
	s_nop 0
	global_load_lds_dwordx4 v[214:215], off
	s_add_i32 m0, s12, 0x2000
	s_add_u32 s12, s34, 0x180080
	v_lshl_add_u64 v[214:215], v[216:217], 0, s[16:17]
	s_addc_u32 s13, s35, 0
	s_add_i32 s24, s26, s27
	global_load_lds_dwordx4 v[214:215], off
	v_lshl_add_u64 v[214:215], s[12:13], 0, v[138:139]
	s_mov_b32 m0, s24
	s_nop 0
	global_load_lds_dwordx4 v[214:215], off
	v_lshl_add_u64 v[214:215], s[12:13], 0, v[142:143]
	s_add_i32 m0, s24, 0x2000
	s_nop 0
	global_load_lds_dwordx4 v[214:215], off
	v_lshl_add_u64 v[214:215], v[218:219], 0, s[16:17]
	s_mov_b32 m0, s46
	s_nop 0
	global_load_lds_dwordx4 v[214:215], off
	v_lshl_add_u64 v[214:215], v[220:221], 0, s[16:17]
	s_mov_b32 m0, s47
	s_nop 0
	global_load_lds_dwordx4 v[214:215], off
	ds_read_b128 v[172:175], v195 offset:49152
	ds_read_b128 v[176:179], v195 offset:50176
	ds_read_b128 v[180:183], v195 offset:51200
	ds_read_b128 v[184:187], v195 offset:52224
	ds_read_b128 v[198:201], v195 offset:53248
	ds_read_b128 v[202:205], v195 offset:54272
	ds_read_b128 v[206:209], v195 offset:55296
	ds_read_b128 v[210:213], v195 offset:56320
	s_waitcnt vmcnt(8) lgkmcnt(0)
	s_barrier
	s_setprio 1
	v_mfma_f32_16x16x32_bf16 v[60:63], v[128:131], v[172:175], v[60:63]
	v_mfma_f32_16x16x32_bf16 v[56:59], v[148:151], v[172:175], v[56:59]
	v_mfma_f32_16x16x32_bf16 v[44:47], v[128:131], v[180:183], v[44:47]
	v_mfma_f32_16x16x32_bf16 v[40:43], v[148:151], v[180:183], v[40:43]
	v_mfma_f32_16x16x32_bf16 v[28:31], v[128:131], v[198:201], v[28:31]
	v_mfma_f32_16x16x32_bf16 v[24:27], v[148:151], v[198:201], v[24:27]
	v_mfma_f32_16x16x32_bf16 v[12:15], v[128:131], v[206:209], v[12:15]
	v_mfma_f32_16x16x32_bf16 v[8:11], v[148:151], v[206:209], v[8:11]
	v_mfma_f32_16x16x32_bf16 v[60:63], v[132:135], v[176:179], v[60:63]
	v_mfma_f32_16x16x32_bf16 v[56:59], v[152:155], v[176:179], v[56:59]
	v_mfma_f32_16x16x32_bf16 v[44:47], v[132:135], v[184:187], v[44:47]
	v_mfma_f32_16x16x32_bf16 v[40:43], v[152:155], v[184:187], v[40:43]
	v_mfma_f32_16x16x32_bf16 v[28:31], v[132:135], v[202:205], v[28:31]
	v_mfma_f32_16x16x32_bf16 v[24:27], v[152:155], v[202:205], v[24:27]
	v_mfma_f32_16x16x32_bf16 v[12:15], v[132:135], v[210:213], v[12:15]
	v_mfma_f32_16x16x32_bf16 v[8:11], v[152:155], v[210:213], v[8:11]
	s_setprio 0
	s_setprio 1
	v_mfma_f32_16x16x32_bf16 v[52:55], v[156:159], v[172:175], v[52:55]
	v_mfma_f32_16x16x32_bf16 v[48:51], v[164:167], v[172:175], v[48:51]
	v_mfma_f32_16x16x32_bf16 v[36:39], v[156:159], v[180:183], v[36:39]
	v_mfma_f32_16x16x32_bf16 v[32:35], v[164:167], v[180:183], v[32:35]
	v_mfma_f32_16x16x32_bf16 v[20:23], v[156:159], v[198:201], v[20:23]
	v_mfma_f32_16x16x32_bf16 v[16:19], v[164:167], v[198:201], v[16:19]
	v_mfma_f32_16x16x32_bf16 v[4:7], v[156:159], v[206:209], v[4:7]
	v_mfma_f32_16x16x32_bf16 v[0:3], v[164:167], v[206:209], v[0:3]
	v_mfma_f32_16x16x32_bf16 v[52:55], v[160:163], v[176:179], v[52:55]
	v_mfma_f32_16x16x32_bf16 v[48:51], v[168:171], v[176:179], v[48:51]
	v_mfma_f32_16x16x32_bf16 v[36:39], v[160:163], v[184:187], v[36:39]
	v_mfma_f32_16x16x32_bf16 v[32:35], v[168:171], v[184:187], v[32:35]
	v_mfma_f32_16x16x32_bf16 v[20:23], v[160:163], v[202:205], v[20:23]
	v_mfma_f32_16x16x32_bf16 v[16:19], v[168:171], v[202:205], v[16:19]
	v_mfma_f32_16x16x32_bf16 v[4:7], v[160:163], v[210:213], v[4:7]
	v_mfma_f32_16x16x32_bf16 v[0:3], v[168:171], v[210:213], v[0:3]
	s_setprio 0
	s_barrier
	s_add_i32 s1, s1, 2
	s_add_u32 s4, s4, 0x100
	s_addc_u32 s5, s5, 0
	s_cmpk_gt_u32 s1, 0x5d
	s_mov_b64 s[24:25], s[30:31]
	s_cbranch_scc0 .LBB0_1077
	s_and_b64 vcc, exec, s[18:19]
	s_cbranch_vccz .LBB0_1080
	s_barrier
